# v14 with merged-group MFMA order: m outer, 4 n snake inside (runs share the srcB quads), k order alternating
# baseline (speedup 1.0000x reference)
; #define PG8_STAGE(bufoff, gbase, voff) do { _Pragma("unroll") for (int _i = 0; _i < 2; ++_i) \
;         __builtin_amdgcn_global_load_lds((const unsigned*)((const char*)(gbase) + (voff)[_i]), (PG8_LAS unsigned*)(lds + (bufoff) + ldsw + _i * 8192), 16, 0, 0); } while (0)
; #define PG8_LDA(dst, b, h) do { _Pragma("unroll") for (int m = 0; m < 4; ++m) _Pragma("unroll") for (int k = 0; k < 2; ++k) dst[m][k] = *(const PG8_LAS bf16x8*)(lds + PG8_SA(b, h) + aoff + m * 2048 + k * 1024); } while (0)
; #define PG8_LDB(dst, b, h) do { _Pragma("unroll") for (int n = 0; n < 2; ++n) _Pragma("unroll") for (int k = 0; k < 2; ++k) dst[n][k] = *(const PG8_LAS bf16x8*)(lds + PG8_SB(b, h) + boff + n * 2048 + k * 1024); } while (0)
; #define PG8_MMA(ai, bj, At, Bt) do { __builtin_amdgcn_s_setprio(1); _Pragma("unroll") for (int m = 0; m < 4; ++m) _Pragma("unroll") for (int n = 0; n < 2; ++n) _Pragma("unroll") for (int k = 0; k < 2; ++k) \
;         acc[ai][bj][m][n] = __builtin_amdgcn_mfma_f32_16x16x32_bf16(Bt[n][k], At[m][k], acc[ai][bj][m][n], 0, 0, 0); __builtin_amdgcn_s_setprio(0); } while (0)
; #define PG8_WAIT_V(n) asm volatile("s_waitcnt vmcnt(" #n ")" ::: "memory")
; #define PG8_WAIT_L(n) asm volatile("s_waitcnt lgkmcnt(" #n ")" ::: "memory")
; #define PG8_BAR __builtin_amdgcn_s_barrier()
; #define PG8_SCHED __builtin_amdgcn_sched_barrier(0)
; template <class Epi, class Sched, bool ALIGN_EPI = false, bool SP2 = false>
; __device__ __forceinline__ void gemm_phase(PG8_LAS unsigned char* lds, const Gemm g, const Sched& S, const Epi& E) {
;     ...
;             PG8_LDB(B0, 0, 0); PG8_LDB(B1, 0, 1); PG8_SCHED; PG8_LDA(At, 0, 0); PG8_STAGE(PG8_SA(1, 1), a1 + hstep, voffA);
;             PG8_WAIT_V(8); PG8_WAIT_L(0); PG8_BAR; PG8_MMA(0, 0, At, B0); PG8_MMA(0, 1, At, B1); PG8_BAR; PG8_SCHED;
;             PG8_LDA(At, 0, 1); PG8_STAGE(PG8_SB(0, 0), b2, voffB); PG8_STAGE(PG8_SB(0, 1), b2 + hstep, voffB); PG8_STAGE(PG8_SA(0, 0), a2, voffA);
;             PG8_WAIT_V(8); PG8_WAIT_L(0); PG8_BAR; PG8_MMA(1, 0, At, B0); PG8_MMA(1, 1, At, B1); PG8_BAR; PG8_SCHED;
.LBB0_115:
	ds_read_b128 v[154:157], v150
	ds_read_b128 v[158:161], v150 offset:1024
	ds_read_b128 v[162:165], v150 offset:2048
	ds_read_b128 v[166:169], v150 offset:3072
	ds_read_b128 v[170:173], v151
	ds_read_b128 v[174:177], v151 offset:1024
	ds_read_b128 v[180:183], v151 offset:2048
	ds_read_b128 v[184:187], v151 offset:3072
	s_add_u32 s50, s48, 0x4000
	s_addc_u32 s51, s49, 0
	s_cmp_eq_u32 s76, 60
	s_cselect_b32 s74, s64, s50
	s_cselect_b32 s75, s25, s51
	s_cselect_b32 s72, s65, s68
	s_cselect_b32 s73, s19, s69
	s_add_u32 s50, s74, 0x8000
	s_addc_u32 s51, s75, 0
	s_sub_u32 s50, s48, 0x4000
	s_subb_u32 s51, s49, 0
	s_mov_b32 m0, s58
	s_nop 0
	global_load_lds_dwordx4 v130, s[50:51]
	s_mov_b32 m0, s59
	s_nop 0
	global_load_lds_dwordx4 v134, s[50:51]
	s_add_i32 m0, s28, 0xc000
	ds_read_b128 v[188:191], v152
	ds_read_b128 v[196:199], v152 offset:1024
	ds_read_b128 v[200:203], v152 offset:2048
	ds_read_b128 v[204:207], v152 offset:3072
	ds_read_b128 v[208:211], v152 offset:4096
	ds_read_b128 v[212:215], v152 offset:5120
	ds_read_b128 v[216:219], v152 offset:6144
	ds_read_b128 v[220:223], v152 offset:7168
	global_load_lds_dwordx4 v140, s[48:49]
	s_add_i32 m0, s28, 0xe000
	s_nop 0
	global_load_lds_dwordx4 v142, s[48:49]
	s_waitcnt vmcnt(8)
	s_waitcnt lgkmcnt(0)
	s_barrier
	s_waitcnt lgkmcnt(0)
	v_mfma_f32_16x16x32_bf16 v[126:129], v[154:157], v[188:191], v[126:129]
	v_mfma_f32_16x16x32_bf16 v[126:129], v[158:161], v[196:199], v[126:129]
	v_mfma_f32_16x16x32_bf16 v[118:121], v[166:169], v[196:199], v[118:121]
	v_mfma_f32_16x16x32_bf16 v[118:121], v[162:165], v[188:191], v[118:121]
	v_mfma_f32_16x16x32_bf16 v[122:125], v[170:173], v[188:191], v[122:125]
	v_mfma_f32_16x16x32_bf16 v[122:125], v[174:177], v[196:199], v[122:125]
	v_mfma_f32_16x16x32_bf16 v[114:117], v[184:187], v[196:199], v[114:117]
	v_mfma_f32_16x16x32_bf16 v[114:117], v[180:183], v[188:191], v[114:117]
	v_mfma_f32_16x16x32_bf16 v[98:101], v[180:183], v[200:203], v[98:101]
	v_mfma_f32_16x16x32_bf16 v[98:101], v[184:187], v[204:207], v[98:101]
	v_mfma_f32_16x16x32_bf16 v[106:109], v[174:177], v[204:207], v[106:109]
	v_mfma_f32_16x16x32_bf16 v[106:109], v[170:173], v[200:203], v[106:109]
	v_mfma_f32_16x16x32_bf16 v[102:105], v[162:165], v[200:203], v[102:105]
	v_mfma_f32_16x16x32_bf16 v[102:105], v[166:169], v[204:207], v[102:105]
	v_mfma_f32_16x16x32_bf16 v[110:113], v[158:161], v[204:207], v[110:113]
	v_mfma_f32_16x16x32_bf16 v[110:113], v[154:157], v[200:203], v[110:113]
	v_mfma_f32_16x16x32_bf16 v[94:97], v[154:157], v[208:211], v[94:97]
	v_mfma_f32_16x16x32_bf16 v[94:97], v[158:161], v[212:215], v[94:97]
	v_mfma_f32_16x16x32_bf16 v[86:89], v[166:169], v[212:215], v[86:89]
	v_mfma_f32_16x16x32_bf16 v[86:89], v[162:165], v[208:211], v[86:89]
	v_mfma_f32_16x16x32_bf16 v[90:93], v[170:173], v[208:211], v[90:93]
	v_mfma_f32_16x16x32_bf16 v[90:93], v[174:177], v[212:215], v[90:93]
	v_mfma_f32_16x16x32_bf16 v[82:85], v[184:187], v[212:215], v[82:85]
	v_mfma_f32_16x16x32_bf16 v[82:85], v[180:183], v[208:211], v[82:85]
	v_mfma_f32_16x16x32_bf16 v[66:69], v[180:183], v[216:219], v[66:69]
	v_mfma_f32_16x16x32_bf16 v[66:69], v[184:187], v[220:223], v[66:69]
	v_mfma_f32_16x16x32_bf16 v[74:77], v[174:177], v[220:223], v[74:77]
	v_mfma_f32_16x16x32_bf16 v[74:77], v[170:173], v[216:219], v[74:77]
	v_mfma_f32_16x16x32_bf16 v[70:73], v[162:165], v[216:219], v[70:73]
	v_mfma_f32_16x16x32_bf16 v[70:73], v[166:169], v[220:223], v[70:73]
	v_mfma_f32_16x16x32_bf16 v[78:81], v[158:161], v[220:223], v[78:81]
	v_mfma_f32_16x16x32_bf16 v[78:81], v[154:157], v[216:219], v[78:81]
	s_barrier
	s_add_i32 s77, s61, s3
	s_mov_b32 m0, s77
	ds_read_b128 v[188:191], v152 offset:16384
	ds_read_b128 v[196:199], v152 offset:17408
	ds_read_b128 v[200:203], v152 offset:18432
	ds_read_b128 v[204:207], v152 offset:19456
	ds_read_b128 v[208:211], v152 offset:20480
	ds_read_b128 v[212:215], v152 offset:21504
	ds_read_b128 v[216:219], v152 offset:22528
	ds_read_b128 v[220:223], v152 offset:23552
	global_load_lds_dwordx4 v132, s[72:73]
	s_add_i32 m0, s77, 0x2000
	s_add_u32 s78, s72, 0x4000
	s_addc_u32 s79, s73, 0
	s_add_i32 s77, s62, s3
	global_load_lds_dwordx4 v136, s[72:73]
	s_mov_b32 m0, s77
	s_nop 0
	global_load_lds_dwordx4 v132, s[78:79]
	s_add_i32 m0, s77, 0x2000
	s_nop 0
	global_load_lds_dwordx4 v136, s[78:79]
	s_waitcnt vmcnt(6)
	s_waitcnt lgkmcnt(0)
	s_barrier
	s_waitcnt lgkmcnt(0)
	v_mfma_f32_16x16x32_bf16 v[62:65], v[154:157], v[188:191], v[62:65]
	v_mfma_f32_16x16x32_bf16 v[62:65], v[158:161], v[196:199], v[62:65]
	v_mfma_f32_16x16x32_bf16 v[54:57], v[166:169], v[196:199], v[54:57]
	v_mfma_f32_16x16x32_bf16 v[54:57], v[162:165], v[188:191], v[54:57]
	v_mfma_f32_16x16x32_bf16 v[58:61], v[170:173], v[188:191], v[58:61]
	v_mfma_f32_16x16x32_bf16 v[58:61], v[174:177], v[196:199], v[58:61]
	v_mfma_f32_16x16x32_bf16 v[50:53], v[184:187], v[196:199], v[50:53]
	v_mfma_f32_16x16x32_bf16 v[50:53], v[180:183], v[188:191], v[50:53]
	v_mfma_f32_16x16x32_bf16 v[34:37], v[180:183], v[200:203], v[34:37]
	v_mfma_f32_16x16x32_bf16 v[34:37], v[184:187], v[204:207], v[34:37]
	v_mfma_f32_16x16x32_bf16 v[42:45], v[174:177], v[204:207], v[42:45]
	v_mfma_f32_16x16x32_bf16 v[42:45], v[170:173], v[200:203], v[42:45]
	v_mfma_f32_16x16x32_bf16 v[38:41], v[162:165], v[200:203], v[38:41]
	v_mfma_f32_16x16x32_bf16 v[38:41], v[166:169], v[204:207], v[38:41]
	v_mfma_f32_16x16x32_bf16 v[46:49], v[158:161], v[204:207], v[46:49]
	v_mfma_f32_16x16x32_bf16 v[46:49], v[154:157], v[200:203], v[46:49]
	v_mfma_f32_16x16x32_bf16 v[30:33], v[154:157], v[208:211], v[30:33]
	v_mfma_f32_16x16x32_bf16 v[30:33], v[158:161], v[212:215], v[30:33]
	v_mfma_f32_16x16x32_bf16 v[22:25], v[166:169], v[212:215], v[22:25]
	v_mfma_f32_16x16x32_bf16 v[22:25], v[162:165], v[208:211], v[22:25]
	v_mfma_f32_16x16x32_bf16 v[26:29], v[170:173], v[208:211], v[26:29]
	v_mfma_f32_16x16x32_bf16 v[26:29], v[174:177], v[212:215], v[26:29]
	v_mfma_f32_16x16x32_bf16 v[18:21], v[184:187], v[212:215], v[18:21]
	v_mfma_f32_16x16x32_bf16 v[18:21], v[180:183], v[208:211], v[18:21]
	v_mfma_f32_16x16x32_bf16 v[2:5], v[180:183], v[216:219], v[2:5]
	v_mfma_f32_16x16x32_bf16 v[2:5], v[184:187], v[220:223], v[2:5]
	v_mfma_f32_16x16x32_bf16 v[10:13], v[174:177], v[220:223], v[10:13]
	v_mfma_f32_16x16x32_bf16 v[10:13], v[170:173], v[216:219], v[10:13]
	v_mfma_f32_16x16x32_bf16 v[6:9], v[162:165], v[216:219], v[6:9]
	v_mfma_f32_16x16x32_bf16 v[6:9], v[166:169], v[220:223], v[6:9]
	v_mfma_f32_16x16x32_bf16 v[14:17], v[158:161], v[220:223], v[14:17]
	v_mfma_f32_16x16x32_bf16 v[14:17], v[154:157], v[216:219], v[14:17]
	s_barrier
; #define PG8_STAGE(bufoff, gbase, voff) do { _Pragma("unroll") for (int _i = 0; _i < 2; ++_i) \
;         __builtin_amdgcn_global_load_lds((const unsigned*)((const char*)(gbase) + (voff)[_i]), (PG8_LAS unsigned*)(lds + (bufoff) + ldsw + _i * 8192), 16, 0, 0); } while (0)
; #define PG8_LDA(dst, b, h) do { _Pragma("unroll") for (int m = 0; m < 4; ++m) _Pragma("unroll") for (int k = 0; k < 2; ++k) dst[m][k] = *(const PG8_LAS bf16x8*)(lds + PG8_SA(b, h) + aoff + m * 2048 + k * 1024); } while (0)
; #define PG8_LDB(dst, b, h) do { _Pragma("unroll") for (int n = 0; n < 2; ++n) _Pragma("unroll") for (int k = 0; k < 2; ++k) dst[n][k] = *(const PG8_LAS bf16x8*)(lds + PG8_SB(b, h) + boff + n * 2048 + k * 1024); } while (0)
; #define PG8_MMA(ai, bj, At, Bt) do { __builtin_amdgcn_s_setprio(1); _Pragma("unroll") for (int m = 0; m < 4; ++m) _Pragma("unroll") for (int n = 0; n < 2; ++n) _Pragma("unroll") for (int k = 0; k < 2; ++k) \
;         acc[ai][bj][m][n] = __builtin_amdgcn_mfma_f32_16x16x32_bf16(Bt[n][k], At[m][k], acc[ai][bj][m][n], 0, 0, 0); __builtin_amdgcn_s_setprio(0); } while (0)
; #define PG8_WAIT_V(n) asm volatile("s_waitcnt vmcnt(" #n ")" ::: "memory")
; #define PG8_WAIT_L(n) asm volatile("s_waitcnt lgkmcnt(" #n ")" ::: "memory")
; #define PG8_BAR __builtin_amdgcn_s_barrier()
; #define PG8_SCHED __builtin_amdgcn_sched_barrier(0)
; template <class Epi, class Sched, bool ALIGN_EPI = false, bool SP2 = false>
; __device__ __forceinline__ void gemm_phase(PG8_LAS unsigned char* lds, const Gemm g, const Sched& S, const Epi& E) {
;     ...
;             PG8_LDB(B0, 1, 0); PG8_LDB(B1, 1, 1); PG8_SCHED; PG8_LDA(At, 1, 0); PG8_STAGE(PG8_SA(0, 1), a2 + hstep, voffA);
;             PG8_WAIT_V(8); PG8_WAIT_L(0); PG8_BAR; PG8_MMA(0, 0, At, B0); PG8_MMA(0, 1, At, B1); PG8_BAR; PG8_SCHED;
;             PG8_LDA(At, 1, 1); PG8_STAGE(PG8_SB(1, 0), b3, voffB); PG8_STAGE(PG8_SB(1, 1), b3 + hstep, voffB); PG8_STAGE(PG8_SA(1, 0), a3, voffA);
;             PG8_WAIT_V(8); PG8_WAIT_L(0); PG8_BAR; PG8_MMA(1, 0, At, B0); PG8_MMA(1, 1, At, B1); PG8_BAR; PG8_SCHED;
	s_add_i32 s77, 0, 0x18000
	v_add_u32_e32 v138, s77, v148
	s_add_i32 s78, 0, 0x1c000
	ds_read_b128 v[154:157], v138
	ds_read_b128 v[158:161], v138 offset:1024
	ds_read_b128 v[162:165], v138 offset:2048
	ds_read_b128 v[166:169], v138 offset:3072
	v_add_u32_e32 v138, s78, v148
	ds_read_b128 v[170:173], v138
	ds_read_b128 v[174:177], v138 offset:1024
	ds_read_b128 v[180:183], v138 offset:2048
	ds_read_b128 v[184:187], v138 offset:3072
	s_mov_b32 m0, s28
	s_nop 0
	global_load_lds_dwordx4 v130, s[74:75]
	s_mov_b32 m0, s29
	s_nop 0
	global_load_lds_dwordx4 v134, s[74:75]
	s_add_u32 s74, s74, 0x4000
	s_addc_u32 s75, s75, 0
	s_mov_b32 m0, s30
	ds_read_b128 v[188:191], v152 offset:32768
	ds_read_b128 v[196:199], v152 offset:33792
	ds_read_b128 v[200:203], v152 offset:34816
	ds_read_b128 v[204:207], v152 offset:35840
	ds_read_b128 v[208:211], v152 offset:36864
	ds_read_b128 v[212:215], v152 offset:37888
	ds_read_b128 v[216:219], v152 offset:38912
	ds_read_b128 v[220:223], v152 offset:39936
	global_load_lds_dwordx4 v130, s[74:75]
	s_mov_b32 m0, s31
	s_nop 0
	global_load_lds_dwordx4 v134, s[74:75]
	s_waitcnt vmcnt(8)
	s_waitcnt lgkmcnt(0)
	s_barrier
	s_waitcnt lgkmcnt(0)
	v_mfma_f32_16x16x32_bf16 v[126:129], v[154:157], v[188:191], v[126:129]
	v_mfma_f32_16x16x32_bf16 v[126:129], v[158:161], v[196:199], v[126:129]
	v_mfma_f32_16x16x32_bf16 v[118:121], v[166:169], v[196:199], v[118:121]
	v_mfma_f32_16x16x32_bf16 v[118:121], v[162:165], v[188:191], v[118:121]
	v_mfma_f32_16x16x32_bf16 v[122:125], v[170:173], v[188:191], v[122:125]
	v_mfma_f32_16x16x32_bf16 v[122:125], v[174:177], v[196:199], v[122:125]
	v_mfma_f32_16x16x32_bf16 v[114:117], v[184:187], v[196:199], v[114:117]
	v_mfma_f32_16x16x32_bf16 v[114:117], v[180:183], v[188:191], v[114:117]
	v_mfma_f32_16x16x32_bf16 v[98:101], v[180:183], v[200:203], v[98:101]
	v_mfma_f32_16x16x32_bf16 v[98:101], v[184:187], v[204:207], v[98:101]
	v_mfma_f32_16x16x32_bf16 v[106:109], v[174:177], v[204:207], v[106:109]
	v_mfma_f32_16x16x32_bf16 v[106:109], v[170:173], v[200:203], v[106:109]
	v_mfma_f32_16x16x32_bf16 v[102:105], v[162:165], v[200:203], v[102:105]
	v_mfma_f32_16x16x32_bf16 v[102:105], v[166:169], v[204:207], v[102:105]
	v_mfma_f32_16x16x32_bf16 v[110:113], v[158:161], v[204:207], v[110:113]
	v_mfma_f32_16x16x32_bf16 v[110:113], v[154:157], v[200:203], v[110:113]
	v_mfma_f32_16x16x32_bf16 v[94:97], v[154:157], v[208:211], v[94:97]
	v_mfma_f32_16x16x32_bf16 v[94:97], v[158:161], v[212:215], v[94:97]
	v_mfma_f32_16x16x32_bf16 v[86:89], v[166:169], v[212:215], v[86:89]
	v_mfma_f32_16x16x32_bf16 v[86:89], v[162:165], v[208:211], v[86:89]
	v_mfma_f32_16x16x32_bf16 v[90:93], v[170:173], v[208:211], v[90:93]
	v_mfma_f32_16x16x32_bf16 v[90:93], v[174:177], v[212:215], v[90:93]
	v_mfma_f32_16x16x32_bf16 v[82:85], v[184:187], v[212:215], v[82:85]
	v_mfma_f32_16x16x32_bf16 v[82:85], v[180:183], v[208:211], v[82:85]
	v_mfma_f32_16x16x32_bf16 v[66:69], v[180:183], v[216:219], v[66:69]
	v_mfma_f32_16x16x32_bf16 v[66:69], v[184:187], v[220:223], v[66:69]
	v_mfma_f32_16x16x32_bf16 v[74:77], v[174:177], v[220:223], v[74:77]
	v_mfma_f32_16x16x32_bf16 v[74:77], v[170:173], v[216:219], v[74:77]
	v_mfma_f32_16x16x32_bf16 v[70:73], v[162:165], v[216:219], v[70:73]
	v_mfma_f32_16x16x32_bf16 v[70:73], v[166:169], v[220:223], v[70:73]
	v_mfma_f32_16x16x32_bf16 v[78:81], v[158:161], v[220:223], v[78:81]
	v_mfma_f32_16x16x32_bf16 v[78:81], v[154:157], v[216:219], v[78:81]
	s_barrier
	s_add_u32 s74, s72, 0x8000
	s_addc_u32 s75, s73, 0
	s_add_i32 s77, s77, s3
	s_mov_b32 m0, s77
	ds_read_b128 v[188:191], v152 offset:49152
	ds_read_b128 v[196:199], v152 offset:50176
	ds_read_b128 v[200:203], v152 offset:51200
	ds_read_b128 v[204:207], v152 offset:52224
	ds_read_b128 v[208:211], v152 offset:53248
	ds_read_b128 v[212:215], v152 offset:54272
	ds_read_b128 v[216:219], v152 offset:55296
	ds_read_b128 v[220:223], v152 offset:56320
	global_load_lds_dwordx4 v132, s[74:75]
	s_add_i32 m0, s77, 0x2000
	s_add_u32 s72, s72, 0xc000
	v_lshl_add_u64 v[224:225], s[74:75], 0, v[136:137]
	s_addc_u32 s73, s73, 0
	s_add_i32 s74, s78, s3
	global_load_lds_dwordx4 v[224:225], off
	s_mov_b32 m0, s74
	s_nop 0
	global_load_lds_dwordx4 v132, s[72:73]
	s_add_i32 m0, s74, 0x2000
	s_nop 0
	global_load_lds_dwordx4 v136, s[72:73]
	s_waitcnt vmcnt(6)
	s_waitcnt lgkmcnt(0)
	s_barrier
	s_waitcnt lgkmcnt(0)
	v_mfma_f32_16x16x32_bf16 v[62:65], v[154:157], v[188:191], v[62:65]
	v_mfma_f32_16x16x32_bf16 v[62:65], v[158:161], v[196:199], v[62:65]
	v_mfma_f32_16x16x32_bf16 v[54:57], v[166:169], v[196:199], v[54:57]
	v_mfma_f32_16x16x32_bf16 v[54:57], v[162:165], v[188:191], v[54:57]
	v_mfma_f32_16x16x32_bf16 v[58:61], v[170:173], v[188:191], v[58:61]
	v_mfma_f32_16x16x32_bf16 v[58:61], v[174:177], v[196:199], v[58:61]
	v_mfma_f32_16x16x32_bf16 v[50:53], v[184:187], v[196:199], v[50:53]
	v_mfma_f32_16x16x32_bf16 v[50:53], v[180:183], v[188:191], v[50:53]
	v_mfma_f32_16x16x32_bf16 v[34:37], v[180:183], v[200:203], v[34:37]
	v_mfma_f32_16x16x32_bf16 v[34:37], v[184:187], v[204:207], v[34:37]
	v_mfma_f32_16x16x32_bf16 v[42:45], v[174:177], v[204:207], v[42:45]
	v_mfma_f32_16x16x32_bf16 v[42:45], v[170:173], v[200:203], v[42:45]
	v_mfma_f32_16x16x32_bf16 v[38:41], v[162:165], v[200:203], v[38:41]
	v_mfma_f32_16x16x32_bf16 v[38:41], v[166:169], v[204:207], v[38:41]
	v_mfma_f32_16x16x32_bf16 v[46:49], v[158:161], v[204:207], v[46:49]
	v_mfma_f32_16x16x32_bf16 v[46:49], v[154:157], v[200:203], v[46:49]
	v_mfma_f32_16x16x32_bf16 v[30:33], v[154:157], v[208:211], v[30:33]
	v_mfma_f32_16x16x32_bf16 v[30:33], v[158:161], v[212:215], v[30:33]
	v_mfma_f32_16x16x32_bf16 v[22:25], v[166:169], v[212:215], v[22:25]
	v_mfma_f32_16x16x32_bf16 v[22:25], v[162:165], v[208:211], v[22:25]
	v_mfma_f32_16x16x32_bf16 v[26:29], v[170:173], v[208:211], v[26:29]
	v_mfma_f32_16x16x32_bf16 v[26:29], v[174:177], v[212:215], v[26:29]
	v_mfma_f32_16x16x32_bf16 v[18:21], v[184:187], v[212:215], v[18:21]
	v_mfma_f32_16x16x32_bf16 v[18:21], v[180:183], v[208:211], v[18:21]
	v_mfma_f32_16x16x32_bf16 v[2:5], v[180:183], v[216:219], v[2:5]
	v_mfma_f32_16x16x32_bf16 v[2:5], v[184:187], v[220:223], v[2:5]
	v_mfma_f32_16x16x32_bf16 v[10:13], v[174:177], v[220:223], v[10:13]
	v_mfma_f32_16x16x32_bf16 v[10:13], v[170:173], v[216:219], v[10:13]
	v_mfma_f32_16x16x32_bf16 v[6:9], v[162:165], v[216:219], v[6:9]
	v_mfma_f32_16x16x32_bf16 v[6:9], v[166:169], v[220:223], v[6:9]
	v_mfma_f32_16x16x32_bf16 v[14:17], v[158:161], v[220:223], v[14:17]
	v_mfma_f32_16x16x32_bf16 v[14:17], v[154:157], v[216:219], v[14:17]
	s_barrier
	s_add_i32 s76, s76, 2
	s_add_u32 s48, s48, 0x10000
	s_addc_u32 s49, s49, 0
	s_add_u32 s68, s68, 0x10000
	s_addc_u32 s69, s69, 0
	s_cmp_gt_u32 s76, 61
	s_cbranch_scc0 .LBB0_115
	s_and_b64 vcc, exec, s[14:15]
	s_cbranch_vccz .LBB0_118
	s_barrier

; #define PG8_STAGE(bufoff, gbase, voff) do { _Pragma("unroll") for (int _i = 0; _i < 2; ++_i) \
;         __builtin_amdgcn_global_load_lds((const unsigned*)((const char*)(gbase) + (voff)[_i]), (PG8_LAS unsigned*)(lds + (bufoff) + ldsw + _i * 8192), 16, 0, 0); } while (0)
; #define PG8_LDA(dst, b, h) do { _Pragma("unroll") for (int m = 0; m < 4; ++m) _Pragma("unroll") for (int k = 0; k < 2; ++k) dst[m][k] = *(const PG8_LAS bf16x8*)(lds + PG8_SA(b, h) + aoff + m * 2048 + k * 1024); } while (0)
; #define PG8_LDB(dst, b, h) do { _Pragma("unroll") for (int n = 0; n < 2; ++n) _Pragma("unroll") for (int k = 0; k < 2; ++k) dst[n][k] = *(const PG8_LAS bf16x8*)(lds + PG8_SB(b, h) + boff + n * 2048 + k * 1024); } while (0)
; #define PG8_MMA(ai, bj, At, Bt) do { __builtin_amdgcn_s_setprio(1); _Pragma("unroll") for (int m = 0; m < 4; ++m) _Pragma("unroll") for (int n = 0; n < 2; ++n) _Pragma("unroll") for (int k = 0; k < 2; ++k) \
;         acc[ai][bj][m][n] = __builtin_amdgcn_mfma_f32_16x16x32_bf16(Bt[n][k], At[m][k], acc[ai][bj][m][n], 0, 0, 0); __builtin_amdgcn_s_setprio(0); } while (0)
; #define PG8_WAIT_V(n) asm volatile("s_waitcnt vmcnt(" #n ")" ::: "memory")
; #define PG8_WAIT_L(n) asm volatile("s_waitcnt lgkmcnt(" #n ")" ::: "memory")
; #define PG8_BAR __builtin_amdgcn_s_barrier()
; #define PG8_SCHED __builtin_amdgcn_sched_barrier(0)
; template <class Epi, class Sched, bool ALIGN_EPI = false, bool SP2 = false>
; __device__ __forceinline__ void gemm_phase(PG8_LAS unsigned char* lds, const Gemm g, const Sched& S, const Epi& E) {
;     ...
;             PG8_LDB(B0, 0, 0); PG8_LDB(B1, 0, 1); PG8_SCHED; PG8_LDA(At, 0, 0); PG8_STAGE(PG8_SA(1, 1), a1 + hstep, voffA);
;             PG8_WAIT_V(8); PG8_WAIT_L(0); PG8_BAR; PG8_MMA(0, 0, At, B0); PG8_MMA(0, 1, At, B1); PG8_BAR; PG8_SCHED;
;             PG8_LDA(At, 0, 1); PG8_STAGE(PG8_SB(0, 0), b2, voffB); PG8_STAGE(PG8_SB(0, 1), b2 + hstep, voffB); PG8_STAGE(PG8_SA(0, 0), a2, voffA);
;             PG8_WAIT_V(8); PG8_WAIT_L(0); PG8_BAR; PG8_MMA(1, 0, At, B0); PG8_MMA(1, 1, At, B1); PG8_BAR; PG8_SCHED;
.LBB0_200:
	ds_read_b128 v[148:151], v154
	ds_read_b128 v[158:161], v154 offset:1024
	ds_read_b128 v[162:165], v154 offset:2048
	ds_read_b128 v[166:169], v154 offset:3072
	ds_read_b128 v[170:173], v155
	ds_read_b128 v[174:177], v155 offset:1024
	ds_read_b128 v[180:183], v155 offset:2048
	ds_read_b128 v[184:187], v155 offset:3072
	s_add_u32 s46, s44, 0x4000
	s_addc_u32 s47, s45, 0
	s_cmpk_eq_i32 s76, 0xa8
	s_cselect_b32 s50, s6, s46
	s_cselect_b32 s51, s7, s47
	s_cselect_b32 s48, s24, s74
	s_cselect_b32 s49, s25, s75
	s_add_u32 s46, s50, 0x8000
	s_addc_u32 s47, s51, 0
	s_sub_u32 s46, s44, 0x4000
	s_subb_u32 s47, s45, 0
	s_mov_b32 m0, s57
	s_nop 0
	global_load_lds_dwordx4 v130, s[46:47]
	s_mov_b32 m0, s58
	s_nop 0
	global_load_lds_dwordx4 v134, s[46:47]
	s_add_i32 m0, s26, 0xc000
	ds_read_b128 v[188:191], v156
	ds_read_b128 v[196:199], v156 offset:1024
	ds_read_b128 v[200:203], v156 offset:2048
	ds_read_b128 v[204:207], v156 offset:3072
	ds_read_b128 v[208:211], v156 offset:4096
	ds_read_b128 v[212:215], v156 offset:5120
	ds_read_b128 v[216:219], v156 offset:6144
	ds_read_b128 v[220:223], v156 offset:7168
	global_load_lds_dwordx4 v140, s[44:45]
	s_add_i32 m0, s26, 0xe000
	s_nop 0
	global_load_lds_dwordx4 v142, s[44:45]
	s_waitcnt vmcnt(8)
	s_waitcnt lgkmcnt(0)
	s_barrier
	s_waitcnt lgkmcnt(0)
	v_mfma_f32_16x16x32_bf16 v[126:129], v[148:151], v[188:191], v[126:129]
	v_mfma_f32_16x16x32_bf16 v[126:129], v[158:161], v[196:199], v[126:129]
	v_mfma_f32_16x16x32_bf16 v[122:125], v[166:169], v[196:199], v[122:125]
	v_mfma_f32_16x16x32_bf16 v[122:125], v[162:165], v[188:191], v[122:125]
	v_mfma_f32_16x16x32_bf16 v[118:121], v[170:173], v[188:191], v[118:121]
	v_mfma_f32_16x16x32_bf16 v[118:121], v[174:177], v[196:199], v[118:121]
	v_mfma_f32_16x16x32_bf16 v[114:117], v[184:187], v[196:199], v[114:117]
	v_mfma_f32_16x16x32_bf16 v[114:117], v[180:183], v[188:191], v[114:117]
	v_mfma_f32_16x16x32_bf16 v[98:101], v[180:183], v[200:203], v[98:101]
	v_mfma_f32_16x16x32_bf16 v[98:101], v[184:187], v[204:207], v[98:101]
	v_mfma_f32_16x16x32_bf16 v[102:105], v[174:177], v[204:207], v[102:105]
	v_mfma_f32_16x16x32_bf16 v[102:105], v[170:173], v[200:203], v[102:105]
	v_mfma_f32_16x16x32_bf16 v[106:109], v[162:165], v[200:203], v[106:109]
	v_mfma_f32_16x16x32_bf16 v[106:109], v[166:169], v[204:207], v[106:109]
	v_mfma_f32_16x16x32_bf16 v[110:113], v[158:161], v[204:207], v[110:113]
	v_mfma_f32_16x16x32_bf16 v[110:113], v[148:151], v[200:203], v[110:113]
	v_mfma_f32_16x16x32_bf16 v[94:97], v[148:151], v[208:211], v[94:97]
	v_mfma_f32_16x16x32_bf16 v[94:97], v[158:161], v[212:215], v[94:97]
	v_mfma_f32_16x16x32_bf16 v[90:93], v[166:169], v[212:215], v[90:93]
	v_mfma_f32_16x16x32_bf16 v[90:93], v[162:165], v[208:211], v[90:93]
	v_mfma_f32_16x16x32_bf16 v[86:89], v[170:173], v[208:211], v[86:89]
	v_mfma_f32_16x16x32_bf16 v[86:89], v[174:177], v[212:215], v[86:89]
	v_mfma_f32_16x16x32_bf16 v[82:85], v[184:187], v[212:215], v[82:85]
	v_mfma_f32_16x16x32_bf16 v[82:85], v[180:183], v[208:211], v[82:85]
	v_mfma_f32_16x16x32_bf16 v[66:69], v[180:183], v[216:219], v[66:69]
	v_mfma_f32_16x16x32_bf16 v[66:69], v[184:187], v[220:223], v[66:69]
	v_mfma_f32_16x16x32_bf16 v[70:73], v[174:177], v[220:223], v[70:73]
	v_mfma_f32_16x16x32_bf16 v[70:73], v[170:173], v[216:219], v[70:73]
	v_mfma_f32_16x16x32_bf16 v[74:77], v[162:165], v[216:219], v[74:77]
	v_mfma_f32_16x16x32_bf16 v[74:77], v[166:169], v[220:223], v[74:77]
	v_mfma_f32_16x16x32_bf16 v[78:81], v[158:161], v[220:223], v[78:81]
	v_mfma_f32_16x16x32_bf16 v[78:81], v[148:151], v[216:219], v[78:81]
	s_barrier
	s_add_i32 s77, s59, s3
	s_mov_b32 m0, s77
	ds_read_b128 v[188:191], v156 offset:16384
	ds_read_b128 v[196:199], v156 offset:17408
	ds_read_b128 v[200:203], v156 offset:18432
	ds_read_b128 v[204:207], v156 offset:19456
	ds_read_b128 v[208:211], v156 offset:20480
	ds_read_b128 v[212:215], v156 offset:21504
	ds_read_b128 v[216:219], v156 offset:22528
	ds_read_b128 v[220:223], v156 offset:23552
	global_load_lds_dwordx4 v132, s[48:49]
	s_add_i32 m0, s77, 0x2000
	s_add_u32 s78, s48, 0x4000
	s_addc_u32 s79, s49, 0
	s_add_i32 s77, s61, s3
	global_load_lds_dwordx4 v136, s[48:49]
	s_mov_b32 m0, s77
	s_nop 0
	global_load_lds_dwordx4 v132, s[78:79]
	s_add_i32 m0, s77, 0x2000
	s_nop 0
	global_load_lds_dwordx4 v136, s[78:79]
	s_waitcnt vmcnt(6)
	s_waitcnt lgkmcnt(0)
	s_barrier
	s_waitcnt lgkmcnt(0)
	v_mfma_f32_16x16x32_bf16 v[62:65], v[148:151], v[188:191], v[62:65]
	v_mfma_f32_16x16x32_bf16 v[62:65], v[158:161], v[196:199], v[62:65]
	v_mfma_f32_16x16x32_bf16 v[58:61], v[166:169], v[196:199], v[58:61]
	v_mfma_f32_16x16x32_bf16 v[58:61], v[162:165], v[188:191], v[58:61]
	v_mfma_f32_16x16x32_bf16 v[54:57], v[170:173], v[188:191], v[54:57]
	v_mfma_f32_16x16x32_bf16 v[54:57], v[174:177], v[196:199], v[54:57]
	v_mfma_f32_16x16x32_bf16 v[50:53], v[184:187], v[196:199], v[50:53]
	v_mfma_f32_16x16x32_bf16 v[50:53], v[180:183], v[188:191], v[50:53]
	v_mfma_f32_16x16x32_bf16 v[34:37], v[180:183], v[200:203], v[34:37]
	v_mfma_f32_16x16x32_bf16 v[34:37], v[184:187], v[204:207], v[34:37]
	v_mfma_f32_16x16x32_bf16 v[38:41], v[174:177], v[204:207], v[38:41]
	v_mfma_f32_16x16x32_bf16 v[38:41], v[170:173], v[200:203], v[38:41]
	v_mfma_f32_16x16x32_bf16 v[42:45], v[162:165], v[200:203], v[42:45]
	v_mfma_f32_16x16x32_bf16 v[42:45], v[166:169], v[204:207], v[42:45]
	v_mfma_f32_16x16x32_bf16 v[46:49], v[158:161], v[204:207], v[46:49]
	v_mfma_f32_16x16x32_bf16 v[46:49], v[148:151], v[200:203], v[46:49]
	v_mfma_f32_16x16x32_bf16 v[30:33], v[148:151], v[208:211], v[30:33]
	v_mfma_f32_16x16x32_bf16 v[30:33], v[158:161], v[212:215], v[30:33]
	v_mfma_f32_16x16x32_bf16 v[26:29], v[166:169], v[212:215], v[26:29]
	v_mfma_f32_16x16x32_bf16 v[26:29], v[162:165], v[208:211], v[26:29]
	v_mfma_f32_16x16x32_bf16 v[22:25], v[170:173], v[208:211], v[22:25]
	v_mfma_f32_16x16x32_bf16 v[22:25], v[174:177], v[212:215], v[22:25]
	v_mfma_f32_16x16x32_bf16 v[18:21], v[184:187], v[212:215], v[18:21]
	v_mfma_f32_16x16x32_bf16 v[18:21], v[180:183], v[208:211], v[18:21]
	v_mfma_f32_16x16x32_bf16 v[2:5], v[180:183], v[216:219], v[2:5]
	v_mfma_f32_16x16x32_bf16 v[2:5], v[184:187], v[220:223], v[2:5]
	v_mfma_f32_16x16x32_bf16 v[6:9], v[174:177], v[220:223], v[6:9]
	v_mfma_f32_16x16x32_bf16 v[6:9], v[170:173], v[216:219], v[6:9]
	v_mfma_f32_16x16x32_bf16 v[10:13], v[162:165], v[216:219], v[10:13]
	v_mfma_f32_16x16x32_bf16 v[10:13], v[166:169], v[220:223], v[10:13]
	v_mfma_f32_16x16x32_bf16 v[14:17], v[158:161], v[220:223], v[14:17]
	v_mfma_f32_16x16x32_bf16 v[14:17], v[148:151], v[216:219], v[14:17]
	s_barrier
; #define PG8_STAGE(bufoff, gbase, voff) do { _Pragma("unroll") for (int _i = 0; _i < 2; ++_i) \
;         __builtin_amdgcn_global_load_lds((const unsigned*)((const char*)(gbase) + (voff)[_i]), (PG8_LAS unsigned*)(lds + (bufoff) + ldsw + _i * 8192), 16, 0, 0); } while (0)
; #define PG8_LDA(dst, b, h) do { _Pragma("unroll") for (int m = 0; m < 4; ++m) _Pragma("unroll") for (int k = 0; k < 2; ++k) dst[m][k] = *(const PG8_LAS bf16x8*)(lds + PG8_SA(b, h) + aoff + m * 2048 + k * 1024); } while (0)
; #define PG8_LDB(dst, b, h) do { _Pragma("unroll") for (int n = 0; n < 2; ++n) _Pragma("unroll") for (int k = 0; k < 2; ++k) dst[n][k] = *(const PG8_LAS bf16x8*)(lds + PG8_SB(b, h) + boff + n * 2048 + k * 1024); } while (0)
; #define PG8_MMA(ai, bj, At, Bt) do { __builtin_amdgcn_s_setprio(1); _Pragma("unroll") for (int m = 0; m < 4; ++m) _Pragma("unroll") for (int n = 0; n < 2; ++n) _Pragma("unroll") for (int k = 0; k < 2; ++k) \
;         acc[ai][bj][m][n] = __builtin_amdgcn_mfma_f32_16x16x32_bf16(Bt[n][k], At[m][k], acc[ai][bj][m][n], 0, 0, 0); __builtin_amdgcn_s_setprio(0); } while (0)
; #define PG8_WAIT_V(n) asm volatile("s_waitcnt vmcnt(" #n ")" ::: "memory")
; #define PG8_WAIT_L(n) asm volatile("s_waitcnt lgkmcnt(" #n ")" ::: "memory")
; #define PG8_BAR __builtin_amdgcn_s_barrier()
; #define PG8_SCHED __builtin_amdgcn_sched_barrier(0)
; template <class Epi, class Sched, bool ALIGN_EPI = false, bool SP2 = false>
; __device__ __forceinline__ void gemm_phase(PG8_LAS unsigned char* lds, const Gemm g, const Sched& S, const Epi& E) {
;     ...
;             PG8_LDB(B0, 1, 0); PG8_LDB(B1, 1, 1); PG8_SCHED; PG8_LDA(At, 1, 0); PG8_STAGE(PG8_SA(0, 1), a2 + hstep, voffA);
;             PG8_WAIT_V(8); PG8_WAIT_L(0); PG8_BAR; PG8_MMA(0, 0, At, B0); PG8_MMA(0, 1, At, B1); PG8_BAR; PG8_SCHED;
;             PG8_LDA(At, 1, 1); PG8_STAGE(PG8_SB(1, 0), b3, voffB); PG8_STAGE(PG8_SB(1, 1), b3 + hstep, voffB); PG8_STAGE(PG8_SA(1, 0), a3, voffA);
;             PG8_WAIT_V(8); PG8_WAIT_L(0); PG8_BAR; PG8_MMA(1, 0, At, B0); PG8_MMA(1, 1, At, B1); PG8_BAR; PG8_SCHED;
	s_add_i32 s77, 0, 0x18000
	v_add_u32_e32 v138, s77, v153
	s_add_i32 s78, 0, 0x1c000
	ds_read_b128 v[148:151], v138
	ds_read_b128 v[158:161], v138 offset:1024
	ds_read_b128 v[162:165], v138 offset:2048
	ds_read_b128 v[166:169], v138 offset:3072
	v_add_u32_e32 v138, s78, v153
	ds_read_b128 v[170:173], v138
	ds_read_b128 v[174:177], v138 offset:1024
	ds_read_b128 v[180:183], v138 offset:2048
	ds_read_b128 v[184:187], v138 offset:3072
	s_mov_b32 m0, s26
	s_nop 0
	global_load_lds_dwordx4 v130, s[50:51]
	s_mov_b32 m0, s27
	s_nop 0
	global_load_lds_dwordx4 v134, s[50:51]
	s_add_u32 s50, s50, 0x4000
	s_addc_u32 s51, s51, 0
	s_mov_b32 m0, s28
	ds_read_b128 v[188:191], v156 offset:32768
	ds_read_b128 v[196:199], v156 offset:33792
	ds_read_b128 v[200:203], v156 offset:34816
	ds_read_b128 v[204:207], v156 offset:35840
	ds_read_b128 v[208:211], v156 offset:36864
	ds_read_b128 v[212:215], v156 offset:37888
	ds_read_b128 v[216:219], v156 offset:38912
	ds_read_b128 v[220:223], v156 offset:39936
	global_load_lds_dwordx4 v130, s[50:51]
	s_mov_b32 m0, s29
	s_nop 0
	global_load_lds_dwordx4 v134, s[50:51]
	s_waitcnt vmcnt(8)
	s_waitcnt lgkmcnt(0)
	s_barrier
	s_waitcnt lgkmcnt(0)
	v_mfma_f32_16x16x32_bf16 v[126:129], v[148:151], v[188:191], v[126:129]
	v_mfma_f32_16x16x32_bf16 v[126:129], v[158:161], v[196:199], v[126:129]
	v_mfma_f32_16x16x32_bf16 v[122:125], v[166:169], v[196:199], v[122:125]
	v_mfma_f32_16x16x32_bf16 v[122:125], v[162:165], v[188:191], v[122:125]
	v_mfma_f32_16x16x32_bf16 v[118:121], v[170:173], v[188:191], v[118:121]
	v_mfma_f32_16x16x32_bf16 v[118:121], v[174:177], v[196:199], v[118:121]
	v_mfma_f32_16x16x32_bf16 v[114:117], v[184:187], v[196:199], v[114:117]
	v_mfma_f32_16x16x32_bf16 v[114:117], v[180:183], v[188:191], v[114:117]
	v_mfma_f32_16x16x32_bf16 v[98:101], v[180:183], v[200:203], v[98:101]
	v_mfma_f32_16x16x32_bf16 v[98:101], v[184:187], v[204:207], v[98:101]
	v_mfma_f32_16x16x32_bf16 v[102:105], v[174:177], v[204:207], v[102:105]
	v_mfma_f32_16x16x32_bf16 v[102:105], v[170:173], v[200:203], v[102:105]
	v_mfma_f32_16x16x32_bf16 v[106:109], v[162:165], v[200:203], v[106:109]
	v_mfma_f32_16x16x32_bf16 v[106:109], v[166:169], v[204:207], v[106:109]
	v_mfma_f32_16x16x32_bf16 v[110:113], v[158:161], v[204:207], v[110:113]
	v_mfma_f32_16x16x32_bf16 v[110:113], v[148:151], v[200:203], v[110:113]
	v_mfma_f32_16x16x32_bf16 v[94:97], v[148:151], v[208:211], v[94:97]
	v_mfma_f32_16x16x32_bf16 v[94:97], v[158:161], v[212:215], v[94:97]
	v_mfma_f32_16x16x32_bf16 v[90:93], v[166:169], v[212:215], v[90:93]
	v_mfma_f32_16x16x32_bf16 v[90:93], v[162:165], v[208:211], v[90:93]
	v_mfma_f32_16x16x32_bf16 v[86:89], v[170:173], v[208:211], v[86:89]
	v_mfma_f32_16x16x32_bf16 v[86:89], v[174:177], v[212:215], v[86:89]
	v_mfma_f32_16x16x32_bf16 v[82:85], v[184:187], v[212:215], v[82:85]
	v_mfma_f32_16x16x32_bf16 v[82:85], v[180:183], v[208:211], v[82:85]
	v_mfma_f32_16x16x32_bf16 v[66:69], v[180:183], v[216:219], v[66:69]
	v_mfma_f32_16x16x32_bf16 v[66:69], v[184:187], v[220:223], v[66:69]
	v_mfma_f32_16x16x32_bf16 v[70:73], v[174:177], v[220:223], v[70:73]
	v_mfma_f32_16x16x32_bf16 v[70:73], v[170:173], v[216:219], v[70:73]
	v_mfma_f32_16x16x32_bf16 v[74:77], v[162:165], v[216:219], v[74:77]
	v_mfma_f32_16x16x32_bf16 v[74:77], v[166:169], v[220:223], v[74:77]
	v_mfma_f32_16x16x32_bf16 v[78:81], v[158:161], v[220:223], v[78:81]
	v_mfma_f32_16x16x32_bf16 v[78:81], v[148:151], v[216:219], v[78:81]
	s_barrier
	s_add_u32 s50, s48, 0x8000
	s_addc_u32 s51, s49, 0
	s_add_i32 s77, s77, s3
	s_mov_b32 m0, s77
	ds_read_b128 v[188:191], v156 offset:49152
	ds_read_b128 v[196:199], v156 offset:50176
	ds_read_b128 v[200:203], v156 offset:51200
	ds_read_b128 v[204:207], v156 offset:52224
	ds_read_b128 v[208:211], v156 offset:53248
	ds_read_b128 v[212:215], v156 offset:54272
	ds_read_b128 v[216:219], v156 offset:55296
	ds_read_b128 v[220:223], v156 offset:56320
	global_load_lds_dwordx4 v132, s[50:51]
	s_add_i32 m0, s77, 0x2000
	s_add_u32 s48, s48, 0xc000
	v_lshl_add_u64 v[224:225], s[50:51], 0, v[136:137]
	s_addc_u32 s49, s49, 0
	s_add_i32 s50, s78, s3
	global_load_lds_dwordx4 v[224:225], off
	s_mov_b32 m0, s50
	s_nop 0
	global_load_lds_dwordx4 v132, s[48:49]
	s_add_i32 m0, s50, 0x2000
	s_nop 0
	global_load_lds_dwordx4 v136, s[48:49]
	s_waitcnt vmcnt(6)
	s_waitcnt lgkmcnt(0)
	s_barrier
	s_waitcnt lgkmcnt(0)
	v_mfma_f32_16x16x32_bf16 v[62:65], v[148:151], v[188:191], v[62:65]
	v_mfma_f32_16x16x32_bf16 v[62:65], v[158:161], v[196:199], v[62:65]
	v_mfma_f32_16x16x32_bf16 v[58:61], v[166:169], v[196:199], v[58:61]
	v_mfma_f32_16x16x32_bf16 v[58:61], v[162:165], v[188:191], v[58:61]
	v_mfma_f32_16x16x32_bf16 v[54:57], v[170:173], v[188:191], v[54:57]
	v_mfma_f32_16x16x32_bf16 v[54:57], v[174:177], v[196:199], v[54:57]
	v_mfma_f32_16x16x32_bf16 v[50:53], v[184:187], v[196:199], v[50:53]
	v_mfma_f32_16x16x32_bf16 v[50:53], v[180:183], v[188:191], v[50:53]
	v_mfma_f32_16x16x32_bf16 v[34:37], v[180:183], v[200:203], v[34:37]
	v_mfma_f32_16x16x32_bf16 v[34:37], v[184:187], v[204:207], v[34:37]
	v_mfma_f32_16x16x32_bf16 v[38:41], v[174:177], v[204:207], v[38:41]
	v_mfma_f32_16x16x32_bf16 v[38:41], v[170:173], v[200:203], v[38:41]
	v_mfma_f32_16x16x32_bf16 v[42:45], v[162:165], v[200:203], v[42:45]
	v_mfma_f32_16x16x32_bf16 v[42:45], v[166:169], v[204:207], v[42:45]
	v_mfma_f32_16x16x32_bf16 v[46:49], v[158:161], v[204:207], v[46:49]
	v_mfma_f32_16x16x32_bf16 v[46:49], v[148:151], v[200:203], v[46:49]
	v_mfma_f32_16x16x32_bf16 v[30:33], v[148:151], v[208:211], v[30:33]
	v_mfma_f32_16x16x32_bf16 v[30:33], v[158:161], v[212:215], v[30:33]
	v_mfma_f32_16x16x32_bf16 v[26:29], v[166:169], v[212:215], v[26:29]
	v_mfma_f32_16x16x32_bf16 v[26:29], v[162:165], v[208:211], v[26:29]
	v_mfma_f32_16x16x32_bf16 v[22:25], v[170:173], v[208:211], v[22:25]
	v_mfma_f32_16x16x32_bf16 v[22:25], v[174:177], v[212:215], v[22:25]
	v_mfma_f32_16x16x32_bf16 v[18:21], v[184:187], v[212:215], v[18:21]
	v_mfma_f32_16x16x32_bf16 v[18:21], v[180:183], v[208:211], v[18:21]
	v_mfma_f32_16x16x32_bf16 v[2:5], v[180:183], v[216:219], v[2:5]
	v_mfma_f32_16x16x32_bf16 v[2:5], v[184:187], v[220:223], v[2:5]
	v_mfma_f32_16x16x32_bf16 v[6:9], v[174:177], v[220:223], v[6:9]
	v_mfma_f32_16x16x32_bf16 v[6:9], v[170:173], v[216:219], v[6:9]
	v_mfma_f32_16x16x32_bf16 v[10:13], v[162:165], v[216:219], v[10:13]
	v_mfma_f32_16x16x32_bf16 v[10:13], v[166:169], v[220:223], v[10:13]
	v_mfma_f32_16x16x32_bf16 v[14:17], v[158:161], v[220:223], v[14:17]
	v_mfma_f32_16x16x32_bf16 v[14:17], v[148:151], v[216:219], v[14:17]
	s_barrier
	s_add_i32 s76, s76, 2
	s_add_u32 s44, s44, 0x10000
	s_addc_u32 s45, s45, 0
	s_add_u32 s74, s74, 0x10000
	s_addc_u32 s75, s75, 0
	s_cmpk_gt_u32 s76, 0xa9
	s_cbranch_scc0 .LBB0_200
	s_and_b64 vcc, exec, s[18:19]
	s_cbranch_vccz .LBB0_203
	s_barrier

; #define PG8_STAGE(bufoff, gbase, voff) do { _Pragma("unroll") for (int _i = 0; _i < 2; ++_i) \
;         __builtin_amdgcn_global_load_lds((const unsigned*)((const char*)(gbase) + (voff)[_i]), (PG8_LAS unsigned*)(lds + (bufoff) + ldsw + _i * 8192), 16, 0, 0); } while (0)
; #define PG8_LDA(dst, b, h) do { _Pragma("unroll") for (int m = 0; m < 4; ++m) _Pragma("unroll") for (int k = 0; k < 2; ++k) dst[m][k] = *(const PG8_LAS bf16x8*)(lds + PG8_SA(b, h) + aoff + m * 2048 + k * 1024); } while (0)
; #define PG8_LDB(dst, b, h) do { _Pragma("unroll") for (int n = 0; n < 2; ++n) _Pragma("unroll") for (int k = 0; k < 2; ++k) dst[n][k] = *(const PG8_LAS bf16x8*)(lds + PG8_SB(b, h) + boff + n * 2048 + k * 1024); } while (0)
; #define PG8_MMA(ai, bj, At, Bt) do { __builtin_amdgcn_s_setprio(1); _Pragma("unroll") for (int m = 0; m < 4; ++m) _Pragma("unroll") for (int n = 0; n < 2; ++n) _Pragma("unroll") for (int k = 0; k < 2; ++k) \
;         acc[ai][bj][m][n] = __builtin_amdgcn_mfma_f32_16x16x32_bf16(Bt[n][k], At[m][k], acc[ai][bj][m][n], 0, 0, 0); __builtin_amdgcn_s_setprio(0); } while (0)
; #define PG8_WAIT_V(n) asm volatile("s_waitcnt vmcnt(" #n ")" ::: "memory")
; #define PG8_WAIT_L(n) asm volatile("s_waitcnt lgkmcnt(" #n ")" ::: "memory")
; #define PG8_BAR __builtin_amdgcn_s_barrier()
; #define PG8_SCHED __builtin_amdgcn_sched_barrier(0)
; template <class Epi, class Sched, bool ALIGN_EPI = false, bool SP2 = false>
; __device__ __forceinline__ void gemm_phase(PG8_LAS unsigned char* lds, const Gemm g, const Sched& S, const Epi& E) {
;     ...
;             PG8_LDB(B0, 0, 0); PG8_LDB(B1, 0, 1); PG8_SCHED; PG8_LDA(At, 0, 0); PG8_STAGE(PG8_SA(1, 1), a1 + hstep, voffA);
;             PG8_WAIT_V(8); PG8_WAIT_L(0); PG8_BAR; PG8_MMA(0, 0, At, B0); PG8_MMA(0, 1, At, B1); PG8_BAR; PG8_SCHED;
;             PG8_LDA(At, 0, 1); PG8_STAGE(PG8_SB(0, 0), b2, voffB); PG8_STAGE(PG8_SB(0, 1), b2 + hstep, voffB); PG8_STAGE(PG8_SA(0, 0), a2, voffA);
;             PG8_WAIT_V(8); PG8_WAIT_L(0); PG8_BAR; PG8_MMA(1, 0, At, B0); PG8_MMA(1, 1, At, B1); PG8_BAR; PG8_SCHED;
.LBB0_290:
	ds_read_b128 v[146:149], v162
	ds_read_b128 v[150:153], v162 offset:1024
	ds_read_b128 v[154:157], v162 offset:2048
	ds_read_b128 v[168:171], v162 offset:3072
	ds_read_b128 v[172:175], v163
	ds_read_b128 v[180:183], v163 offset:1024
	ds_read_b128 v[184:187], v163 offset:2048
	ds_read_b128 v[188:191], v163 offset:3072
	s_add_u32 s59, s72, 0x4000
	s_addc_u32 s62, s73, 0
	s_cmp_eq_u32 s58, 60
	s_cselect_b32 s78, s19, s59
	s_cselect_b32 s79, s5, s62
	s_cselect_b32 s76, s26, s33
	s_cselect_b32 s77, s17, s56
	s_add_u32 s74, s78, 0x8000
	s_addc_u32 s75, s79, 0
	s_sub_u32 s74, s72, 0x4000
	s_subb_u32 s75, s73, 0
	s_mov_b32 m0, s51
	s_nop 0
	global_load_lds_dwordx4 v130, s[74:75]
	s_mov_b32 m0, s57
	s_nop 0
	global_load_lds_dwordx4 v134, s[74:75]
	s_add_i32 m0, s15, 0xc000
	ds_read_b128 v[198:201], v164
	ds_read_b128 v[202:205], v164 offset:1024
	ds_read_b128 v[206:209], v164 offset:2048
	ds_read_b128 v[210:213], v164 offset:3072
	ds_read_b128 v[214:217], v164 offset:4096
	ds_read_b128 v[218:221], v164 offset:5120
	ds_read_b128 v[222:225], v164 offset:6144
	ds_read_b128 v[226:229], v164 offset:7168
	global_load_lds_dwordx4 v138, s[72:73]
	s_add_i32 m0, s15, 0xe000
	s_nop 0
	global_load_lds_dwordx4 v140, s[72:73]
	s_waitcnt vmcnt(8)
	s_waitcnt lgkmcnt(0)
	s_barrier
	s_waitcnt lgkmcnt(0)
	v_mfma_f32_16x16x32_bf16 v[126:129], v[146:149], v[198:201], v[126:129]
	v_mfma_f32_16x16x32_bf16 v[126:129], v[150:153], v[202:205], v[126:129]
	v_mfma_f32_16x16x32_bf16 v[122:125], v[168:171], v[202:205], v[122:125]
	v_mfma_f32_16x16x32_bf16 v[122:125], v[154:157], v[198:201], v[122:125]
	v_mfma_f32_16x16x32_bf16 v[118:121], v[172:175], v[198:201], v[118:121]
	v_mfma_f32_16x16x32_bf16 v[118:121], v[180:183], v[202:205], v[118:121]
	v_mfma_f32_16x16x32_bf16 v[114:117], v[188:191], v[202:205], v[114:117]
	v_mfma_f32_16x16x32_bf16 v[114:117], v[184:187], v[198:201], v[114:117]
	v_mfma_f32_16x16x32_bf16 v[98:101], v[184:187], v[206:209], v[98:101]
	v_mfma_f32_16x16x32_bf16 v[98:101], v[188:191], v[210:213], v[98:101]
	v_mfma_f32_16x16x32_bf16 v[102:105], v[180:183], v[210:213], v[102:105]
	v_mfma_f32_16x16x32_bf16 v[102:105], v[172:175], v[206:209], v[102:105]
	v_mfma_f32_16x16x32_bf16 v[106:109], v[154:157], v[206:209], v[106:109]
	v_mfma_f32_16x16x32_bf16 v[106:109], v[168:171], v[210:213], v[106:109]
	v_mfma_f32_16x16x32_bf16 v[110:113], v[150:153], v[210:213], v[110:113]
	v_mfma_f32_16x16x32_bf16 v[110:113], v[146:149], v[206:209], v[110:113]
	v_mfma_f32_16x16x32_bf16 v[94:97], v[146:149], v[214:217], v[94:97]
	v_mfma_f32_16x16x32_bf16 v[94:97], v[150:153], v[218:221], v[94:97]
	v_mfma_f32_16x16x32_bf16 v[90:93], v[168:171], v[218:221], v[90:93]
	v_mfma_f32_16x16x32_bf16 v[90:93], v[154:157], v[214:217], v[90:93]
	v_mfma_f32_16x16x32_bf16 v[86:89], v[172:175], v[214:217], v[86:89]
	v_mfma_f32_16x16x32_bf16 v[86:89], v[180:183], v[218:221], v[86:89]
	v_mfma_f32_16x16x32_bf16 v[82:85], v[188:191], v[218:221], v[82:85]
	v_mfma_f32_16x16x32_bf16 v[82:85], v[184:187], v[214:217], v[82:85]
	v_mfma_f32_16x16x32_bf16 v[66:69], v[184:187], v[222:225], v[66:69]
	v_mfma_f32_16x16x32_bf16 v[66:69], v[188:191], v[226:229], v[66:69]
	v_mfma_f32_16x16x32_bf16 v[70:73], v[180:183], v[226:229], v[70:73]
	v_mfma_f32_16x16x32_bf16 v[70:73], v[172:175], v[222:225], v[70:73]
	v_mfma_f32_16x16x32_bf16 v[74:77], v[154:157], v[222:225], v[74:77]
	v_mfma_f32_16x16x32_bf16 v[74:77], v[168:171], v[226:229], v[74:77]
	v_mfma_f32_16x16x32_bf16 v[78:81], v[150:153], v[226:229], v[78:81]
	v_mfma_f32_16x16x32_bf16 v[78:81], v[146:149], v[222:225], v[78:81]
	s_barrier
	s_add_i32 s59, s81, s3
	s_mov_b32 m0, s59
	ds_read_b128 v[198:201], v164 offset:16384
	ds_read_b128 v[202:205], v164 offset:17408
	ds_read_b128 v[206:209], v164 offset:18432
	ds_read_b128 v[210:213], v164 offset:19456
	ds_read_b128 v[214:217], v164 offset:20480
	ds_read_b128 v[218:221], v164 offset:21504
	ds_read_b128 v[222:225], v164 offset:22528
	ds_read_b128 v[226:229], v164 offset:23552
	global_load_lds_dwordx4 v132, s[76:77]
	s_add_i32 m0, s59, 0x2000
	s_add_u32 s62, s76, 0x4000
	s_addc_u32 s63, s77, 0
	s_add_i32 s59, s82, s3
	global_load_lds_dwordx4 v136, s[76:77]
	s_mov_b32 m0, s59
	s_nop 0
	global_load_lds_dwordx4 v132, s[62:63]
	s_add_i32 m0, s59, 0x2000
	s_nop 0
	global_load_lds_dwordx4 v136, s[62:63]
	s_waitcnt vmcnt(6)
	s_waitcnt lgkmcnt(0)
	s_barrier
	s_waitcnt lgkmcnt(0)
	v_mfma_f32_16x16x32_bf16 v[62:65], v[146:149], v[198:201], v[62:65]
	v_mfma_f32_16x16x32_bf16 v[62:65], v[150:153], v[202:205], v[62:65]
	v_mfma_f32_16x16x32_bf16 v[58:61], v[168:171], v[202:205], v[58:61]
	v_mfma_f32_16x16x32_bf16 v[58:61], v[154:157], v[198:201], v[58:61]
	v_mfma_f32_16x16x32_bf16 v[54:57], v[172:175], v[198:201], v[54:57]
	v_mfma_f32_16x16x32_bf16 v[54:57], v[180:183], v[202:205], v[54:57]
	v_mfma_f32_16x16x32_bf16 v[50:53], v[188:191], v[202:205], v[50:53]
	v_mfma_f32_16x16x32_bf16 v[50:53], v[184:187], v[198:201], v[50:53]
	v_mfma_f32_16x16x32_bf16 v[34:37], v[184:187], v[206:209], v[34:37]
	v_mfma_f32_16x16x32_bf16 v[34:37], v[188:191], v[210:213], v[34:37]
	v_mfma_f32_16x16x32_bf16 v[38:41], v[180:183], v[210:213], v[38:41]
	v_mfma_f32_16x16x32_bf16 v[38:41], v[172:175], v[206:209], v[38:41]
	v_mfma_f32_16x16x32_bf16 v[42:45], v[154:157], v[206:209], v[42:45]
	v_mfma_f32_16x16x32_bf16 v[42:45], v[168:171], v[210:213], v[42:45]
	v_mfma_f32_16x16x32_bf16 v[46:49], v[150:153], v[210:213], v[46:49]
	v_mfma_f32_16x16x32_bf16 v[46:49], v[146:149], v[206:209], v[46:49]
	v_mfma_f32_16x16x32_bf16 v[30:33], v[146:149], v[214:217], v[30:33]
	v_mfma_f32_16x16x32_bf16 v[30:33], v[150:153], v[218:221], v[30:33]
	v_mfma_f32_16x16x32_bf16 v[26:29], v[168:171], v[218:221], v[26:29]
	v_mfma_f32_16x16x32_bf16 v[26:29], v[154:157], v[214:217], v[26:29]
	v_mfma_f32_16x16x32_bf16 v[22:25], v[172:175], v[214:217], v[22:25]
	v_mfma_f32_16x16x32_bf16 v[22:25], v[180:183], v[218:221], v[22:25]
	v_mfma_f32_16x16x32_bf16 v[18:21], v[188:191], v[218:221], v[18:21]
	v_mfma_f32_16x16x32_bf16 v[18:21], v[184:187], v[214:217], v[18:21]
	v_mfma_f32_16x16x32_bf16 v[2:5], v[184:187], v[222:225], v[2:5]
	v_mfma_f32_16x16x32_bf16 v[2:5], v[188:191], v[226:229], v[2:5]
	v_mfma_f32_16x16x32_bf16 v[6:9], v[180:183], v[226:229], v[6:9]
	v_mfma_f32_16x16x32_bf16 v[6:9], v[172:175], v[222:225], v[6:9]
	v_mfma_f32_16x16x32_bf16 v[10:13], v[154:157], v[222:225], v[10:13]
	v_mfma_f32_16x16x32_bf16 v[10:13], v[168:171], v[226:229], v[10:13]
	v_mfma_f32_16x16x32_bf16 v[14:17], v[150:153], v[226:229], v[14:17]
	v_mfma_f32_16x16x32_bf16 v[14:17], v[146:149], v[222:225], v[14:17]
	s_barrier
; #define PG8_STAGE(bufoff, gbase, voff) do { _Pragma("unroll") for (int _i = 0; _i < 2; ++_i) \
;         __builtin_amdgcn_global_load_lds((const unsigned*)((const char*)(gbase) + (voff)[_i]), (PG8_LAS unsigned*)(lds + (bufoff) + ldsw + _i * 8192), 16, 0, 0); } while (0)
; #define PG8_LDA(dst, b, h) do { _Pragma("unroll") for (int m = 0; m < 4; ++m) _Pragma("unroll") for (int k = 0; k < 2; ++k) dst[m][k] = *(const PG8_LAS bf16x8*)(lds + PG8_SA(b, h) + aoff + m * 2048 + k * 1024); } while (0)
; #define PG8_LDB(dst, b, h) do { _Pragma("unroll") for (int n = 0; n < 2; ++n) _Pragma("unroll") for (int k = 0; k < 2; ++k) dst[n][k] = *(const PG8_LAS bf16x8*)(lds + PG8_SB(b, h) + boff + n * 2048 + k * 1024); } while (0)
; #define PG8_MMA(ai, bj, At, Bt) do { __builtin_amdgcn_s_setprio(1); _Pragma("unroll") for (int m = 0; m < 4; ++m) _Pragma("unroll") for (int n = 0; n < 2; ++n) _Pragma("unroll") for (int k = 0; k < 2; ++k) \
;         acc[ai][bj][m][n] = __builtin_amdgcn_mfma_f32_16x16x32_bf16(Bt[n][k], At[m][k], acc[ai][bj][m][n], 0, 0, 0); __builtin_amdgcn_s_setprio(0); } while (0)
; #define PG8_WAIT_V(n) asm volatile("s_waitcnt vmcnt(" #n ")" ::: "memory")
; #define PG8_WAIT_L(n) asm volatile("s_waitcnt lgkmcnt(" #n ")" ::: "memory")
; #define PG8_BAR __builtin_amdgcn_s_barrier()
; #define PG8_SCHED __builtin_amdgcn_sched_barrier(0)
; template <class Epi, class Sched, bool ALIGN_EPI = false, bool SP2 = false>
; __device__ __forceinline__ void gemm_phase(PG8_LAS unsigned char* lds, const Gemm g, const Sched& S, const Epi& E) {
;     ...
;             PG8_LDB(B0, 1, 0); PG8_LDB(B1, 1, 1); PG8_SCHED; PG8_LDA(At, 1, 0); PG8_STAGE(PG8_SA(0, 1), a2 + hstep, voffA);
;             PG8_WAIT_V(8); PG8_WAIT_L(0); PG8_BAR; PG8_MMA(0, 0, At, B0); PG8_MMA(0, 1, At, B1); PG8_BAR; PG8_SCHED;
;             PG8_LDA(At, 1, 1); PG8_STAGE(PG8_SB(1, 0), b3, voffB); PG8_STAGE(PG8_SB(1, 1), b3 + hstep, voffB); PG8_STAGE(PG8_SA(1, 0), a3, voffA);
;             PG8_WAIT_V(8); PG8_WAIT_L(0); PG8_BAR; PG8_MMA(1, 0, At, B0); PG8_MMA(1, 1, At, B1); PG8_BAR; PG8_SCHED;
	s_add_i32 s59, 0, 0x18000
	v_add_u32_e32 v158, s59, v160
	s_add_i32 s64, 0, 0x1c000
	ds_read_b128 v[146:149], v158
	ds_read_b128 v[150:153], v158 offset:1024
	ds_read_b128 v[154:157], v158 offset:2048
	ds_read_b128 v[168:171], v158 offset:3072
	v_add_u32_e32 v158, s64, v160
	ds_read_b128 v[172:175], v158
	ds_read_b128 v[180:183], v158 offset:1024
	ds_read_b128 v[184:187], v158 offset:2048
	ds_read_b128 v[188:191], v158 offset:3072
	s_mov_b32 m0, s15
	s_nop 0
	global_load_lds_dwordx4 v130, s[78:79]
	s_mov_b32 m0, s27
	s_nop 0
	global_load_lds_dwordx4 v134, s[78:79]
	s_add_u32 s62, s78, 0x4000
	s_addc_u32 s63, s79, 0
	s_mov_b32 m0, s28
	ds_read_b128 v[198:201], v164 offset:32768
	ds_read_b128 v[202:205], v164 offset:33792
	ds_read_b128 v[206:209], v164 offset:34816
	ds_read_b128 v[210:213], v164 offset:35840
	ds_read_b128 v[214:217], v164 offset:36864
	ds_read_b128 v[218:221], v164 offset:37888
	ds_read_b128 v[222:225], v164 offset:38912
	ds_read_b128 v[226:229], v164 offset:39936
	global_load_lds_dwordx4 v130, s[62:63]
	s_mov_b32 m0, s29
	s_nop 0
	global_load_lds_dwordx4 v134, s[62:63]
	s_waitcnt vmcnt(8)
	s_waitcnt lgkmcnt(0)
	s_barrier
	s_waitcnt lgkmcnt(0)
	v_mfma_f32_16x16x32_bf16 v[126:129], v[146:149], v[198:201], v[126:129]
	v_mfma_f32_16x16x32_bf16 v[126:129], v[150:153], v[202:205], v[126:129]
	v_mfma_f32_16x16x32_bf16 v[122:125], v[168:171], v[202:205], v[122:125]
	v_mfma_f32_16x16x32_bf16 v[122:125], v[154:157], v[198:201], v[122:125]
	v_mfma_f32_16x16x32_bf16 v[118:121], v[172:175], v[198:201], v[118:121]
	v_mfma_f32_16x16x32_bf16 v[118:121], v[180:183], v[202:205], v[118:121]
	v_mfma_f32_16x16x32_bf16 v[114:117], v[188:191], v[202:205], v[114:117]
	v_mfma_f32_16x16x32_bf16 v[114:117], v[184:187], v[198:201], v[114:117]
	v_mfma_f32_16x16x32_bf16 v[98:101], v[184:187], v[206:209], v[98:101]
	v_mfma_f32_16x16x32_bf16 v[98:101], v[188:191], v[210:213], v[98:101]
	v_mfma_f32_16x16x32_bf16 v[102:105], v[180:183], v[210:213], v[102:105]
	v_mfma_f32_16x16x32_bf16 v[102:105], v[172:175], v[206:209], v[102:105]
	v_mfma_f32_16x16x32_bf16 v[106:109], v[154:157], v[206:209], v[106:109]
	v_mfma_f32_16x16x32_bf16 v[106:109], v[168:171], v[210:213], v[106:109]
	v_mfma_f32_16x16x32_bf16 v[110:113], v[150:153], v[210:213], v[110:113]
	v_mfma_f32_16x16x32_bf16 v[110:113], v[146:149], v[206:209], v[110:113]
	v_mfma_f32_16x16x32_bf16 v[94:97], v[146:149], v[214:217], v[94:97]
	v_mfma_f32_16x16x32_bf16 v[94:97], v[150:153], v[218:221], v[94:97]
	v_mfma_f32_16x16x32_bf16 v[90:93], v[168:171], v[218:221], v[90:93]
	v_mfma_f32_16x16x32_bf16 v[90:93], v[154:157], v[214:217], v[90:93]
	v_mfma_f32_16x16x32_bf16 v[86:89], v[172:175], v[214:217], v[86:89]
	v_mfma_f32_16x16x32_bf16 v[86:89], v[180:183], v[218:221], v[86:89]
	v_mfma_f32_16x16x32_bf16 v[82:85], v[188:191], v[218:221], v[82:85]
	v_mfma_f32_16x16x32_bf16 v[82:85], v[184:187], v[214:217], v[82:85]
	v_mfma_f32_16x16x32_bf16 v[66:69], v[184:187], v[222:225], v[66:69]
	v_mfma_f32_16x16x32_bf16 v[66:69], v[188:191], v[226:229], v[66:69]
	v_mfma_f32_16x16x32_bf16 v[70:73], v[180:183], v[226:229], v[70:73]
	v_mfma_f32_16x16x32_bf16 v[70:73], v[172:175], v[222:225], v[70:73]
	v_mfma_f32_16x16x32_bf16 v[74:77], v[154:157], v[222:225], v[74:77]
	v_mfma_f32_16x16x32_bf16 v[74:77], v[168:171], v[226:229], v[74:77]
	v_mfma_f32_16x16x32_bf16 v[78:81], v[150:153], v[226:229], v[78:81]
	v_mfma_f32_16x16x32_bf16 v[78:81], v[146:149], v[222:225], v[78:81]
	s_barrier
	s_add_u32 s62, s76, 0x8000
	s_addc_u32 s63, s77, 0
	s_add_i32 s59, s59, s3
	s_mov_b32 m0, s59
	ds_read_b128 v[198:201], v164 offset:49152
	ds_read_b128 v[202:205], v164 offset:50176
	ds_read_b128 v[206:209], v164 offset:51200
	ds_read_b128 v[210:213], v164 offset:52224
	ds_read_b128 v[214:217], v164 offset:53248
	ds_read_b128 v[218:221], v164 offset:54272
	ds_read_b128 v[222:225], v164 offset:55296
	ds_read_b128 v[226:229], v164 offset:56320
	global_load_lds_dwordx4 v132, s[62:63]
	s_add_i32 m0, s59, 0x2000
	v_lshl_add_u64 v[158:159], s[62:63], 0, v[136:137]
	s_add_u32 s62, s76, 0xc000
	s_addc_u32 s63, s77, 0
	s_add_i32 s59, s64, s3
	global_load_lds_dwordx4 v[158:159], off
	s_mov_b32 m0, s59
	s_nop 0
	global_load_lds_dwordx4 v132, s[62:63]
	s_add_i32 m0, s59, 0x2000
	s_nop 0
	global_load_lds_dwordx4 v136, s[62:63]
	s_waitcnt vmcnt(6)
	s_waitcnt lgkmcnt(0)
	s_barrier
	s_waitcnt lgkmcnt(0)
	v_mfma_f32_16x16x32_bf16 v[62:65], v[146:149], v[198:201], v[62:65]
	v_mfma_f32_16x16x32_bf16 v[62:65], v[150:153], v[202:205], v[62:65]
	v_mfma_f32_16x16x32_bf16 v[58:61], v[168:171], v[202:205], v[58:61]
	v_mfma_f32_16x16x32_bf16 v[58:61], v[154:157], v[198:201], v[58:61]
	v_mfma_f32_16x16x32_bf16 v[54:57], v[172:175], v[198:201], v[54:57]
	v_mfma_f32_16x16x32_bf16 v[54:57], v[180:183], v[202:205], v[54:57]
	v_mfma_f32_16x16x32_bf16 v[50:53], v[188:191], v[202:205], v[50:53]
	v_mfma_f32_16x16x32_bf16 v[50:53], v[184:187], v[198:201], v[50:53]
	v_mfma_f32_16x16x32_bf16 v[34:37], v[184:187], v[206:209], v[34:37]
	v_mfma_f32_16x16x32_bf16 v[34:37], v[188:191], v[210:213], v[34:37]
	v_mfma_f32_16x16x32_bf16 v[38:41], v[180:183], v[210:213], v[38:41]
	v_mfma_f32_16x16x32_bf16 v[38:41], v[172:175], v[206:209], v[38:41]
	v_mfma_f32_16x16x32_bf16 v[42:45], v[154:157], v[206:209], v[42:45]
	v_mfma_f32_16x16x32_bf16 v[42:45], v[168:171], v[210:213], v[42:45]
	v_mfma_f32_16x16x32_bf16 v[46:49], v[150:153], v[210:213], v[46:49]
	v_mfma_f32_16x16x32_bf16 v[46:49], v[146:149], v[206:209], v[46:49]
	v_mfma_f32_16x16x32_bf16 v[30:33], v[146:149], v[214:217], v[30:33]
	v_mfma_f32_16x16x32_bf16 v[30:33], v[150:153], v[218:221], v[30:33]
	v_mfma_f32_16x16x32_bf16 v[26:29], v[168:171], v[218:221], v[26:29]
	v_mfma_f32_16x16x32_bf16 v[26:29], v[154:157], v[214:217], v[26:29]
	v_mfma_f32_16x16x32_bf16 v[22:25], v[172:175], v[214:217], v[22:25]
	v_mfma_f32_16x16x32_bf16 v[22:25], v[180:183], v[218:221], v[22:25]
	v_mfma_f32_16x16x32_bf16 v[18:21], v[188:191], v[218:221], v[18:21]
	v_mfma_f32_16x16x32_bf16 v[18:21], v[184:187], v[214:217], v[18:21]
	v_mfma_f32_16x16x32_bf16 v[2:5], v[184:187], v[222:225], v[2:5]
	v_mfma_f32_16x16x32_bf16 v[2:5], v[188:191], v[226:229], v[2:5]
	v_mfma_f32_16x16x32_bf16 v[6:9], v[180:183], v[226:229], v[6:9]
	v_mfma_f32_16x16x32_bf16 v[6:9], v[172:175], v[222:225], v[6:9]
	v_mfma_f32_16x16x32_bf16 v[10:13], v[154:157], v[222:225], v[10:13]
	v_mfma_f32_16x16x32_bf16 v[10:13], v[168:171], v[226:229], v[10:13]
	v_mfma_f32_16x16x32_bf16 v[14:17], v[150:153], v[226:229], v[14:17]
	v_mfma_f32_16x16x32_bf16 v[14:17], v[146:149], v[222:225], v[14:17]
	s_barrier
	s_add_i32 s58, s58, 2
	s_add_u32 s72, s72, 0x10000
	s_addc_u32 s73, s73, 0
	s_add_u32 s33, s33, 0x10000
	s_addc_u32 s56, s56, 0
	s_cmp_gt_u32 s58, 61
	s_cbranch_scc0 .LBB0_290
	s_and_b64 vcc, exec, s[12:13]
	s_cbranch_vccz .LBB0_293
	s_barrier

; #define PG8_STAGE(bufoff, gbase, voff) do { _Pragma("unroll") for (int _i = 0; _i < 2; ++_i) \
;         __builtin_amdgcn_global_load_lds((const unsigned*)((const char*)(gbase) + (voff)[_i]), (PG8_LAS unsigned*)(lds + (bufoff) + ldsw + _i * 8192), 16, 0, 0); } while (0)
; #define PG8_LDA(dst, b, h) do { _Pragma("unroll") for (int m = 0; m < 4; ++m) _Pragma("unroll") for (int k = 0; k < 2; ++k) dst[m][k] = *(const PG8_LAS bf16x8*)(lds + PG8_SA(b, h) + aoff + m * 2048 + k * 1024); } while (0)
; #define PG8_LDB(dst, b, h) do { _Pragma("unroll") for (int n = 0; n < 2; ++n) _Pragma("unroll") for (int k = 0; k < 2; ++k) dst[n][k] = *(const PG8_LAS bf16x8*)(lds + PG8_SB(b, h) + boff + n * 2048 + k * 1024); } while (0)
; #define PG8_MMA(ai, bj, At, Bt) do { __builtin_amdgcn_s_setprio(1); _Pragma("unroll") for (int m = 0; m < 4; ++m) _Pragma("unroll") for (int n = 0; n < 2; ++n) _Pragma("unroll") for (int k = 0; k < 2; ++k) \
;         acc[ai][bj][m][n] = __builtin_amdgcn_mfma_f32_16x16x32_bf16(Bt[n][k], At[m][k], acc[ai][bj][m][n], 0, 0, 0); __builtin_amdgcn_s_setprio(0); } while (0)
; #define PG8_WAIT_V(n) asm volatile("s_waitcnt vmcnt(" #n ")" ::: "memory")
; #define PG8_WAIT_L(n) asm volatile("s_waitcnt lgkmcnt(" #n ")" ::: "memory")
; #define PG8_BAR __builtin_amdgcn_s_barrier()
; #define PG8_SCHED __builtin_amdgcn_sched_barrier(0)
; template <class Epi, class Sched, bool ALIGN_EPI = false, bool SP2 = false>
; __device__ __forceinline__ void gemm_phase(PG8_LAS unsigned char* lds, const Gemm g, const Sched& S, const Epi& E) {
;     ...
;             PG8_LDB(B0, 0, 0); PG8_LDB(B1, 0, 1); PG8_SCHED; PG8_LDA(At, 0, 0); PG8_STAGE(PG8_SA(1, 1), a1 + hstep, voffA);
;             PG8_WAIT_V(8); PG8_WAIT_L(0); PG8_BAR; PG8_MMA(0, 0, At, B0); PG8_MMA(0, 1, At, B1); PG8_BAR; PG8_SCHED;
;             PG8_LDA(At, 0, 1); PG8_STAGE(PG8_SB(0, 0), b2, voffB); PG8_STAGE(PG8_SB(0, 1), b2 + hstep, voffB); PG8_STAGE(PG8_SA(0, 0), a2, voffA);
.LBB0_682:
	ds_read_b128 v[166:169], v163
	ds_read_b128 v[170:173], v163 offset:1024
	ds_read_b128 v[174:177], v163 offset:2048
	ds_read_b128 v[180:183], v163 offset:3072
	ds_read_b128 v[184:187], v164
	ds_read_b128 v[188:191], v164 offset:1024
	ds_read_b128 v[198:201], v164 offset:2048
	ds_read_b128 v[202:205], v164 offset:3072
	v_lshl_add_u64 v[242:243], v[130:131], 0, s[44:45]
	s_add_i32 s83, s29, 0xc000
	v_lshl_add_u64 v[238:239], v[242:243], 0, s[10:11]
	s_mov_b32 m0, s83
	v_lshl_add_u64 v[244:245], v[132:133], 0, s[44:45]
	s_add_i32 s84, s29, 0xe000
	ds_read_b128 v[206:209], v165
	ds_read_b128 v[210:213], v165 offset:1024
	ds_read_b128 v[214:217], v165 offset:2048
	ds_read_b128 v[218:221], v165 offset:3072
	ds_read_b128 v[222:225], v165 offset:4096
	ds_read_b128 v[226:229], v165 offset:5120
	ds_read_b128 v[230:233], v165 offset:6144
	ds_read_b128 v[234:237], v165 offset:7168
	global_load_lds_dwordx4 v[238:239], off
	v_lshl_add_u64 v[238:239], v[244:245], 0, s[10:11]
	s_mov_b32 m0, s84
	s_nop 0
	global_load_lds_dwordx4 v[238:239], off
	s_waitcnt vmcnt(8)
	s_waitcnt lgkmcnt(0)
	s_barrier
	s_waitcnt lgkmcnt(0)
	v_mfma_f32_16x16x32_bf16 v[14:17], v[166:169], v[206:209], v[14:17]
	v_mfma_f32_16x16x32_bf16 v[14:17], v[170:173], v[210:213], v[14:17]
	v_mfma_f32_16x16x32_bf16 v[10:13], v[180:183], v[210:213], v[10:13]
	v_mfma_f32_16x16x32_bf16 v[10:13], v[174:177], v[206:209], v[10:13]
	v_mfma_f32_16x16x32_bf16 v[30:33], v[184:187], v[206:209], v[30:33]
	v_mfma_f32_16x16x32_bf16 v[30:33], v[188:191], v[210:213], v[30:33]
	v_mfma_f32_16x16x32_bf16 v[26:29], v[202:205], v[210:213], v[26:29]
	v_mfma_f32_16x16x32_bf16 v[26:29], v[198:201], v[206:209], v[26:29]
	v_mfma_f32_16x16x32_bf16 v[50:53], v[198:201], v[214:217], v[50:53]
	v_mfma_f32_16x16x32_bf16 v[50:53], v[202:205], v[218:221], v[50:53]
	v_mfma_f32_16x16x32_bf16 v[54:57], v[188:191], v[218:221], v[54:57]
	v_mfma_f32_16x16x32_bf16 v[54:57], v[184:187], v[214:217], v[54:57]
	v_mfma_f32_16x16x32_bf16 v[34:37], v[174:177], v[214:217], v[34:37]
	v_mfma_f32_16x16x32_bf16 v[34:37], v[180:183], v[218:221], v[34:37]
	v_mfma_f32_16x16x32_bf16 v[38:41], v[170:173], v[218:221], v[38:41]
	v_mfma_f32_16x16x32_bf16 v[38:41], v[166:169], v[214:217], v[38:41]
	v_mfma_f32_16x16x32_bf16 v[70:73], v[166:169], v[222:225], v[70:73]
	v_mfma_f32_16x16x32_bf16 v[70:73], v[170:173], v[226:229], v[70:73]
	v_mfma_f32_16x16x32_bf16 v[66:69], v[180:183], v[226:229], v[66:69]
	v_mfma_f32_16x16x32_bf16 v[66:69], v[174:177], v[222:225], v[66:69]
	v_mfma_f32_16x16x32_bf16 v[86:89], v[184:187], v[222:225], v[86:89]
	v_mfma_f32_16x16x32_bf16 v[86:89], v[188:191], v[226:229], v[86:89]
	v_mfma_f32_16x16x32_bf16 v[82:85], v[202:205], v[226:229], v[82:85]
	v_mfma_f32_16x16x32_bf16 v[82:85], v[198:201], v[222:225], v[82:85]
	v_mfma_f32_16x16x32_bf16 v[106:109], v[198:201], v[230:233], v[106:109]
	v_mfma_f32_16x16x32_bf16 v[106:109], v[202:205], v[234:237], v[106:109]
	v_mfma_f32_16x16x32_bf16 v[110:113], v[188:191], v[234:237], v[110:113]
	v_mfma_f32_16x16x32_bf16 v[110:113], v[184:187], v[230:233], v[110:113]
	v_mfma_f32_16x16x32_bf16 v[90:93], v[174:177], v[230:233], v[90:93]
	v_mfma_f32_16x16x32_bf16 v[90:93], v[180:183], v[234:237], v[90:93]
	v_mfma_f32_16x16x32_bf16 v[94:97], v[170:173], v[234:237], v[94:97]
	v_mfma_f32_16x16x32_bf16 v[94:97], v[166:169], v[230:233], v[94:97]
	s_barrier
	v_lshl_add_u64 v[246:247], v[156:157], 0, s[44:45]
	s_add_i32 s85, s80, s28
	v_lshl_add_u64 v[238:239], v[246:247], 0, s[14:15]
	s_mov_b32 m0, s85
	v_lshl_add_u64 v[248:249], v[158:159], 0, s[44:45]
	s_add_i32 s86, s85, 0x2000
	ds_read_b128 v[206:209], v165 offset:16384
	ds_read_b128 v[210:213], v165 offset:17408
	ds_read_b128 v[214:217], v165 offset:18432
	ds_read_b128 v[218:221], v165 offset:19456
	ds_read_b128 v[222:225], v165 offset:20480
	ds_read_b128 v[226:229], v165 offset:21504
	ds_read_b128 v[230:233], v165 offset:22528
	ds_read_b128 v[234:237], v165 offset:23552
	global_load_lds_dwordx4 v[238:239], off
	v_lshl_add_u64 v[238:239], v[248:249], 0, s[14:15]
	s_mov_b32 m0, s86
	s_add_i32 s87, s81, s28
	global_load_lds_dwordx4 v[238:239], off
	v_lshl_add_u64 v[238:239], v[246:247], 0, s[16:17]
	s_mov_b32 m0, s87
	s_add_i32 s88, s87, 0x2000
	global_load_lds_dwordx4 v[238:239], off
	v_lshl_add_u64 v[238:239], v[248:249], 0, s[16:17]
	s_mov_b32 m0, s88
	s_nop 0
	global_load_lds_dwordx4 v[238:239], off
	v_lshl_add_u64 v[238:239], v[242:243], 0, s[14:15]
	s_mov_b32 m0, s29
	s_nop 0
	global_load_lds_dwordx4 v[238:239], off
	v_lshl_add_u64 v[238:239], v[244:245], 0, s[14:15]
	s_mov_b32 m0, s30
	s_nop 0
	global_load_lds_dwordx4 v[238:239], off
	s_waitcnt vmcnt(8)
	s_waitcnt lgkmcnt(0)
	s_barrier
; #define PG8_STAGE(bufoff, gbase, voff) do { _Pragma("unroll") for (int _i = 0; _i < 2; ++_i) \
;         __builtin_amdgcn_global_load_lds((const unsigned*)((const char*)(gbase) + (voff)[_i]), (PG8_LAS unsigned*)(lds + (bufoff) + ldsw + _i * 8192), 16, 0, 0); } while (0)
; #define PG8_LDA(dst, b, h) do { _Pragma("unroll") for (int m = 0; m < 4; ++m) _Pragma("unroll") for (int k = 0; k < 2; ++k) dst[m][k] = *(const PG8_LAS bf16x8*)(lds + PG8_SA(b, h) + aoff + m * 2048 + k * 1024); } while (0)
; #define PG8_LDB(dst, b, h) do { _Pragma("unroll") for (int n = 0; n < 2; ++n) _Pragma("unroll") for (int k = 0; k < 2; ++k) dst[n][k] = *(const PG8_LAS bf16x8*)(lds + PG8_SB(b, h) + boff + n * 2048 + k * 1024); } while (0)
; #define PG8_MMA(ai, bj, At, Bt) do { __builtin_amdgcn_s_setprio(1); _Pragma("unroll") for (int m = 0; m < 4; ++m) _Pragma("unroll") for (int n = 0; n < 2; ++n) _Pragma("unroll") for (int k = 0; k < 2; ++k) \
;         acc[ai][bj][m][n] = __builtin_amdgcn_mfma_f32_16x16x32_bf16(Bt[n][k], At[m][k], acc[ai][bj][m][n], 0, 0, 0); __builtin_amdgcn_s_setprio(0); } while (0)
; #define PG8_WAIT_V(n) asm volatile("s_waitcnt vmcnt(" #n ")" ::: "memory")
; #define PG8_WAIT_L(n) asm volatile("s_waitcnt lgkmcnt(" #n ")" ::: "memory")
; #define PG8_BAR __builtin_amdgcn_s_barrier()
; #define PG8_SCHED __builtin_amdgcn_sched_barrier(0)
; template <class Epi, class Sched, bool ALIGN_EPI = false, bool SP2 = false>
; __device__ __forceinline__ void gemm_phase(PG8_LAS unsigned char* lds, const Gemm g, const Sched& S, const Epi& E) {
;     ...
;             PG8_WAIT_V(8); PG8_WAIT_L(0); PG8_BAR; PG8_MMA(1, 0, At, B0); PG8_MMA(1, 1, At, B1); PG8_BAR; PG8_SCHED;
;             PG8_LDB(B0, 1, 0); PG8_LDB(B1, 1, 1); PG8_SCHED; PG8_LDA(At, 1, 0); PG8_STAGE(PG8_SA(0, 1), a2 + hstep, voffA);
;             PG8_WAIT_V(8); PG8_WAIT_L(0); PG8_BAR; PG8_MMA(0, 0, At, B0); PG8_MMA(0, 1, At, B1); PG8_BAR; PG8_SCHED;
	s_waitcnt lgkmcnt(0)
	v_mfma_f32_16x16x32_bf16 v[126:129], v[166:169], v[206:209], v[126:129]
	v_mfma_f32_16x16x32_bf16 v[126:129], v[170:173], v[210:213], v[126:129]
	v_mfma_f32_16x16x32_bf16 v[122:125], v[180:183], v[210:213], v[122:125]
	v_mfma_f32_16x16x32_bf16 v[122:125], v[174:177], v[206:209], v[122:125]
	v_mfma_f32_16x16x32_bf16 v[118:121], v[184:187], v[206:209], v[118:121]
	v_mfma_f32_16x16x32_bf16 v[118:121], v[188:191], v[210:213], v[118:121]
	v_mfma_f32_16x16x32_bf16 v[114:117], v[202:205], v[210:213], v[114:117]
	v_mfma_f32_16x16x32_bf16 v[114:117], v[198:201], v[206:209], v[114:117]
	v_mfma_f32_16x16x32_bf16 v[74:77], v[198:201], v[214:217], v[74:77]
	v_mfma_f32_16x16x32_bf16 v[74:77], v[202:205], v[218:221], v[74:77]
	v_mfma_f32_16x16x32_bf16 v[78:81], v[188:191], v[218:221], v[78:81]
	v_mfma_f32_16x16x32_bf16 v[78:81], v[184:187], v[214:217], v[78:81]
	v_mfma_f32_16x16x32_bf16 v[98:101], v[174:177], v[214:217], v[98:101]
	v_mfma_f32_16x16x32_bf16 v[98:101], v[180:183], v[218:221], v[98:101]
	v_mfma_f32_16x16x32_bf16 v[102:105], v[170:173], v[218:221], v[102:105]
	v_mfma_f32_16x16x32_bf16 v[102:105], v[166:169], v[214:217], v[102:105]
	v_mfma_f32_16x16x32_bf16 v[62:65], v[166:169], v[222:225], v[62:65]
	v_mfma_f32_16x16x32_bf16 v[62:65], v[170:173], v[226:229], v[62:65]
	v_mfma_f32_16x16x32_bf16 v[58:61], v[180:183], v[226:229], v[58:61]
	v_mfma_f32_16x16x32_bf16 v[58:61], v[174:177], v[222:225], v[58:61]
	v_mfma_f32_16x16x32_bf16 v[46:49], v[184:187], v[222:225], v[46:49]
	v_mfma_f32_16x16x32_bf16 v[46:49], v[188:191], v[226:229], v[46:49]
	v_mfma_f32_16x16x32_bf16 v[42:45], v[202:205], v[226:229], v[42:45]
	v_mfma_f32_16x16x32_bf16 v[42:45], v[198:201], v[222:225], v[42:45]
	v_mfma_f32_16x16x32_bf16 v[2:5], v[198:201], v[230:233], v[2:5]
	v_mfma_f32_16x16x32_bf16 v[2:5], v[202:205], v[234:237], v[2:5]
	v_mfma_f32_16x16x32_bf16 v[6:9], v[188:191], v[234:237], v[6:9]
	v_mfma_f32_16x16x32_bf16 v[6:9], v[184:187], v[230:233], v[6:9]
	v_mfma_f32_16x16x32_bf16 v[18:21], v[174:177], v[230:233], v[18:21]
	v_mfma_f32_16x16x32_bf16 v[18:21], v[180:183], v[234:237], v[18:21]
	v_mfma_f32_16x16x32_bf16 v[22:25], v[170:173], v[234:237], v[22:25]
	v_mfma_f32_16x16x32_bf16 v[22:25], v[166:169], v[230:233], v[22:25]
	s_barrier
	s_add_i32 s89, 0, 0x18000
	s_add_i32 s91, 0, 0x1c000
	v_add_u32_e32 v142, s89, v161
	v_add_u32_e32 v167, s91, v161
	ds_read_b128 v[168:171], v142
	ds_read_b128 v[172:175], v142 offset:1024
	ds_read_b128 v[180:183], v142 offset:2048
	ds_read_b128 v[184:187], v142 offset:3072
	ds_read_b128 v[188:191], v167
	ds_read_b128 v[198:201], v167 offset:1024
	ds_read_b128 v[202:205], v167 offset:2048
	ds_read_b128 v[206:209], v167 offset:3072
	s_mov_b32 m0, s31
	v_lshl_add_u64 v[176:177], v[242:243], 0, s[16:17]
	ds_read_b128 v[210:213], v165 offset:32768
	ds_read_b128 v[214:217], v165 offset:33792
	ds_read_b128 v[218:221], v165 offset:34816
	ds_read_b128 v[222:225], v165 offset:35840
	ds_read_b128 v[226:229], v165 offset:36864
	ds_read_b128 v[230:233], v165 offset:37888
	ds_read_b128 v[234:237], v165 offset:38912
	ds_read_b128 v[238:241], v165 offset:39936
	global_load_lds_dwordx4 v[176:177], off
	v_lshl_add_u64 v[176:177], v[244:245], 0, s[16:17]
	s_mov_b32 m0, s35
	s_nop 0
	global_load_lds_dwordx4 v[176:177], off
	s_waitcnt vmcnt(8)
	s_waitcnt lgkmcnt(0)
	s_barrier
	s_waitcnt lgkmcnt(0)
	v_mfma_f32_16x16x32_bf16 v[14:17], v[168:171], v[210:213], v[14:17]
	v_mfma_f32_16x16x32_bf16 v[14:17], v[172:175], v[214:217], v[14:17]
	v_mfma_f32_16x16x32_bf16 v[10:13], v[184:187], v[214:217], v[10:13]
	v_mfma_f32_16x16x32_bf16 v[10:13], v[180:183], v[210:213], v[10:13]
	v_mfma_f32_16x16x32_bf16 v[30:33], v[188:191], v[210:213], v[30:33]
	v_mfma_f32_16x16x32_bf16 v[30:33], v[198:201], v[214:217], v[30:33]
	v_mfma_f32_16x16x32_bf16 v[26:29], v[206:209], v[214:217], v[26:29]
	v_mfma_f32_16x16x32_bf16 v[26:29], v[202:205], v[210:213], v[26:29]
	v_mfma_f32_16x16x32_bf16 v[50:53], v[202:205], v[218:221], v[50:53]
	v_mfma_f32_16x16x32_bf16 v[50:53], v[206:209], v[222:225], v[50:53]
	v_mfma_f32_16x16x32_bf16 v[54:57], v[198:201], v[222:225], v[54:57]
	v_mfma_f32_16x16x32_bf16 v[54:57], v[188:191], v[218:221], v[54:57]
	v_mfma_f32_16x16x32_bf16 v[34:37], v[180:183], v[218:221], v[34:37]
	v_mfma_f32_16x16x32_bf16 v[34:37], v[184:187], v[222:225], v[34:37]
	v_mfma_f32_16x16x32_bf16 v[38:41], v[172:175], v[222:225], v[38:41]
	v_mfma_f32_16x16x32_bf16 v[38:41], v[168:171], v[218:221], v[38:41]
	v_mfma_f32_16x16x32_bf16 v[70:73], v[168:171], v[226:229], v[70:73]
	v_mfma_f32_16x16x32_bf16 v[70:73], v[172:175], v[230:233], v[70:73]
	v_mfma_f32_16x16x32_bf16 v[66:69], v[184:187], v[230:233], v[66:69]
	v_mfma_f32_16x16x32_bf16 v[66:69], v[180:183], v[226:229], v[66:69]
	v_mfma_f32_16x16x32_bf16 v[86:89], v[188:191], v[226:229], v[86:89]
	v_mfma_f32_16x16x32_bf16 v[86:89], v[198:201], v[230:233], v[86:89]
	v_mfma_f32_16x16x32_bf16 v[82:85], v[206:209], v[230:233], v[82:85]
	v_mfma_f32_16x16x32_bf16 v[82:85], v[202:205], v[226:229], v[82:85]
	v_mfma_f32_16x16x32_bf16 v[106:109], v[202:205], v[234:237], v[106:109]
	v_mfma_f32_16x16x32_bf16 v[106:109], v[206:209], v[238:241], v[106:109]
	v_mfma_f32_16x16x32_bf16 v[110:113], v[198:201], v[238:241], v[110:113]
	v_mfma_f32_16x16x32_bf16 v[110:113], v[188:191], v[234:237], v[110:113]
	v_mfma_f32_16x16x32_bf16 v[90:93], v[180:183], v[234:237], v[90:93]
	v_mfma_f32_16x16x32_bf16 v[90:93], v[184:187], v[238:241], v[90:93]
	v_mfma_f32_16x16x32_bf16 v[94:97], v[172:175], v[238:241], v[94:97]
	v_mfma_f32_16x16x32_bf16 v[94:97], v[168:171], v[234:237], v[94:97]
	s_barrier
; __device__ __forceinline__ float bflo(unsigned w) { return __uint_as_float(w << 16); }
; __device__ __forceinline__ float bfhi(unsigned w) { return __uint_as_float(w & 0xffff0000u); }
; #define PG8_STAGE(bufoff, gbase, voff) do { _Pragma("unroll") for (int _i = 0; _i < 2; ++_i) \
;         __builtin_amdgcn_global_load_lds((const unsigned*)((const char*)(gbase) + (voff)[_i]), (PG8_LAS unsigned*)(lds + (bufoff) + ldsw + _i * 8192), 16, 0, 0); } while (0)
; #define PG8_LDA(dst, b, h) do { _Pragma("unroll") for (int m = 0; m < 4; ++m) _Pragma("unroll") for (int k = 0; k < 2; ++k) dst[m][k] = *(const PG8_LAS bf16x8*)(lds + PG8_SA(b, h) + aoff + m * 2048 + k * 1024); } while (0)
; #define PG8_BAR __builtin_amdgcn_s_barrier()
;     __device__ __forceinline__ void mid(f32x4 (&acc)[2][2][4][2], const Unit& u, int wr, int wc, int fr, int fq) const {
;         int row0 = u.pm * BM + wr * 64 + fr; const int col0 = u.pn * BM + wc * 32 + 8 * fq;
;         asm volatile("" : "+v"(row0));
; #pragma unroll
;         for (int ai = 0; ai < 2; ++ai)
; #pragma unroll
;             for (int m = 0; m < 4; ++m) { const bf16_t* pr = P + (size_t)(row0 + ai * HALF + m * 16) * NP + col0;
; #pragma unroll
;                 for (int bj = 0; bj < 2; ++bj) { const u32x4 a = *(const u32x4*)(pr + PC_GA + bj * HALF), b = *(const u32x4*)(pr + PC_GB + bj * HALF);
;                     const f32x4 b0 = {bflo(b.x), bfhi(b.x), bflo(b.y), bfhi(b.y)}, b1 = {bflo(b.z), bfhi(b.z), bflo(b.w), bfhi(b.w)};
;                     const f32x4 a0 = {bflo(a.x), bfhi(a.x), bflo(a.y), bfhi(a.y)}, a1 = {bflo(a.z), bfhi(a.z), bflo(a.w), bfhi(a.w)};
;                     f32x4 r0, r1;
; #pragma unroll
;                     for (int j = 0; j < 4; ++j) { r0[j] = a0[j] * __builtin_amdgcn_rcpf(fmaxf(b0[j], 1e-30f)); r1[j] = a1[j] * __builtin_amdgcn_rcpf(fmaxf(b1[j], 1e-30f)); }
;                     acc[ai][bj][m][0] *= r0; acc[ai][bj][m][1] *= r1; }
; template <class Epi, class Sched, bool ALIGN_EPI = false, bool SP2 = false>
; __device__ __forceinline__ void gemm_phase(PG8_LAS unsigned char* lds, const Gemm g, const Sched& S, const Epi& E) {
;     ...
;             PG8_LDA(At, 1, 1); PG8_STAGE(PG8_SB(1, 0), b3, voffB); PG8_STAGE(PG8_SB(1, 1), b3 + hstep, voffB); PG8_STAGE(PG8_SA(1, 0), a3, voffA);
;             PG8_WAIT_V(8); PG8_WAIT_L(0); PG8_BAR; PG8_MMA(1, 0, At, B0); PG8_MMA(1, 1, At, B1); PG8_BAR; PG8_SCHED;
	s_add_i32 s89, s89, s28
	v_lshl_add_u64 v[176:177], v[246:247], 0, s[22:23]
	s_mov_b32 m0, s89
	s_add_i32 s90, s89, 0x2000
	ds_read_b128 v[210:213], v165 offset:49152
	ds_read_b128 v[214:217], v165 offset:50176
	ds_read_b128 v[218:221], v165 offset:51200
	ds_read_b128 v[222:225], v165 offset:52224
	ds_read_b128 v[226:229], v165 offset:53248
	ds_read_b128 v[230:233], v165 offset:54272
	ds_read_b128 v[234:237], v165 offset:55296
	ds_read_b128 v[238:241], v165 offset:56320
	global_load_lds_dwordx4 v[176:177], off
	v_lshl_add_u64 v[176:177], v[248:249], 0, s[22:23]
	s_mov_b32 m0, s90
	s_add_i32 s91, s91, s28
	global_load_lds_dwordx4 v[176:177], off
	v_lshl_add_u64 v[176:177], v[246:247], 0, s[36:37]
	s_mov_b32 m0, s91
	s_add_i32 s92, s91, 0x2000
	global_load_lds_dwordx4 v[176:177], off
	v_lshl_add_u64 v[176:177], v[248:249], 0, s[36:37]
	s_mov_b32 m0, s92
	s_nop 0
	global_load_lds_dwordx4 v[176:177], off
	v_lshl_add_u64 v[176:177], v[242:243], 0, s[22:23]
	s_mov_b32 m0, s75
	s_nop 0
	global_load_lds_dwordx4 v[176:177], off
	v_lshl_add_u64 v[176:177], v[244:245], 0, s[22:23]
	s_mov_b32 m0, s76
	s_nop 0
	global_load_lds_dwordx4 v[176:177], off
	s_waitcnt vmcnt(8)
	s_waitcnt lgkmcnt(0)
	s_barrier
	s_waitcnt lgkmcnt(0)
	v_mfma_f32_16x16x32_bf16 v[126:129], v[168:171], v[210:213], v[126:129]
	v_mfma_f32_16x16x32_bf16 v[126:129], v[172:175], v[214:217], v[126:129]
	v_mfma_f32_16x16x32_bf16 v[122:125], v[184:187], v[214:217], v[122:125]
	v_mfma_f32_16x16x32_bf16 v[122:125], v[180:183], v[210:213], v[122:125]
	v_mfma_f32_16x16x32_bf16 v[118:121], v[188:191], v[210:213], v[118:121]
	v_mfma_f32_16x16x32_bf16 v[118:121], v[198:201], v[214:217], v[118:121]
	v_mfma_f32_16x16x32_bf16 v[114:117], v[206:209], v[214:217], v[114:117]
	v_mfma_f32_16x16x32_bf16 v[114:117], v[202:205], v[210:213], v[114:117]
	v_mfma_f32_16x16x32_bf16 v[74:77], v[202:205], v[218:221], v[74:77]
	v_mfma_f32_16x16x32_bf16 v[74:77], v[206:209], v[222:225], v[74:77]
	v_mfma_f32_16x16x32_bf16 v[78:81], v[198:201], v[222:225], v[78:81]
	v_mfma_f32_16x16x32_bf16 v[78:81], v[188:191], v[218:221], v[78:81]
	v_mfma_f32_16x16x32_bf16 v[98:101], v[180:183], v[218:221], v[98:101]
	v_mfma_f32_16x16x32_bf16 v[98:101], v[184:187], v[222:225], v[98:101]
	v_mfma_f32_16x16x32_bf16 v[102:105], v[172:175], v[222:225], v[102:105]
	v_mfma_f32_16x16x32_bf16 v[102:105], v[168:171], v[218:221], v[102:105]
	v_mfma_f32_16x16x32_bf16 v[62:65], v[168:171], v[226:229], v[62:65]
	v_mfma_f32_16x16x32_bf16 v[62:65], v[172:175], v[230:233], v[62:65]
	v_mfma_f32_16x16x32_bf16 v[58:61], v[184:187], v[230:233], v[58:61]
	v_mfma_f32_16x16x32_bf16 v[58:61], v[180:183], v[226:229], v[58:61]
	v_mfma_f32_16x16x32_bf16 v[46:49], v[188:191], v[226:229], v[46:49]
	v_mfma_f32_16x16x32_bf16 v[46:49], v[198:201], v[230:233], v[46:49]
	v_mfma_f32_16x16x32_bf16 v[42:45], v[206:209], v[230:233], v[42:45]
	v_mfma_f32_16x16x32_bf16 v[42:45], v[202:205], v[226:229], v[42:45]
	v_mfma_f32_16x16x32_bf16 v[2:5], v[202:205], v[234:237], v[2:5]
	v_mfma_f32_16x16x32_bf16 v[2:5], v[206:209], v[238:241], v[2:5]
	v_mfma_f32_16x16x32_bf16 v[6:9], v[198:201], v[238:241], v[6:9]
	v_mfma_f32_16x16x32_bf16 v[6:9], v[188:191], v[234:237], v[6:9]
	v_mfma_f32_16x16x32_bf16 v[18:21], v[180:183], v[234:237], v[18:21]
	v_mfma_f32_16x16x32_bf16 v[18:21], v[184:187], v[238:241], v[18:21]
	v_mfma_f32_16x16x32_bf16 v[22:25], v[172:175], v[238:241], v[22:25]
	v_mfma_f32_16x16x32_bf16 v[22:25], v[168:171], v[234:237], v[22:25]
	s_barrier
	s_add_i32 s27, s27, 2
	s_add_u32 s44, s44, 0x10000
	s_addc_u32 s45, s45, 0
	s_cmp_lt_u32 s27, 30
	s_cbranch_scc1 .LBB0_682
	s_ashr_i32 s41, s40, 31
	s_lshl_b64 s[44:45], s[40:41], 21
	s_add_u32 s44, s18, s44
	s_addc_u32 s45, s19, s45
	s_ashr_i32 s39, s38, 31
	s_lshl_b64 s[46:47], s[38:39], 21
	v_readlane_b32 s58, v255, 15
	v_readlane_b32 s59, v255, 16
	s_add_u32 s46, s58, s46
	s_addc_u32 s47, s59, s47
	s_lshl_b32 s39, s26, 8
	v_or_b32_e32 v130, s39, v162
	v_ashrrev_i32_e32 v131, 31, v130
	v_lshl_add_u32 v166, s70, 8, v160
	v_lshl_add_u64 v[156:157], v[130:131], 1, s[24:25]
	v_mov_b32_e32 v168, v166
	s_and_b64 s[26:27], s[0:1], exec
	v_mad_i64_i32 v[158:159], s[58:59], v168, s78, v[156:157]
	v_add_co_u32_e32 v174, vcc, s61, v158
	s_cselect_b32 s41, s45, s51
	s_nop 0
	v_addc_co_u32_e32 v175, vcc, 0, v159, vcc
	v_add_co_u32_e32 v158, vcc, s77, v158
	global_load_dwordx4 v[130:133], v[174:175], off
	s_nop 0
	v_addc_co_u32_e32 v159, vcc, 0, v159, vcc
	global_load_dwordx4 v[170:173], v[158:159], off
	s_cselect_b32 s93, s44, s50
	s_cselect_b32 s27, s47, s49
	s_cselect_b32 s97, s46, s48
	s_add_u32 s50, s50, 0x10c000
	s_addc_u32 s51, s51, 0
	s_add_u32 s26, s48, 0x110000
	s_addc_u32 s33, s49, 0
	s_mov_b32 s56, 30
	s_waitcnt vmcnt(0)
	v_and_b32_e32 v177, 0xffff0000, v130
	v_lshlrev_b32_e32 v169, 16, v170
	v_max_f32_e32 v169, v169, v169
	v_lshlrev_b32_e32 v178, 16, v171
	v_and_b32_e32 v179, 0xffff0000, v171
	v_lshlrev_b32_e32 v171, 16, v172
	v_max_f32_e32 v169, 0xda24260, v169
	v_and_b32_e32 v176, 0xffff0000, v170
	v_rcp_f32_e32 v170, v169
	v_max_f32_e32 v169, v171, v171
	v_max_f32_e32 v169, 0xda24260, v169
	v_and_b32_e32 v180, 0xffff0000, v172
	v_rcp_f32_e32 v172, v169
	v_max_f32_e32 v169, v176, v176
	v_max_f32_e32 v169, 0xda24260, v169
	v_lshlrev_b32_e32 v176, 16, v130
	v_max_f32_e32 v130, v180, v180
	v_rcp_f32_e32 v171, v169
	v_max_f32_e32 v130, 0xda24260, v130
	v_lshlrev_b32_e32 v181, 16, v173
	v_and_b32_e32 v182, 0xffff0000, v173
	v_rcp_f32_e32 v173, v130
	v_max_f32_e32 v130, v178, v178
	v_pk_mul_f32 v[170:171], v[170:171], v[176:177]
	v_lshlrev_b32_e32 v176, 16, v132
	v_and_b32_e32 v177, 0xffff0000, v132
	v_max_f32_e32 v130, 0xda24260, v130
	v_pk_mul_f32 v[172:173], v[172:173], v[176:177]
	v_rcp_f32_e32 v176, v130
	v_max_f32_e32 v130, v181, v181
	v_lshlrev_b32_e32 v180, 16, v131
	v_and_b32_e32 v181, 0xffff0000, v131
	v_max_f32_e32 v131, v182, v182
	v_max_f32_e32 v130, 0xda24260, v130
	v_max_f32_e32 v131, 0xda24260, v131
	v_rcp_f32_e32 v130, v130
	v_rcp_f32_e32 v131, v131
	v_max_f32_e32 v132, v179, v179
	v_max_f32_e32 v132, 0xda24260, v132
	v_rcp_f32_e32 v177, v132
	v_lshlrev_b32_e32 v132, 16, v133
	v_and_b32_e32 v133, 0xffff0000, v133
	v_pk_mul_f32 v[130:131], v[130:131], v[132:133]
	v_pk_mul_f32 v[14:15], v[14:15], v[170:171]
	v_pk_mul_f32 v[12:13], v[12:13], v[130:131]
	v_pk_mul_f32 v[10:11], v[10:11], v[172:173]
	global_load_dwordx4 v[130:133], v[174:175], off offset:256
	global_load_dwordx4 v[170:173], v[158:159], off offset:256
	v_pk_mul_f32 v[176:177], v[176:177], v[180:181]
	s_waitcnt vmcnt(0)
; __device__ __forceinline__ float bflo(unsigned w) { return __uint_as_float(w << 16); }
; __device__ __forceinline__ float bfhi(unsigned w) { return __uint_as_float(w & 0xffff0000u); }
;     __device__ __forceinline__ void mid(f32x4 (&acc)[2][2][4][2], const Unit& u, int wr, int wc, int fr, int fq) const {
;     ...
;             for (int m = 0; m < 4; ++m) { const bf16_t* pr = P + (size_t)(row0 + ai * HALF + m * 16) * NP + col0;
; #pragma unroll
;                 for (int bj = 0; bj < 2; ++bj) { const u32x4 a = *(const u32x4*)(pr + PC_GA + bj * HALF), b = *(const u32x4*)(pr + PC_GB + bj * HALF);
;                     const f32x4 b0 = {bflo(b.x), bfhi(b.x), bflo(b.y), bfhi(b.y)}, b1 = {bflo(b.z), bfhi(b.z), bflo(b.w), bfhi(b.w)};
;                     const f32x4 a0 = {bflo(a.x), bfhi(a.x), bflo(a.y), bfhi(a.y)}, a1 = {bflo(a.z), bfhi(a.z), bflo(a.w), bfhi(a.w)};
;                     f32x4 r0, r1;
; #pragma unroll
;                     for (int j = 0; j < 4; ++j) { r0[j] = a0[j] * __builtin_amdgcn_rcpf(fmaxf(b0[j], 1e-30f)); r1[j] = a1[j] * __builtin_amdgcn_rcpf(fmaxf(b1[j], 1e-30f)); }
;                     acc[ai][bj][m][0] *= r0; acc[ai][bj][m][1] *= r1; }
;                 asm volatile("" ::: "memory"); }
	v_lshlrev_b32_e32 v158, 16, v170
	v_and_b32_e32 v159, 0xffff0000, v170
	v_lshlrev_b32_e32 v169, 16, v171
	v_and_b32_e32 v174, 0xffff0000, v171
	v_lshlrev_b32_e32 v170, 16, v172
	v_and_b32_e32 v171, 0xffff0000, v172
	v_max_f32_e32 v158, v158, v158
	v_max_f32_e32 v159, v159, v159
	v_pk_mul_f32 v[16:17], v[16:17], v[176:177]
	v_lshlrev_b32_e32 v175, 16, v173
	v_and_b32_e32 v176, 0xffff0000, v173
	v_max_f32_e32 v158, 0xda24260, v158
	v_max_f32_e32 v170, v170, v170
	v_max_f32_e32 v159, 0xda24260, v159
	v_lshlrev_b32_e32 v172, 16, v130
	v_and_b32_e32 v173, 0xffff0000, v130
	v_max_f32_e32 v130, v171, v171
	v_rcp_f32_e32 v158, v158
	v_max_f32_e32 v170, 0xda24260, v170
	v_rcp_f32_e32 v159, v159
	v_max_f32_e32 v130, 0xda24260, v130
	v_rcp_f32_e32 v170, v170
	v_rcp_f32_e32 v171, v130
	v_max_f32_e32 v130, v169, v169
	v_pk_mul_f32 v[158:159], v[158:159], v[172:173]
	v_lshlrev_b32_e32 v172, 16, v132
	v_and_b32_e32 v173, 0xffff0000, v132
	v_max_f32_e32 v130, 0xda24260, v130
	v_pk_mul_f32 v[170:171], v[170:171], v[172:173]
	v_rcp_f32_e32 v172, v130
	v_max_f32_e32 v130, v175, v175
	v_max_f32_e32 v132, v174, v174
	v_lshlrev_b32_e32 v174, 16, v131
	v_and_b32_e32 v175, 0xffff0000, v131
	v_max_f32_e32 v131, v176, v176
	v_max_f32_e32 v130, 0xda24260, v130
	v_max_f32_e32 v131, 0xda24260, v131
	v_rcp_f32_e32 v130, v130
	v_rcp_f32_e32 v131, v131
	v_max_f32_e32 v132, 0xda24260, v132
	v_rcp_f32_e32 v173, v132
	v_lshlrev_b32_e32 v132, 16, v133
	v_and_b32_e32 v133, 0xffff0000, v133
	v_pk_mul_f32 v[130:131], v[130:131], v[132:133]
	v_pk_mul_f32 v[30:31], v[30:31], v[158:159]
	v_pk_mul_f32 v[28:29], v[28:29], v[130:131]
	v_add_u32_e32 v130, 16, v168
	v_mad_i64_i32 v[158:159], s[58:59], v130, s78, v[156:157]
	v_pk_mul_f32 v[172:173], v[172:173], v[174:175]
	v_add_co_u32_e32 v174, vcc, s61, v158
	v_pk_mul_f32 v[32:33], v[32:33], v[172:173]
	s_nop 0
	v_addc_co_u32_e32 v175, vcc, 0, v159, vcc
	v_add_co_u32_e32 v158, vcc, s77, v158
	v_pk_mul_f32 v[26:27], v[26:27], v[170:171]
	s_nop 0
	v_addc_co_u32_e32 v159, vcc, 0, v159, vcc
	global_load_dwordx4 v[130:133], v[174:175], off
	global_load_dwordx4 v[170:173], v[158:159], off
	s_waitcnt vmcnt(1)
	v_and_b32_e32 v177, 0xffff0000, v130
	s_waitcnt vmcnt(0)
	v_lshlrev_b32_e32 v169, 16, v170
	v_max_f32_e32 v169, v169, v169
	v_lshlrev_b32_e32 v178, 16, v171
	v_and_b32_e32 v179, 0xffff0000, v171
	v_lshlrev_b32_e32 v171, 16, v172
	v_max_f32_e32 v169, 0xda24260, v169
	v_and_b32_e32 v176, 0xffff0000, v170
	v_rcp_f32_e32 v170, v169
	v_max_f32_e32 v169, v171, v171
	v_max_f32_e32 v169, 0xda24260, v169
	v_and_b32_e32 v180, 0xffff0000, v172
	v_rcp_f32_e32 v172, v169
	v_max_f32_e32 v169, v176, v176
	v_max_f32_e32 v169, 0xda24260, v169
	v_lshlrev_b32_e32 v176, 16, v130
	v_max_f32_e32 v130, v180, v180
	v_rcp_f32_e32 v171, v169
	v_max_f32_e32 v130, 0xda24260, v130
	v_lshlrev_b32_e32 v181, 16, v173
	v_and_b32_e32 v182, 0xffff0000, v173
	v_rcp_f32_e32 v173, v130
	v_max_f32_e32 v130, v178, v178
	v_pk_mul_f32 v[170:171], v[170:171], v[176:177]
	v_lshlrev_b32_e32 v176, 16, v132
	v_and_b32_e32 v177, 0xffff0000, v132
	v_max_f32_e32 v130, 0xda24260, v130
	v_pk_mul_f32 v[172:173], v[172:173], v[176:177]
	v_rcp_f32_e32 v176, v130
	v_max_f32_e32 v130, v181, v181
	v_lshlrev_b32_e32 v180, 16, v131
	v_and_b32_e32 v181, 0xffff0000, v131
	v_max_f32_e32 v131, v182, v182
	v_max_f32_e32 v130, 0xda24260, v130
	v_max_f32_e32 v131, 0xda24260, v131
	v_rcp_f32_e32 v130, v130
	v_rcp_f32_e32 v131, v131
	v_max_f32_e32 v132, v179, v179
	v_max_f32_e32 v132, 0xda24260, v132
	v_rcp_f32_e32 v177, v132
	v_lshlrev_b32_e32 v132, 16, v133
	v_and_b32_e32 v133, 0xffff0000, v133
	v_pk_mul_f32 v[130:131], v[130:131], v[132:133]
	v_pk_mul_f32 v[38:39], v[38:39], v[170:171]
	v_pk_mul_f32 v[36:37], v[36:37], v[130:131]
	v_pk_mul_f32 v[34:35], v[34:35], v[172:173]
	global_load_dwordx4 v[130:133], v[174:175], off offset:256
	global_load_dwordx4 v[170:173], v[158:159], off offset:256
	v_pk_mul_f32 v[176:177], v[176:177], v[180:181]
	s_waitcnt vmcnt(0)
	v_lshlrev_b32_e32 v158, 16, v170
	v_and_b32_e32 v159, 0xffff0000, v170
	v_lshlrev_b32_e32 v169, 16, v171
	v_and_b32_e32 v174, 0xffff0000, v171
	v_lshlrev_b32_e32 v170, 16, v172
	v_and_b32_e32 v171, 0xffff0000, v172
	v_max_f32_e32 v158, v158, v158
	v_max_f32_e32 v159, v159, v159
	v_pk_mul_f32 v[40:41], v[40:41], v[176:177]
	v_lshlrev_b32_e32 v175, 16, v173
	v_and_b32_e32 v176, 0xffff0000, v173
	v_max_f32_e32 v158, 0xda24260, v158
	v_max_f32_e32 v170, v170, v170
	v_max_f32_e32 v159, 0xda24260, v159
	v_lshlrev_b32_e32 v172, 16, v130
	v_and_b32_e32 v173, 0xffff0000, v130
	v_max_f32_e32 v130, v171, v171
	v_rcp_f32_e32 v158, v158
	v_max_f32_e32 v170, 0xda24260, v170
	v_rcp_f32_e32 v159, v159
	v_max_f32_e32 v130, 0xda24260, v130
	v_rcp_f32_e32 v170, v170
	v_rcp_f32_e32 v171, v130
	v_max_f32_e32 v130, v169, v169
	v_pk_mul_f32 v[158:159], v[158:159], v[172:173]
	v_lshlrev_b32_e32 v172, 16, v132
	v_and_b32_e32 v173, 0xffff0000, v132
	v_max_f32_e32 v130, 0xda24260, v130
	v_pk_mul_f32 v[170:171], v[170:171], v[172:173]
	v_rcp_f32_e32 v172, v130
	v_max_f32_e32 v130, v175, v175
	v_max_f32_e32 v132, v174, v174
	v_lshlrev_b32_e32 v174, 16, v131
	v_and_b32_e32 v175, 0xffff0000, v131
	v_max_f32_e32 v131, v176, v176
	v_max_f32_e32 v130, 0xda24260, v130
	v_max_f32_e32 v131, 0xda24260, v131
	v_rcp_f32_e32 v130, v130
	v_rcp_f32_e32 v131, v131
	v_max_f32_e32 v132, 0xda24260, v132
	v_rcp_f32_e32 v173, v132
	v_lshlrev_b32_e32 v132, 16, v133
	v_and_b32_e32 v133, 0xffff0000, v133
	v_pk_mul_f32 v[130:131], v[130:131], v[132:133]
	v_pk_mul_f32 v[54:55], v[54:55], v[158:159]
	v_pk_mul_f32 v[52:53], v[52:53], v[130:131]
	v_add_u32_e32 v130, 32, v168
	v_mad_i64_i32 v[158:159], s[58:59], v130, s78, v[156:157]
	v_pk_mul_f32 v[172:173], v[172:173], v[174:175]
	v_add_co_u32_e32 v174, vcc, s61, v158
	v_pk_mul_f32 v[56:57], v[56:57], v[172:173]
	s_nop 0
	v_addc_co_u32_e32 v175, vcc, 0, v159, vcc
	v_add_co_u32_e32 v158, vcc, s77, v158
	v_pk_mul_f32 v[50:51], v[50:51], v[170:171]
	s_nop 0
	v_addc_co_u32_e32 v159, vcc, 0, v159, vcc
	global_load_dwordx4 v[130:133], v[174:175], off
	global_load_dwordx4 v[170:173], v[158:159], off
	s_waitcnt vmcnt(1)
; __device__ __forceinline__ float bflo(unsigned w) { return __uint_as_float(w << 16); }
; __device__ __forceinline__ float bfhi(unsigned w) { return __uint_as_float(w & 0xffff0000u); }
;     __device__ __forceinline__ void mid(f32x4 (&acc)[2][2][4][2], const Unit& u, int wr, int wc, int fr, int fq) const {
;     ...
;             for (int m = 0; m < 4; ++m) { const bf16_t* pr = P + (size_t)(row0 + ai * HALF + m * 16) * NP + col0;
; #pragma unroll
;                 for (int bj = 0; bj < 2; ++bj) { const u32x4 a = *(const u32x4*)(pr + PC_GA + bj * HALF), b = *(const u32x4*)(pr + PC_GB + bj * HALF);
;                     const f32x4 b0 = {bflo(b.x), bfhi(b.x), bflo(b.y), bfhi(b.y)}, b1 = {bflo(b.z), bfhi(b.z), bflo(b.w), bfhi(b.w)};
;                     const f32x4 a0 = {bflo(a.x), bfhi(a.x), bflo(a.y), bfhi(a.y)}, a1 = {bflo(a.z), bfhi(a.z), bflo(a.w), bfhi(a.w)};
;                     f32x4 r0, r1;
; #pragma unroll
;                     for (int j = 0; j < 4; ++j) { r0[j] = a0[j] * __builtin_amdgcn_rcpf(fmaxf(b0[j], 1e-30f)); r1[j] = a1[j] * __builtin_amdgcn_rcpf(fmaxf(b1[j], 1e-30f)); }
;                     acc[ai][bj][m][0] *= r0; acc[ai][bj][m][1] *= r1; }
;                 asm volatile("" ::: "memory"); }
	v_and_b32_e32 v177, 0xffff0000, v130
	s_waitcnt vmcnt(0)
	v_lshlrev_b32_e32 v169, 16, v170
	v_max_f32_e32 v169, v169, v169
	v_lshlrev_b32_e32 v178, 16, v171
	v_and_b32_e32 v179, 0xffff0000, v171
	v_lshlrev_b32_e32 v171, 16, v172
	v_max_f32_e32 v169, 0xda24260, v169
	v_and_b32_e32 v176, 0xffff0000, v170
	v_rcp_f32_e32 v170, v169
	v_max_f32_e32 v169, v171, v171
	v_max_f32_e32 v169, 0xda24260, v169
	v_and_b32_e32 v180, 0xffff0000, v172
	v_rcp_f32_e32 v172, v169
	v_max_f32_e32 v169, v176, v176
	v_max_f32_e32 v169, 0xda24260, v169
	v_lshlrev_b32_e32 v176, 16, v130
	v_max_f32_e32 v130, v180, v180
	v_rcp_f32_e32 v171, v169
	v_max_f32_e32 v130, 0xda24260, v130
	v_lshlrev_b32_e32 v181, 16, v173
	v_and_b32_e32 v182, 0xffff0000, v173
	v_rcp_f32_e32 v173, v130
	v_max_f32_e32 v130, v178, v178
	v_pk_mul_f32 v[170:171], v[170:171], v[176:177]
	v_lshlrev_b32_e32 v176, 16, v132
	v_and_b32_e32 v177, 0xffff0000, v132
	v_max_f32_e32 v130, 0xda24260, v130
	v_pk_mul_f32 v[172:173], v[172:173], v[176:177]
	v_rcp_f32_e32 v176, v130
	v_max_f32_e32 v130, v181, v181
	v_lshlrev_b32_e32 v180, 16, v131
	v_and_b32_e32 v181, 0xffff0000, v131
	v_max_f32_e32 v131, v182, v182
	v_max_f32_e32 v130, 0xda24260, v130
	v_max_f32_e32 v131, 0xda24260, v131
	v_rcp_f32_e32 v130, v130
	v_rcp_f32_e32 v131, v131
	v_max_f32_e32 v132, v179, v179
	v_max_f32_e32 v132, 0xda24260, v132
	v_rcp_f32_e32 v177, v132
	v_lshlrev_b32_e32 v132, 16, v133
	v_and_b32_e32 v133, 0xffff0000, v133
	v_pk_mul_f32 v[130:131], v[130:131], v[132:133]
	v_pk_mul_f32 v[70:71], v[70:71], v[170:171]
	v_pk_mul_f32 v[68:69], v[68:69], v[130:131]
	v_pk_mul_f32 v[66:67], v[66:67], v[172:173]
	global_load_dwordx4 v[130:133], v[174:175], off offset:256
	global_load_dwordx4 v[170:173], v[158:159], off offset:256
	v_pk_mul_f32 v[176:177], v[176:177], v[180:181]
	s_waitcnt vmcnt(0)
	v_lshlrev_b32_e32 v158, 16, v170
	v_and_b32_e32 v159, 0xffff0000, v170
	v_lshlrev_b32_e32 v169, 16, v171
	v_and_b32_e32 v174, 0xffff0000, v171
	v_lshlrev_b32_e32 v170, 16, v172
	v_and_b32_e32 v171, 0xffff0000, v172
	v_max_f32_e32 v158, v158, v158
	v_max_f32_e32 v159, v159, v159
	v_pk_mul_f32 v[72:73], v[72:73], v[176:177]
	v_lshlrev_b32_e32 v175, 16, v173
	v_and_b32_e32 v176, 0xffff0000, v173
	v_max_f32_e32 v158, 0xda24260, v158
	v_max_f32_e32 v170, v170, v170
	v_max_f32_e32 v159, 0xda24260, v159
	v_lshlrev_b32_e32 v172, 16, v130
	v_and_b32_e32 v173, 0xffff0000, v130
	v_max_f32_e32 v130, v171, v171
	v_rcp_f32_e32 v158, v158
	v_max_f32_e32 v170, 0xda24260, v170
	v_rcp_f32_e32 v159, v159
	v_max_f32_e32 v130, 0xda24260, v130
	v_rcp_f32_e32 v170, v170
	v_rcp_f32_e32 v171, v130
	v_max_f32_e32 v130, v169, v169
	v_pk_mul_f32 v[158:159], v[158:159], v[172:173]
	v_lshlrev_b32_e32 v172, 16, v132
	v_and_b32_e32 v173, 0xffff0000, v132
	v_max_f32_e32 v130, 0xda24260, v130
	v_pk_mul_f32 v[170:171], v[170:171], v[172:173]
	v_rcp_f32_e32 v172, v130
	v_max_f32_e32 v130, v175, v175
	v_max_f32_e32 v132, v174, v174
	v_lshlrev_b32_e32 v174, 16, v131
	v_and_b32_e32 v175, 0xffff0000, v131
	v_max_f32_e32 v131, v176, v176
	v_max_f32_e32 v130, 0xda24260, v130
	v_max_f32_e32 v131, 0xda24260, v131
	v_rcp_f32_e32 v130, v130
	v_rcp_f32_e32 v131, v131
	v_max_f32_e32 v132, 0xda24260, v132
	v_rcp_f32_e32 v173, v132
	v_lshlrev_b32_e32 v132, 16, v133
	v_and_b32_e32 v133, 0xffff0000, v133
	v_pk_mul_f32 v[130:131], v[130:131], v[132:133]
	v_pk_mul_f32 v[86:87], v[86:87], v[158:159]
	v_pk_mul_f32 v[84:85], v[84:85], v[130:131]
	v_add_u32_e32 v130, 48, v168
	v_mad_i64_i32 v[158:159], s[58:59], v130, s78, v[156:157]
	v_pk_mul_f32 v[172:173], v[172:173], v[174:175]
	v_add_co_u32_e32 v174, vcc, s61, v158
	v_pk_mul_f32 v[88:89], v[88:89], v[172:173]
	s_nop 0
	v_addc_co_u32_e32 v175, vcc, 0, v159, vcc
	v_add_co_u32_e32 v158, vcc, s77, v158
	v_pk_mul_f32 v[82:83], v[82:83], v[170:171]
	s_nop 0
	v_addc_co_u32_e32 v159, vcc, 0, v159, vcc
	global_load_dwordx4 v[130:133], v[174:175], off
	global_load_dwordx4 v[170:173], v[158:159], off
	s_waitcnt vmcnt(1)
	v_and_b32_e32 v177, 0xffff0000, v130
	s_waitcnt vmcnt(0)
	v_lshlrev_b32_e32 v169, 16, v170
	v_max_f32_e32 v169, v169, v169
	v_lshlrev_b32_e32 v178, 16, v171
	v_and_b32_e32 v179, 0xffff0000, v171
	v_lshlrev_b32_e32 v171, 16, v172
	v_max_f32_e32 v169, 0xda24260, v169
	v_and_b32_e32 v176, 0xffff0000, v170
	v_rcp_f32_e32 v170, v169
	v_max_f32_e32 v169, v171, v171
	v_max_f32_e32 v169, 0xda24260, v169
	v_and_b32_e32 v180, 0xffff0000, v172
	v_rcp_f32_e32 v172, v169
	v_max_f32_e32 v169, v176, v176
	v_max_f32_e32 v169, 0xda24260, v169
	v_lshlrev_b32_e32 v176, 16, v130
	v_max_f32_e32 v130, v180, v180
	v_rcp_f32_e32 v171, v169
	v_max_f32_e32 v130, 0xda24260, v130
	v_lshlrev_b32_e32 v181, 16, v173
	v_and_b32_e32 v182, 0xffff0000, v173
	v_rcp_f32_e32 v173, v130
	v_max_f32_e32 v130, v178, v178
	v_pk_mul_f32 v[170:171], v[170:171], v[176:177]
	v_lshlrev_b32_e32 v176, 16, v132
	v_and_b32_e32 v177, 0xffff0000, v132
	v_max_f32_e32 v130, 0xda24260, v130
	v_pk_mul_f32 v[172:173], v[172:173], v[176:177]
	v_rcp_f32_e32 v176, v130
	v_max_f32_e32 v130, v181, v181
	v_lshlrev_b32_e32 v180, 16, v131
	v_and_b32_e32 v181, 0xffff0000, v131
	v_max_f32_e32 v131, v182, v182
	v_max_f32_e32 v130, 0xda24260, v130
	v_max_f32_e32 v131, 0xda24260, v131
	v_rcp_f32_e32 v130, v130
	v_rcp_f32_e32 v131, v131
	v_max_f32_e32 v132, v179, v179
	v_max_f32_e32 v132, 0xda24260, v132
	v_rcp_f32_e32 v177, v132
	v_lshlrev_b32_e32 v132, 16, v133
	v_and_b32_e32 v133, 0xffff0000, v133
	v_pk_mul_f32 v[130:131], v[130:131], v[132:133]
	v_pk_mul_f32 v[94:95], v[94:95], v[170:171]
	v_pk_mul_f32 v[92:93], v[92:93], v[130:131]
	v_pk_mul_f32 v[90:91], v[90:91], v[172:173]
	global_load_dwordx4 v[130:133], v[174:175], off offset:256
	global_load_dwordx4 v[170:173], v[158:159], off offset:256
	v_pk_mul_f32 v[176:177], v[176:177], v[180:181]
	s_waitcnt vmcnt(0)
; __device__ __forceinline__ float bflo(unsigned w) { return __uint_as_float(w << 16); }
; __device__ __forceinline__ float bfhi(unsigned w) { return __uint_as_float(w & 0xffff0000u); }
;     __device__ __forceinline__ void mid(f32x4 (&acc)[2][2][4][2], const Unit& u, int wr, int wc, int fr, int fq) const {
;     ...
;             for (int m = 0; m < 4; ++m) { const bf16_t* pr = P + (size_t)(row0 + ai * HALF + m * 16) * NP + col0;
; #pragma unroll
;                 for (int bj = 0; bj < 2; ++bj) { const u32x4 a = *(const u32x4*)(pr + PC_GA + bj * HALF), b = *(const u32x4*)(pr + PC_GB + bj * HALF);
;                     const f32x4 b0 = {bflo(b.x), bfhi(b.x), bflo(b.y), bfhi(b.y)}, b1 = {bflo(b.z), bfhi(b.z), bflo(b.w), bfhi(b.w)};
;                     const f32x4 a0 = {bflo(a.x), bfhi(a.x), bflo(a.y), bfhi(a.y)}, a1 = {bflo(a.z), bfhi(a.z), bflo(a.w), bfhi(a.w)};
;                     f32x4 r0, r1;
; #pragma unroll
;                     for (int j = 0; j < 4; ++j) { r0[j] = a0[j] * __builtin_amdgcn_rcpf(fmaxf(b0[j], 1e-30f)); r1[j] = a1[j] * __builtin_amdgcn_rcpf(fmaxf(b1[j], 1e-30f)); }
;                     acc[ai][bj][m][0] *= r0; acc[ai][bj][m][1] *= r1; }
;                 asm volatile("" ::: "memory"); }
	v_lshlrev_b32_e32 v158, 16, v170
	v_and_b32_e32 v159, 0xffff0000, v170
	v_lshlrev_b32_e32 v169, 16, v171
	v_and_b32_e32 v174, 0xffff0000, v171
	v_lshlrev_b32_e32 v170, 16, v172
	v_and_b32_e32 v171, 0xffff0000, v172
	v_max_f32_e32 v158, v158, v158
	v_max_f32_e32 v159, v159, v159
	v_pk_mul_f32 v[96:97], v[96:97], v[176:177]
	v_lshlrev_b32_e32 v175, 16, v173
	v_and_b32_e32 v176, 0xffff0000, v173
	v_max_f32_e32 v158, 0xda24260, v158
	v_max_f32_e32 v170, v170, v170
	v_max_f32_e32 v159, 0xda24260, v159
	v_lshlrev_b32_e32 v172, 16, v130
	v_and_b32_e32 v173, 0xffff0000, v130
	v_max_f32_e32 v130, v171, v171
	v_rcp_f32_e32 v158, v158
	v_max_f32_e32 v170, 0xda24260, v170
	v_rcp_f32_e32 v159, v159
	v_max_f32_e32 v130, 0xda24260, v130
	v_rcp_f32_e32 v170, v170
	v_rcp_f32_e32 v171, v130
	v_max_f32_e32 v130, v169, v169
	v_pk_mul_f32 v[158:159], v[158:159], v[172:173]
	v_lshlrev_b32_e32 v172, 16, v132
	v_and_b32_e32 v173, 0xffff0000, v132
	v_max_f32_e32 v130, 0xda24260, v130
	v_pk_mul_f32 v[170:171], v[170:171], v[172:173]
	v_rcp_f32_e32 v172, v130
	v_max_f32_e32 v130, v175, v175
	v_max_f32_e32 v132, v174, v174
	v_lshlrev_b32_e32 v174, 16, v131
	v_and_b32_e32 v175, 0xffff0000, v131
	v_max_f32_e32 v131, v176, v176
	v_max_f32_e32 v130, 0xda24260, v130
	v_max_f32_e32 v131, 0xda24260, v131
	v_rcp_f32_e32 v130, v130
	v_rcp_f32_e32 v131, v131
	v_max_f32_e32 v132, 0xda24260, v132
	v_rcp_f32_e32 v173, v132
	v_lshlrev_b32_e32 v132, 16, v133
	v_and_b32_e32 v133, 0xffff0000, v133
	v_pk_mul_f32 v[130:131], v[130:131], v[132:133]
	v_pk_mul_f32 v[110:111], v[110:111], v[158:159]
	v_pk_mul_f32 v[108:109], v[108:109], v[130:131]
	v_add_u32_e32 v130, 0x80, v168
	v_mad_i64_i32 v[158:159], s[58:59], v130, s78, v[156:157]
	v_pk_mul_f32 v[172:173], v[172:173], v[174:175]
	v_add_co_u32_e32 v174, vcc, s61, v158
	v_pk_mul_f32 v[112:113], v[112:113], v[172:173]
	s_nop 0
	v_addc_co_u32_e32 v175, vcc, 0, v159, vcc
	v_add_co_u32_e32 v158, vcc, s77, v158
	v_pk_mul_f32 v[106:107], v[106:107], v[170:171]
	s_nop 0
	v_addc_co_u32_e32 v159, vcc, 0, v159, vcc
	global_load_dwordx4 v[130:133], v[174:175], off
	global_load_dwordx4 v[170:173], v[158:159], off
	s_waitcnt vmcnt(1)
	v_and_b32_e32 v177, 0xffff0000, v130
	s_waitcnt vmcnt(0)
	v_lshlrev_b32_e32 v169, 16, v170
	v_max_f32_e32 v169, v169, v169
	v_lshlrev_b32_e32 v178, 16, v171
	v_and_b32_e32 v179, 0xffff0000, v171
	v_lshlrev_b32_e32 v171, 16, v172
	v_max_f32_e32 v169, 0xda24260, v169
	v_and_b32_e32 v176, 0xffff0000, v170
	v_rcp_f32_e32 v170, v169
	v_max_f32_e32 v169, v171, v171
	v_max_f32_e32 v169, 0xda24260, v169
	v_and_b32_e32 v180, 0xffff0000, v172
	v_rcp_f32_e32 v172, v169
	v_max_f32_e32 v169, v176, v176
	v_max_f32_e32 v169, 0xda24260, v169
	v_lshlrev_b32_e32 v176, 16, v130
	v_max_f32_e32 v130, v180, v180
	v_rcp_f32_e32 v171, v169
	v_max_f32_e32 v130, 0xda24260, v130
	v_lshlrev_b32_e32 v181, 16, v173
	v_and_b32_e32 v182, 0xffff0000, v173
	v_rcp_f32_e32 v173, v130
	v_max_f32_e32 v130, v178, v178
	v_pk_mul_f32 v[170:171], v[170:171], v[176:177]
	v_lshlrev_b32_e32 v176, 16, v132
	v_and_b32_e32 v177, 0xffff0000, v132
	v_max_f32_e32 v130, 0xda24260, v130
	v_pk_mul_f32 v[172:173], v[172:173], v[176:177]
	v_rcp_f32_e32 v176, v130
	v_max_f32_e32 v130, v181, v181
	v_lshlrev_b32_e32 v180, 16, v131
	v_and_b32_e32 v181, 0xffff0000, v131
	v_max_f32_e32 v131, v182, v182
	v_max_f32_e32 v130, 0xda24260, v130
	v_max_f32_e32 v131, 0xda24260, v131
	v_rcp_f32_e32 v130, v130
	v_rcp_f32_e32 v131, v131
	v_max_f32_e32 v132, v179, v179
	v_max_f32_e32 v132, 0xda24260, v132
	v_rcp_f32_e32 v177, v132
	v_lshlrev_b32_e32 v132, 16, v133
	v_and_b32_e32 v133, 0xffff0000, v133
	v_pk_mul_f32 v[130:131], v[130:131], v[132:133]
	v_pk_mul_f32 v[126:127], v[126:127], v[170:171]
	v_pk_mul_f32 v[124:125], v[124:125], v[130:131]
	v_pk_mul_f32 v[122:123], v[122:123], v[172:173]
	global_load_dwordx4 v[130:133], v[174:175], off offset:256
	global_load_dwordx4 v[170:173], v[158:159], off offset:256
	v_pk_mul_f32 v[176:177], v[176:177], v[180:181]
	s_waitcnt vmcnt(0)
	v_lshlrev_b32_e32 v158, 16, v170
	v_and_b32_e32 v159, 0xffff0000, v170
	v_lshlrev_b32_e32 v169, 16, v171
	v_and_b32_e32 v174, 0xffff0000, v171
	v_lshlrev_b32_e32 v170, 16, v172
	v_and_b32_e32 v171, 0xffff0000, v172
	v_max_f32_e32 v158, v158, v158
	v_max_f32_e32 v159, v159, v159
	v_pk_mul_f32 v[128:129], v[128:129], v[176:177]
	v_lshlrev_b32_e32 v175, 16, v173
	v_and_b32_e32 v176, 0xffff0000, v173
	v_max_f32_e32 v158, 0xda24260, v158
	v_max_f32_e32 v170, v170, v170
	v_max_f32_e32 v159, 0xda24260, v159
	v_lshlrev_b32_e32 v172, 16, v130
	v_and_b32_e32 v173, 0xffff0000, v130
	v_max_f32_e32 v130, v171, v171
	v_rcp_f32_e32 v158, v158
	v_max_f32_e32 v170, 0xda24260, v170
	v_rcp_f32_e32 v159, v159
	v_max_f32_e32 v130, 0xda24260, v130
	v_rcp_f32_e32 v170, v170
	v_rcp_f32_e32 v171, v130
	v_max_f32_e32 v130, v169, v169
	v_pk_mul_f32 v[158:159], v[158:159], v[172:173]
	v_lshlrev_b32_e32 v172, 16, v132
	v_and_b32_e32 v173, 0xffff0000, v132
	v_max_f32_e32 v130, 0xda24260, v130
	v_pk_mul_f32 v[170:171], v[170:171], v[172:173]
	v_rcp_f32_e32 v172, v130
	v_max_f32_e32 v130, v175, v175
	v_max_f32_e32 v132, v174, v174
	v_lshlrev_b32_e32 v174, 16, v131
	v_and_b32_e32 v175, 0xffff0000, v131
	v_max_f32_e32 v131, v176, v176
	v_max_f32_e32 v130, 0xda24260, v130
	v_max_f32_e32 v131, 0xda24260, v131
	v_rcp_f32_e32 v130, v130
	v_rcp_f32_e32 v131, v131
	v_max_f32_e32 v132, 0xda24260, v132
	v_rcp_f32_e32 v173, v132
	v_lshlrev_b32_e32 v132, 16, v133
	v_and_b32_e32 v133, 0xffff0000, v133
	v_pk_mul_f32 v[130:131], v[130:131], v[132:133]
	v_pk_mul_f32 v[118:119], v[118:119], v[158:159]
	v_pk_mul_f32 v[116:117], v[116:117], v[130:131]
	v_add_u32_e32 v130, 0x90, v168
	v_mad_i64_i32 v[158:159], s[58:59], v130, s78, v[156:157]
	v_pk_mul_f32 v[172:173], v[172:173], v[174:175]
	v_add_co_u32_e32 v174, vcc, s61, v158
	v_pk_mul_f32 v[120:121], v[120:121], v[172:173]
	s_nop 0
	v_addc_co_u32_e32 v175, vcc, 0, v159, vcc
	v_add_co_u32_e32 v158, vcc, s77, v158
	v_pk_mul_f32 v[114:115], v[114:115], v[170:171]
	s_nop 0
	v_addc_co_u32_e32 v159, vcc, 0, v159, vcc
	global_load_dwordx4 v[130:133], v[174:175], off
	global_load_dwordx4 v[170:173], v[158:159], off
	s_waitcnt vmcnt(1)
; __device__ __forceinline__ float bflo(unsigned w) { return __uint_as_float(w << 16); }
; __device__ __forceinline__ float bfhi(unsigned w) { return __uint_as_float(w & 0xffff0000u); }
;     __device__ __forceinline__ void mid(f32x4 (&acc)[2][2][4][2], const Unit& u, int wr, int wc, int fr, int fq) const {
;     ...
;             for (int m = 0; m < 4; ++m) { const bf16_t* pr = P + (size_t)(row0 + ai * HALF + m * 16) * NP + col0;
; #pragma unroll
;                 for (int bj = 0; bj < 2; ++bj) { const u32x4 a = *(const u32x4*)(pr + PC_GA + bj * HALF), b = *(const u32x4*)(pr + PC_GB + bj * HALF);
;                     const f32x4 b0 = {bflo(b.x), bfhi(b.x), bflo(b.y), bfhi(b.y)}, b1 = {bflo(b.z), bfhi(b.z), bflo(b.w), bfhi(b.w)};
;                     const f32x4 a0 = {bflo(a.x), bfhi(a.x), bflo(a.y), bfhi(a.y)}, a1 = {bflo(a.z), bfhi(a.z), bflo(a.w), bfhi(a.w)};
;                     f32x4 r0, r1;
; #pragma unroll
;                     for (int j = 0; j < 4; ++j) { r0[j] = a0[j] * __builtin_amdgcn_rcpf(fmaxf(b0[j], 1e-30f)); r1[j] = a1[j] * __builtin_amdgcn_rcpf(fmaxf(b1[j], 1e-30f)); }
;                     acc[ai][bj][m][0] *= r0; acc[ai][bj][m][1] *= r1; }
;                 asm volatile("" ::: "memory"); }
	v_and_b32_e32 v177, 0xffff0000, v130
	s_waitcnt vmcnt(0)
	v_lshlrev_b32_e32 v169, 16, v170
	v_max_f32_e32 v169, v169, v169
	v_lshlrev_b32_e32 v178, 16, v171
	v_and_b32_e32 v179, 0xffff0000, v171
	v_lshlrev_b32_e32 v171, 16, v172
	v_max_f32_e32 v169, 0xda24260, v169
	v_and_b32_e32 v176, 0xffff0000, v170
	v_rcp_f32_e32 v170, v169
	v_max_f32_e32 v169, v171, v171
	v_max_f32_e32 v169, 0xda24260, v169
	v_and_b32_e32 v180, 0xffff0000, v172
	v_rcp_f32_e32 v172, v169
	v_max_f32_e32 v169, v176, v176
	v_max_f32_e32 v169, 0xda24260, v169
	v_lshlrev_b32_e32 v176, 16, v130
	v_max_f32_e32 v130, v180, v180
	v_rcp_f32_e32 v171, v169
	v_max_f32_e32 v130, 0xda24260, v130
	v_lshlrev_b32_e32 v181, 16, v173
	v_and_b32_e32 v182, 0xffff0000, v173
	v_rcp_f32_e32 v173, v130
	v_max_f32_e32 v130, v178, v178
	v_pk_mul_f32 v[170:171], v[170:171], v[176:177]
	v_lshlrev_b32_e32 v176, 16, v132
	v_and_b32_e32 v177, 0xffff0000, v132
	v_max_f32_e32 v130, 0xda24260, v130
	v_pk_mul_f32 v[172:173], v[172:173], v[176:177]
	v_rcp_f32_e32 v176, v130
	v_max_f32_e32 v130, v181, v181
	v_lshlrev_b32_e32 v180, 16, v131
	v_and_b32_e32 v181, 0xffff0000, v131
	v_max_f32_e32 v131, v182, v182
	v_max_f32_e32 v130, 0xda24260, v130
	v_max_f32_e32 v131, 0xda24260, v131
	v_rcp_f32_e32 v130, v130
	v_rcp_f32_e32 v131, v131
	v_max_f32_e32 v132, v179, v179
	v_max_f32_e32 v132, 0xda24260, v132
	v_rcp_f32_e32 v177, v132
	v_lshlrev_b32_e32 v132, 16, v133
	v_and_b32_e32 v133, 0xffff0000, v133
	v_pk_mul_f32 v[130:131], v[130:131], v[132:133]
	v_pk_mul_f32 v[102:103], v[102:103], v[170:171]
	v_pk_mul_f32 v[100:101], v[100:101], v[130:131]
	v_pk_mul_f32 v[98:99], v[98:99], v[172:173]
	global_load_dwordx4 v[130:133], v[174:175], off offset:256
	global_load_dwordx4 v[170:173], v[158:159], off offset:256
	v_pk_mul_f32 v[176:177], v[176:177], v[180:181]
	s_waitcnt vmcnt(0)
	v_lshlrev_b32_e32 v158, 16, v170
	v_and_b32_e32 v159, 0xffff0000, v170
	v_lshlrev_b32_e32 v169, 16, v171
	v_and_b32_e32 v174, 0xffff0000, v171
	v_lshlrev_b32_e32 v170, 16, v172
	v_and_b32_e32 v171, 0xffff0000, v172
	v_max_f32_e32 v158, v158, v158
	v_max_f32_e32 v159, v159, v159
	v_pk_mul_f32 v[104:105], v[104:105], v[176:177]
	v_lshlrev_b32_e32 v175, 16, v173
	v_and_b32_e32 v176, 0xffff0000, v173
	v_max_f32_e32 v158, 0xda24260, v158
	v_max_f32_e32 v170, v170, v170
	v_max_f32_e32 v159, 0xda24260, v159
	v_lshlrev_b32_e32 v172, 16, v130
	v_and_b32_e32 v173, 0xffff0000, v130
	v_max_f32_e32 v130, v171, v171
	v_rcp_f32_e32 v158, v158
	v_max_f32_e32 v170, 0xda24260, v170
	v_rcp_f32_e32 v159, v159
	v_max_f32_e32 v130, 0xda24260, v130
	v_rcp_f32_e32 v170, v170
	v_rcp_f32_e32 v171, v130
	v_max_f32_e32 v130, v169, v169
	v_pk_mul_f32 v[158:159], v[158:159], v[172:173]
	v_lshlrev_b32_e32 v172, 16, v132
	v_and_b32_e32 v173, 0xffff0000, v132
	v_max_f32_e32 v130, 0xda24260, v130
	v_pk_mul_f32 v[170:171], v[170:171], v[172:173]
	v_rcp_f32_e32 v172, v130
	v_max_f32_e32 v130, v175, v175
	v_max_f32_e32 v132, v174, v174
	v_lshlrev_b32_e32 v174, 16, v131
	v_and_b32_e32 v175, 0xffff0000, v131
	v_max_f32_e32 v131, v176, v176
	v_max_f32_e32 v130, 0xda24260, v130
	v_max_f32_e32 v131, 0xda24260, v131
	v_rcp_f32_e32 v130, v130
	v_rcp_f32_e32 v131, v131
	v_max_f32_e32 v132, 0xda24260, v132
	v_rcp_f32_e32 v173, v132
	v_lshlrev_b32_e32 v132, 16, v133
	v_and_b32_e32 v133, 0xffff0000, v133
	v_pk_mul_f32 v[130:131], v[130:131], v[132:133]
	v_pk_mul_f32 v[78:79], v[78:79], v[158:159]
	v_pk_mul_f32 v[76:77], v[76:77], v[130:131]
	v_add_u32_e32 v130, 0xa0, v168
	v_mad_i64_i32 v[158:159], s[58:59], v130, s78, v[156:157]
	v_pk_mul_f32 v[172:173], v[172:173], v[174:175]
	v_add_co_u32_e32 v174, vcc, s61, v158
	v_pk_mul_f32 v[80:81], v[80:81], v[172:173]
	s_nop 0
	v_addc_co_u32_e32 v175, vcc, 0, v159, vcc
	v_add_co_u32_e32 v158, vcc, s77, v158
	v_pk_mul_f32 v[74:75], v[74:75], v[170:171]
	s_nop 0
	v_addc_co_u32_e32 v159, vcc, 0, v159, vcc
	global_load_dwordx4 v[130:133], v[174:175], off
	global_load_dwordx4 v[170:173], v[158:159], off
	s_waitcnt vmcnt(1)
	v_and_b32_e32 v177, 0xffff0000, v130
	s_waitcnt vmcnt(0)
	v_lshlrev_b32_e32 v169, 16, v170
	v_max_f32_e32 v169, v169, v169
	v_lshlrev_b32_e32 v178, 16, v171
	v_and_b32_e32 v179, 0xffff0000, v171
	v_lshlrev_b32_e32 v171, 16, v172
	v_max_f32_e32 v169, 0xda24260, v169
	v_and_b32_e32 v176, 0xffff0000, v170
	v_rcp_f32_e32 v170, v169
	v_max_f32_e32 v169, v171, v171
	v_max_f32_e32 v169, 0xda24260, v169
	v_and_b32_e32 v180, 0xffff0000, v172
	v_rcp_f32_e32 v172, v169
	v_max_f32_e32 v169, v176, v176
	v_max_f32_e32 v169, 0xda24260, v169
	v_lshlrev_b32_e32 v176, 16, v130
	v_max_f32_e32 v130, v180, v180
	v_rcp_f32_e32 v171, v169
	v_max_f32_e32 v130, 0xda24260, v130
	v_lshlrev_b32_e32 v181, 16, v173
	v_and_b32_e32 v182, 0xffff0000, v173
	v_rcp_f32_e32 v173, v130
	v_max_f32_e32 v130, v178, v178
	v_pk_mul_f32 v[170:171], v[170:171], v[176:177]
	v_lshlrev_b32_e32 v176, 16, v132
	v_and_b32_e32 v177, 0xffff0000, v132
	v_max_f32_e32 v130, 0xda24260, v130
	v_pk_mul_f32 v[172:173], v[172:173], v[176:177]
	v_rcp_f32_e32 v176, v130
	v_max_f32_e32 v130, v181, v181
	v_lshlrev_b32_e32 v180, 16, v131
	v_and_b32_e32 v181, 0xffff0000, v131
	v_max_f32_e32 v131, v182, v182
	v_max_f32_e32 v130, 0xda24260, v130
	v_max_f32_e32 v131, 0xda24260, v131
	v_rcp_f32_e32 v130, v130
	v_rcp_f32_e32 v131, v131
	v_max_f32_e32 v132, v179, v179
	v_max_f32_e32 v132, 0xda24260, v132
	v_rcp_f32_e32 v177, v132
	v_lshlrev_b32_e32 v132, 16, v133
	v_and_b32_e32 v133, 0xffff0000, v133
	v_pk_mul_f32 v[130:131], v[130:131], v[132:133]
	v_pk_mul_f32 v[62:63], v[62:63], v[170:171]
	v_pk_mul_f32 v[60:61], v[60:61], v[130:131]
	v_pk_mul_f32 v[58:59], v[58:59], v[172:173]
	global_load_dwordx4 v[130:133], v[174:175], off offset:256
	global_load_dwordx4 v[170:173], v[158:159], off offset:256
	v_pk_mul_f32 v[176:177], v[176:177], v[180:181]
	s_waitcnt vmcnt(0)
; __device__ __forceinline__ float bflo(unsigned w) { return __uint_as_float(w << 16); }
; __device__ __forceinline__ float bfhi(unsigned w) { return __uint_as_float(w & 0xffff0000u); }
;     __device__ __forceinline__ void mid(f32x4 (&acc)[2][2][4][2], const Unit& u, int wr, int wc, int fr, int fq) const {
;     ...
;             for (int m = 0; m < 4; ++m) { const bf16_t* pr = P + (size_t)(row0 + ai * HALF + m * 16) * NP + col0;
; #pragma unroll
;                 for (int bj = 0; bj < 2; ++bj) { const u32x4 a = *(const u32x4*)(pr + PC_GA + bj * HALF), b = *(const u32x4*)(pr + PC_GB + bj * HALF);
;                     const f32x4 b0 = {bflo(b.x), bfhi(b.x), bflo(b.y), bfhi(b.y)}, b1 = {bflo(b.z), bfhi(b.z), bflo(b.w), bfhi(b.w)};
;                     const f32x4 a0 = {bflo(a.x), bfhi(a.x), bflo(a.y), bfhi(a.y)}, a1 = {bflo(a.z), bfhi(a.z), bflo(a.w), bfhi(a.w)};
;                     f32x4 r0, r1;
; #pragma unroll
;                     for (int j = 0; j < 4; ++j) { r0[j] = a0[j] * __builtin_amdgcn_rcpf(fmaxf(b0[j], 1e-30f)); r1[j] = a1[j] * __builtin_amdgcn_rcpf(fmaxf(b1[j], 1e-30f)); }
;                     acc[ai][bj][m][0] *= r0; acc[ai][bj][m][1] *= r1; }
;                 asm volatile("" ::: "memory"); }
	v_lshlrev_b32_e32 v158, 16, v170
	v_and_b32_e32 v159, 0xffff0000, v170
	v_lshlrev_b32_e32 v169, 16, v171
	v_and_b32_e32 v174, 0xffff0000, v171
	v_lshlrev_b32_e32 v170, 16, v172
	v_and_b32_e32 v171, 0xffff0000, v172
	v_max_f32_e32 v158, v158, v158
	v_max_f32_e32 v159, v159, v159
	v_pk_mul_f32 v[64:65], v[64:65], v[176:177]
	v_lshlrev_b32_e32 v175, 16, v173
	v_and_b32_e32 v176, 0xffff0000, v173
	v_max_f32_e32 v158, 0xda24260, v158
	v_max_f32_e32 v170, v170, v170
	v_max_f32_e32 v159, 0xda24260, v159
	v_lshlrev_b32_e32 v172, 16, v130
	v_and_b32_e32 v173, 0xffff0000, v130
	v_max_f32_e32 v130, v171, v171
	v_rcp_f32_e32 v158, v158
	v_max_f32_e32 v170, 0xda24260, v170
	v_rcp_f32_e32 v159, v159
	v_max_f32_e32 v130, 0xda24260, v130
	v_rcp_f32_e32 v170, v170
	v_rcp_f32_e32 v171, v130
	v_max_f32_e32 v130, v169, v169
	v_pk_mul_f32 v[158:159], v[158:159], v[172:173]
	v_lshlrev_b32_e32 v172, 16, v132
	v_and_b32_e32 v173, 0xffff0000, v132
	v_max_f32_e32 v130, 0xda24260, v130
	v_pk_mul_f32 v[170:171], v[170:171], v[172:173]
	v_rcp_f32_e32 v172, v130
	v_max_f32_e32 v130, v175, v175
	v_max_f32_e32 v132, v174, v174
	v_lshlrev_b32_e32 v174, 16, v131
	v_and_b32_e32 v175, 0xffff0000, v131
	v_max_f32_e32 v131, v176, v176
	v_max_f32_e32 v130, 0xda24260, v130
	v_max_f32_e32 v131, 0xda24260, v131
	v_rcp_f32_e32 v130, v130
	v_rcp_f32_e32 v131, v131
	v_max_f32_e32 v132, 0xda24260, v132
	v_rcp_f32_e32 v173, v132
	v_lshlrev_b32_e32 v132, 16, v133
	v_and_b32_e32 v133, 0xffff0000, v133
	v_pk_mul_f32 v[130:131], v[130:131], v[132:133]
	v_pk_mul_f32 v[46:47], v[46:47], v[158:159]
	v_pk_mul_f32 v[44:45], v[44:45], v[130:131]
	v_add_u32_e32 v130, 0xb0, v168
	v_mad_i64_i32 v[156:157], s[58:59], v130, s78, v[156:157]
	v_add_co_u32_e32 v158, vcc, s61, v156
	v_pk_mul_f32 v[42:43], v[42:43], v[170:171]
	s_nop 0
	v_addc_co_u32_e32 v159, vcc, 0, v157, vcc
	v_add_co_u32_e32 v156, vcc, s77, v156
	global_load_dwordx4 v[130:133], v[158:159], off
	s_nop 0
	v_addc_co_u32_e32 v157, vcc, 0, v157, vcc
	global_load_dwordx4 v[168:171], v[156:157], off
	v_pk_mul_f32 v[172:173], v[172:173], v[174:175]
	s_waitcnt vmcnt(0)
	v_lshlrev_b32_e32 v174, 16, v169
	v_and_b32_e32 v175, 0xffff0000, v169
	v_lshlrev_b32_e32 v169, 16, v170
	v_max_f32_e32 v169, v169, v169
	v_pk_mul_f32 v[48:49], v[48:49], v[172:173]
	v_lshlrev_b32_e32 v172, 16, v168
	v_and_b32_e32 v173, 0xffff0000, v168
	v_max_f32_e32 v169, 0xda24260, v169
	v_and_b32_e32 v176, 0xffff0000, v170
	v_max_f32_e32 v168, v172, v172
	v_rcp_f32_e32 v170, v169
	v_max_f32_e32 v169, v173, v173
	v_max_f32_e32 v168, 0xda24260, v168
	v_max_f32_e32 v169, 0xda24260, v169
	v_lshlrev_b32_e32 v172, 16, v130
	v_and_b32_e32 v173, 0xffff0000, v130
	v_max_f32_e32 v130, v176, v176
	v_rcp_f32_e32 v168, v168
	v_rcp_f32_e32 v169, v169
	v_max_f32_e32 v130, 0xda24260, v130
	v_lshlrev_b32_e32 v177, 16, v171
	v_and_b32_e32 v178, 0xffff0000, v171
	v_rcp_f32_e32 v171, v130
	v_max_f32_e32 v130, v174, v174
	v_pk_mul_f32 v[168:169], v[168:169], v[172:173]
	v_lshlrev_b32_e32 v172, 16, v132
	v_and_b32_e32 v173, 0xffff0000, v132
	v_max_f32_e32 v130, 0xda24260, v130
	v_pk_mul_f32 v[170:171], v[170:171], v[172:173]
	v_rcp_f32_e32 v172, v130
	v_max_f32_e32 v130, v177, v177
	v_max_f32_e32 v132, v175, v175
	v_lshlrev_b32_e32 v174, 16, v131
	v_and_b32_e32 v175, 0xffff0000, v131
	v_max_f32_e32 v131, v178, v178
	v_max_f32_e32 v130, 0xda24260, v130
	v_max_f32_e32 v131, 0xda24260, v131
	v_rcp_f32_e32 v130, v130
	v_rcp_f32_e32 v131, v131
	v_max_f32_e32 v132, 0xda24260, v132
	v_rcp_f32_e32 v173, v132
	v_lshlrev_b32_e32 v132, 16, v133
	v_and_b32_e32 v133, 0xffff0000, v133
	v_pk_mul_f32 v[130:131], v[130:131], v[132:133]
	v_pk_mul_f32 v[18:19], v[18:19], v[170:171]
	v_pk_mul_f32 v[20:21], v[20:21], v[130:131]
	global_load_dwordx4 v[130:133], v[158:159], off offset:256
	s_nop 0
	global_load_dwordx4 v[156:159], v[156:157], off offset:256
	v_pk_mul_f32 v[172:173], v[172:173], v[174:175]
	v_pk_mul_f32 v[22:23], v[22:23], v[168:169]
	v_pk_mul_f32 v[24:25], v[24:25], v[172:173]
	s_waitcnt vmcnt(0)
	v_lshlrev_b32_e32 v170, 16, v157
	v_and_b32_e32 v171, 0xffff0000, v157
	v_lshlrev_b32_e32 v157, 16, v158
	v_max_f32_e32 v157, v157, v157
	v_lshlrev_b32_e32 v168, 16, v156
	v_and_b32_e32 v169, 0xffff0000, v156
	v_max_f32_e32 v157, 0xda24260, v157
	v_and_b32_e32 v172, 0xffff0000, v158
	v_max_f32_e32 v156, v168, v168
	v_rcp_f32_e32 v158, v157
	v_max_f32_e32 v157, v169, v169
	v_max_f32_e32 v156, 0xda24260, v156
	v_max_f32_e32 v157, 0xda24260, v157
	v_lshlrev_b32_e32 v168, 16, v130
	v_and_b32_e32 v169, 0xffff0000, v130
	v_max_f32_e32 v130, v172, v172
	v_rcp_f32_e32 v156, v156
	v_rcp_f32_e32 v157, v157
	v_max_f32_e32 v130, 0xda24260, v130
	v_lshlrev_b32_e32 v173, 16, v159
	v_and_b32_e32 v174, 0xffff0000, v159
	v_rcp_f32_e32 v159, v130
	v_max_f32_e32 v130, v170, v170
	v_pk_mul_f32 v[156:157], v[156:157], v[168:169]
	v_lshlrev_b32_e32 v168, 16, v132
	v_and_b32_e32 v169, 0xffff0000, v132
	v_max_f32_e32 v130, 0xda24260, v130
	v_pk_mul_f32 v[158:159], v[158:159], v[168:169]
	v_rcp_f32_e32 v168, v130
	v_max_f32_e32 v130, v173, v173
	v_max_f32_e32 v132, v171, v171
	v_lshlrev_b32_e32 v170, 16, v131
	v_and_b32_e32 v171, 0xffff0000, v131
	v_max_f32_e32 v131, v174, v174
	v_max_f32_e32 v130, 0xda24260, v130
	v_max_f32_e32 v132, 0xda24260, v132
	v_max_f32_e32 v131, 0xda24260, v131
	v_rcp_f32_e32 v130, v130
	v_rcp_f32_e32 v169, v132
	v_rcp_f32_e32 v131, v131
	v_lshlrev_b32_e32 v132, 16, v133
	v_and_b32_e32 v133, 0xffff0000, v133
	v_pk_mul_f32 v[168:169], v[168:169], v[170:171]
	v_pk_mul_f32 v[130:131], v[130:131], v[132:133]
	v_pk_mul_f32 v[8:9], v[8:9], v[168:169]
	v_pk_mul_f32 v[6:7], v[6:7], v[156:157]
	v_pk_mul_f32 v[4:5], v[4:5], v[130:131]
	v_pk_mul_f32 v[2:3], v[2:3], v[158:159]
; #define PG8_STAGE(bufoff, gbase, voff) do { _Pragma("unroll") for (int _i = 0; _i < 2; ++_i) \
;         __builtin_amdgcn_global_load_lds((const unsigned*)((const char*)(gbase) + (voff)[_i]), (PG8_LAS unsigned*)(lds + (bufoff) + ldsw + _i * 8192), 16, 0, 0); } while (0)
; #define PG8_LDA(dst, b, h) do { _Pragma("unroll") for (int m = 0; m < 4; ++m) _Pragma("unroll") for (int k = 0; k < 2; ++k) dst[m][k] = *(const PG8_LAS bf16x8*)(lds + PG8_SA(b, h) + aoff + m * 2048 + k * 1024); } while (0)
; #define PG8_LDB(dst, b, h) do { _Pragma("unroll") for (int n = 0; n < 2; ++n) _Pragma("unroll") for (int k = 0; k < 2; ++k) dst[n][k] = *(const PG8_LAS bf16x8*)(lds + PG8_SB(b, h) + boff + n * 2048 + k * 1024); } while (0)
; #define PG8_MMA(ai, bj, At, Bt) do { __builtin_amdgcn_s_setprio(1); _Pragma("unroll") for (int m = 0; m < 4; ++m) _Pragma("unroll") for (int n = 0; n < 2; ++n) _Pragma("unroll") for (int k = 0; k < 2; ++k) \
;         acc[ai][bj][m][n] = __builtin_amdgcn_mfma_f32_16x16x32_bf16(Bt[n][k], At[m][k], acc[ai][bj][m][n], 0, 0, 0); __builtin_amdgcn_s_setprio(0); } while (0)
; #define PG8_WAIT_V(n) asm volatile("s_waitcnt vmcnt(" #n ")" ::: "memory")
; #define PG8_WAIT_L(n) asm volatile("s_waitcnt lgkmcnt(" #n ")" ::: "memory")
; #define PG8_BAR __builtin_amdgcn_s_barrier()
; #define PG8_SCHED __builtin_amdgcn_sched_barrier(0)
; template <class Epi, class Sched, bool ALIGN_EPI = false, bool SP2 = false>
; __device__ __forceinline__ void gemm_phase(PG8_LAS unsigned char* lds, const Gemm g, const Sched& S, const Epi& E) {
;     ...
;             PG8_LDB(B0, 0, 0); PG8_LDB(B1, 0, 1); PG8_SCHED; PG8_LDA(At, 0, 0); PG8_STAGE(PG8_SA(1, 1), a1 + hstep, voffA);
;             PG8_WAIT_V(8); PG8_WAIT_L(0); PG8_BAR; PG8_MMA(0, 0, At, B0); PG8_MMA(0, 1, At, B1); PG8_BAR; PG8_SCHED;
;             PG8_LDA(At, 0, 1); PG8_STAGE(PG8_SB(0, 0), b2, voffB); PG8_STAGE(PG8_SB(0, 1), b2 + hstep, voffB); PG8_STAGE(PG8_SA(0, 0), a2, voffA);
;             PG8_WAIT_V(8); PG8_WAIT_L(0); PG8_BAR; PG8_MMA(1, 0, At, B0); PG8_MMA(1, 1, At, B1); PG8_BAR; PG8_SCHED;
.LBB0_684:
	ds_read_b128 v[130:133], v163
	ds_read_b128 v[156:159], v163 offset:1024
	ds_read_b128 v[168:171], v163 offset:2048
	ds_read_b128 v[172:175], v163 offset:3072
	ds_read_b128 v[180:183], v164
	ds_read_b128 v[184:187], v164 offset:1024
	ds_read_b128 v[188:191], v164 offset:2048
	ds_read_b128 v[198:201], v164 offset:3072
	s_add_u32 s48, s50, 0x4000
	s_addc_u32 s49, s51, 0
	s_cmp_eq_u32 s56, 60
	s_cselect_b32 s72, s93, s48
	s_cselect_b32 s73, s41, s49
	s_cselect_b32 s70, s97, s26
	s_cselect_b32 s71, s27, s33
	s_add_u32 s48, s72, 0x8000
	s_addc_u32 s49, s73, 0
	s_mov_b32 m0, s83
	ds_read_b128 v[202:205], v165
	ds_read_b128 v[206:209], v165 offset:1024
	ds_read_b128 v[210:213], v165 offset:2048
	ds_read_b128 v[214:217], v165 offset:3072
	ds_read_b128 v[218:221], v165 offset:4096
	ds_read_b128 v[222:225], v165 offset:5120
	ds_read_b128 v[226:229], v165 offset:6144
	ds_read_b128 v[230:233], v165 offset:7168
	global_load_lds_dwordx4 v144, s[50:51]
	s_mov_b32 m0, s84
	s_nop 0
	global_load_lds_dwordx4 v146, s[50:51]
	s_waitcnt vmcnt(8)
	s_waitcnt lgkmcnt(0)
	s_barrier
	s_waitcnt lgkmcnt(0)
	v_mfma_f32_16x16x32_bf16 v[14:17], v[130:133], v[202:205], v[14:17]
	v_mfma_f32_16x16x32_bf16 v[14:17], v[156:159], v[206:209], v[14:17]
	v_mfma_f32_16x16x32_bf16 v[10:13], v[172:175], v[206:209], v[10:13]
	v_mfma_f32_16x16x32_bf16 v[10:13], v[168:171], v[202:205], v[10:13]
	v_mfma_f32_16x16x32_bf16 v[30:33], v[180:183], v[202:205], v[30:33]
	v_mfma_f32_16x16x32_bf16 v[30:33], v[184:187], v[206:209], v[30:33]
	v_mfma_f32_16x16x32_bf16 v[26:29], v[198:201], v[206:209], v[26:29]
	v_mfma_f32_16x16x32_bf16 v[26:29], v[188:191], v[202:205], v[26:29]
	v_mfma_f32_16x16x32_bf16 v[50:53], v[188:191], v[210:213], v[50:53]
	v_mfma_f32_16x16x32_bf16 v[50:53], v[198:201], v[214:217], v[50:53]
	v_mfma_f32_16x16x32_bf16 v[54:57], v[184:187], v[214:217], v[54:57]
	v_mfma_f32_16x16x32_bf16 v[54:57], v[180:183], v[210:213], v[54:57]
	v_mfma_f32_16x16x32_bf16 v[34:37], v[168:171], v[210:213], v[34:37]
	v_mfma_f32_16x16x32_bf16 v[34:37], v[172:175], v[214:217], v[34:37]
	v_mfma_f32_16x16x32_bf16 v[38:41], v[156:159], v[214:217], v[38:41]
	v_mfma_f32_16x16x32_bf16 v[38:41], v[130:133], v[210:213], v[38:41]
	v_mfma_f32_16x16x32_bf16 v[70:73], v[130:133], v[218:221], v[70:73]
	v_mfma_f32_16x16x32_bf16 v[70:73], v[156:159], v[222:225], v[70:73]
	v_mfma_f32_16x16x32_bf16 v[66:69], v[172:175], v[222:225], v[66:69]
	v_mfma_f32_16x16x32_bf16 v[66:69], v[168:171], v[218:221], v[66:69]
	v_mfma_f32_16x16x32_bf16 v[86:89], v[180:183], v[218:221], v[86:89]
	v_mfma_f32_16x16x32_bf16 v[86:89], v[184:187], v[222:225], v[86:89]
	v_mfma_f32_16x16x32_bf16 v[82:85], v[198:201], v[222:225], v[82:85]
	v_mfma_f32_16x16x32_bf16 v[82:85], v[188:191], v[218:221], v[82:85]
	v_mfma_f32_16x16x32_bf16 v[106:109], v[188:191], v[226:229], v[106:109]
	v_mfma_f32_16x16x32_bf16 v[106:109], v[198:201], v[230:233], v[106:109]
	v_mfma_f32_16x16x32_bf16 v[110:113], v[184:187], v[230:233], v[110:113]
	v_mfma_f32_16x16x32_bf16 v[110:113], v[180:183], v[226:229], v[110:113]
	v_mfma_f32_16x16x32_bf16 v[90:93], v[168:171], v[226:229], v[90:93]
	v_mfma_f32_16x16x32_bf16 v[90:93], v[172:175], v[230:233], v[90:93]
	v_mfma_f32_16x16x32_bf16 v[94:97], v[156:159], v[230:233], v[94:97]
	v_mfma_f32_16x16x32_bf16 v[94:97], v[130:133], v[226:229], v[94:97]
	s_barrier
	s_mov_b32 m0, s85
	s_add_u32 s58, s70, 0x4000
	ds_read_b128 v[202:205], v165 offset:16384
	ds_read_b128 v[206:209], v165 offset:17408
	ds_read_b128 v[210:213], v165 offset:18432
	ds_read_b128 v[214:217], v165 offset:19456
	ds_read_b128 v[218:221], v165 offset:20480
	ds_read_b128 v[222:225], v165 offset:21504
	ds_read_b128 v[226:229], v165 offset:22528
	ds_read_b128 v[230:233], v165 offset:23552
	global_load_lds_dwordx4 v136, s[70:71]
	s_mov_b32 m0, s86
	s_addc_u32 s59, s71, 0
	global_load_lds_dwordx4 v140, s[70:71]
	s_mov_b32 m0, s87
	s_nop 0
	global_load_lds_dwordx4 v136, s[58:59]
	s_mov_b32 m0, s88
	s_nop 0
	global_load_lds_dwordx4 v140, s[58:59]
	s_mov_b32 m0, s29
	s_nop 0
	global_load_lds_dwordx4 v134, s[72:73]
	s_mov_b32 m0, s30
	s_nop 0
	global_load_lds_dwordx4 v138, s[72:73]
	s_waitcnt vmcnt(8)
	s_waitcnt lgkmcnt(0)
	s_barrier
	s_waitcnt lgkmcnt(0)
	v_mfma_f32_16x16x32_bf16 v[126:129], v[130:133], v[202:205], v[126:129]
	v_mfma_f32_16x16x32_bf16 v[126:129], v[156:159], v[206:209], v[126:129]
	v_mfma_f32_16x16x32_bf16 v[122:125], v[172:175], v[206:209], v[122:125]
	v_mfma_f32_16x16x32_bf16 v[122:125], v[168:171], v[202:205], v[122:125]
	v_mfma_f32_16x16x32_bf16 v[118:121], v[180:183], v[202:205], v[118:121]
	v_mfma_f32_16x16x32_bf16 v[118:121], v[184:187], v[206:209], v[118:121]
	v_mfma_f32_16x16x32_bf16 v[114:117], v[198:201], v[206:209], v[114:117]
	v_mfma_f32_16x16x32_bf16 v[114:117], v[188:191], v[202:205], v[114:117]
	v_mfma_f32_16x16x32_bf16 v[74:77], v[188:191], v[210:213], v[74:77]
	v_mfma_f32_16x16x32_bf16 v[74:77], v[198:201], v[214:217], v[74:77]
	v_mfma_f32_16x16x32_bf16 v[78:81], v[184:187], v[214:217], v[78:81]
	v_mfma_f32_16x16x32_bf16 v[78:81], v[180:183], v[210:213], v[78:81]
	v_mfma_f32_16x16x32_bf16 v[98:101], v[168:171], v[210:213], v[98:101]
	v_mfma_f32_16x16x32_bf16 v[98:101], v[172:175], v[214:217], v[98:101]
	v_mfma_f32_16x16x32_bf16 v[102:105], v[156:159], v[214:217], v[102:105]
	v_mfma_f32_16x16x32_bf16 v[102:105], v[130:133], v[210:213], v[102:105]
	v_mfma_f32_16x16x32_bf16 v[62:65], v[130:133], v[218:221], v[62:65]
	v_mfma_f32_16x16x32_bf16 v[62:65], v[156:159], v[222:225], v[62:65]
	v_mfma_f32_16x16x32_bf16 v[58:61], v[172:175], v[222:225], v[58:61]
	v_mfma_f32_16x16x32_bf16 v[58:61], v[168:171], v[218:221], v[58:61]
	v_mfma_f32_16x16x32_bf16 v[46:49], v[180:183], v[218:221], v[46:49]
	v_mfma_f32_16x16x32_bf16 v[46:49], v[184:187], v[222:225], v[46:49]
	v_mfma_f32_16x16x32_bf16 v[42:45], v[198:201], v[222:225], v[42:45]
	v_mfma_f32_16x16x32_bf16 v[42:45], v[188:191], v[218:221], v[42:45]
	v_mfma_f32_16x16x32_bf16 v[2:5], v[188:191], v[226:229], v[2:5]
	v_mfma_f32_16x16x32_bf16 v[2:5], v[198:201], v[230:233], v[2:5]
	v_mfma_f32_16x16x32_bf16 v[6:9], v[184:187], v[230:233], v[6:9]
	v_mfma_f32_16x16x32_bf16 v[6:9], v[180:183], v[226:229], v[6:9]
	v_mfma_f32_16x16x32_bf16 v[18:21], v[168:171], v[226:229], v[18:21]
	v_mfma_f32_16x16x32_bf16 v[18:21], v[172:175], v[230:233], v[18:21]
	v_mfma_f32_16x16x32_bf16 v[22:25], v[156:159], v[230:233], v[22:25]
	v_mfma_f32_16x16x32_bf16 v[22:25], v[130:133], v[226:229], v[22:25]
	s_barrier
; #define PG8_STAGE(bufoff, gbase, voff) do { _Pragma("unroll") for (int _i = 0; _i < 2; ++_i) \
;         __builtin_amdgcn_global_load_lds((const unsigned*)((const char*)(gbase) + (voff)[_i]), (PG8_LAS unsigned*)(lds + (bufoff) + ldsw + _i * 8192), 16, 0, 0); } while (0)
; #define PG8_LDA(dst, b, h) do { _Pragma("unroll") for (int m = 0; m < 4; ++m) _Pragma("unroll") for (int k = 0; k < 2; ++k) dst[m][k] = *(const PG8_LAS bf16x8*)(lds + PG8_SA(b, h) + aoff + m * 2048 + k * 1024); } while (0)
; #define PG8_LDB(dst, b, h) do { _Pragma("unroll") for (int n = 0; n < 2; ++n) _Pragma("unroll") for (int k = 0; k < 2; ++k) dst[n][k] = *(const PG8_LAS bf16x8*)(lds + PG8_SB(b, h) + boff + n * 2048 + k * 1024); } while (0)
; #define PG8_MMA(ai, bj, At, Bt) do { __builtin_amdgcn_s_setprio(1); _Pragma("unroll") for (int m = 0; m < 4; ++m) _Pragma("unroll") for (int n = 0; n < 2; ++n) _Pragma("unroll") for (int k = 0; k < 2; ++k) \
;         acc[ai][bj][m][n] = __builtin_amdgcn_mfma_f32_16x16x32_bf16(Bt[n][k], At[m][k], acc[ai][bj][m][n], 0, 0, 0); __builtin_amdgcn_s_setprio(0); } while (0)
; #define PG8_WAIT_V(n) asm volatile("s_waitcnt vmcnt(" #n ")" ::: "memory")
; #define PG8_WAIT_L(n) asm volatile("s_waitcnt lgkmcnt(" #n ")" ::: "memory")
; #define PG8_BAR __builtin_amdgcn_s_barrier()
; #define PG8_SCHED __builtin_amdgcn_sched_barrier(0)
; template <class Epi, class Sched, bool ALIGN_EPI = false, bool SP2 = false>
; __device__ __forceinline__ void gemm_phase(PG8_LAS unsigned char* lds, const Gemm g, const Sched& S, const Epi& E) {
;     ...
;             PG8_LDB(B0, 1, 0); PG8_LDB(B1, 1, 1); PG8_SCHED; PG8_LDA(At, 1, 0); PG8_STAGE(PG8_SA(0, 1), a2 + hstep, voffA);
;             PG8_WAIT_V(8); PG8_WAIT_L(0); PG8_BAR; PG8_MMA(0, 0, At, B0); PG8_MMA(0, 1, At, B1); PG8_BAR; PG8_SCHED;
;             PG8_LDA(At, 1, 1); PG8_STAGE(PG8_SB(1, 0), b3, voffB); PG8_STAGE(PG8_SB(1, 1), b3 + hstep, voffB); PG8_STAGE(PG8_SA(1, 0), a3, voffA);
;             PG8_WAIT_V(8); PG8_WAIT_L(0); PG8_BAR; PG8_MMA(1, 0, At, B0); PG8_MMA(1, 1, At, B1); PG8_BAR; PG8_SCHED;
	ds_read_b128 v[130:133], v142
	ds_read_b128 v[156:159], v142 offset:1024
	ds_read_b128 v[168:171], v142 offset:2048
	ds_read_b128 v[172:175], v142 offset:3072
	ds_read_b128 v[180:183], v167
	ds_read_b128 v[184:187], v167 offset:1024
	ds_read_b128 v[188:191], v167 offset:2048
	ds_read_b128 v[198:201], v167 offset:3072
	s_add_u32 s58, s72, 0x4000
	s_addc_u32 s59, s73, 0
	s_mov_b32 m0, s31
	ds_read_b128 v[202:205], v165 offset:32768
	ds_read_b128 v[206:209], v165 offset:33792
	ds_read_b128 v[210:213], v165 offset:34816
	ds_read_b128 v[214:217], v165 offset:35840
	ds_read_b128 v[218:221], v165 offset:36864
	ds_read_b128 v[222:225], v165 offset:37888
	ds_read_b128 v[226:229], v165 offset:38912
	ds_read_b128 v[230:233], v165 offset:39936
	global_load_lds_dwordx4 v134, s[58:59]
	s_mov_b32 m0, s35
	s_nop 0
	global_load_lds_dwordx4 v138, s[58:59]
	s_waitcnt vmcnt(8)
	s_waitcnt lgkmcnt(0)
	s_barrier
	s_waitcnt lgkmcnt(0)
	v_mfma_f32_16x16x32_bf16 v[14:17], v[130:133], v[202:205], v[14:17]
	v_mfma_f32_16x16x32_bf16 v[14:17], v[156:159], v[206:209], v[14:17]
	v_mfma_f32_16x16x32_bf16 v[10:13], v[172:175], v[206:209], v[10:13]
	v_mfma_f32_16x16x32_bf16 v[10:13], v[168:171], v[202:205], v[10:13]
	v_mfma_f32_16x16x32_bf16 v[30:33], v[180:183], v[202:205], v[30:33]
	v_mfma_f32_16x16x32_bf16 v[30:33], v[184:187], v[206:209], v[30:33]
	v_mfma_f32_16x16x32_bf16 v[26:29], v[198:201], v[206:209], v[26:29]
	v_mfma_f32_16x16x32_bf16 v[26:29], v[188:191], v[202:205], v[26:29]
	v_mfma_f32_16x16x32_bf16 v[50:53], v[188:191], v[210:213], v[50:53]
	v_mfma_f32_16x16x32_bf16 v[50:53], v[198:201], v[214:217], v[50:53]
	v_mfma_f32_16x16x32_bf16 v[54:57], v[184:187], v[214:217], v[54:57]
	v_mfma_f32_16x16x32_bf16 v[54:57], v[180:183], v[210:213], v[54:57]
	v_mfma_f32_16x16x32_bf16 v[34:37], v[168:171], v[210:213], v[34:37]
	v_mfma_f32_16x16x32_bf16 v[34:37], v[172:175], v[214:217], v[34:37]
	v_mfma_f32_16x16x32_bf16 v[38:41], v[156:159], v[214:217], v[38:41]
	v_mfma_f32_16x16x32_bf16 v[38:41], v[130:133], v[210:213], v[38:41]
	v_mfma_f32_16x16x32_bf16 v[70:73], v[130:133], v[218:221], v[70:73]
	v_mfma_f32_16x16x32_bf16 v[70:73], v[156:159], v[222:225], v[70:73]
	v_mfma_f32_16x16x32_bf16 v[66:69], v[172:175], v[222:225], v[66:69]
	v_mfma_f32_16x16x32_bf16 v[66:69], v[168:171], v[218:221], v[66:69]
	v_mfma_f32_16x16x32_bf16 v[86:89], v[180:183], v[218:221], v[86:89]
	v_mfma_f32_16x16x32_bf16 v[86:89], v[184:187], v[222:225], v[86:89]
	v_mfma_f32_16x16x32_bf16 v[82:85], v[198:201], v[222:225], v[82:85]
	v_mfma_f32_16x16x32_bf16 v[82:85], v[188:191], v[218:221], v[82:85]
	v_mfma_f32_16x16x32_bf16 v[106:109], v[188:191], v[226:229], v[106:109]
	v_mfma_f32_16x16x32_bf16 v[106:109], v[198:201], v[230:233], v[106:109]
	v_mfma_f32_16x16x32_bf16 v[110:113], v[184:187], v[230:233], v[110:113]
	v_mfma_f32_16x16x32_bf16 v[110:113], v[180:183], v[226:229], v[110:113]
	v_mfma_f32_16x16x32_bf16 v[90:93], v[168:171], v[226:229], v[90:93]
	v_mfma_f32_16x16x32_bf16 v[90:93], v[172:175], v[230:233], v[90:93]
	v_mfma_f32_16x16x32_bf16 v[94:97], v[156:159], v[230:233], v[94:97]
	v_mfma_f32_16x16x32_bf16 v[94:97], v[130:133], v[226:229], v[94:97]
	s_barrier
	s_add_u32 s58, s70, 0x8000
	s_addc_u32 s59, s71, 0
	s_mov_b32 m0, s89
	ds_read_b128 v[202:205], v165 offset:49152
	ds_read_b128 v[206:209], v165 offset:50176
	ds_read_b128 v[210:213], v165 offset:51200
	ds_read_b128 v[214:217], v165 offset:52224
	ds_read_b128 v[218:221], v165 offset:53248
	ds_read_b128 v[222:225], v165 offset:54272
	ds_read_b128 v[226:229], v165 offset:55296
	ds_read_b128 v[230:233], v165 offset:56320
	global_load_lds_dwordx4 v136, s[58:59]
	v_lshl_add_u64 v[176:177], s[58:59], 0, v[140:141]
	s_add_u32 s58, s70, 0xc000
	s_mov_b32 m0, s90
	s_addc_u32 s59, s71, 0
	global_load_lds_dwordx4 v[176:177], off
	s_mov_b32 m0, s91
	s_nop 0
	global_load_lds_dwordx4 v136, s[58:59]
	s_mov_b32 m0, s92
	s_nop 0
	global_load_lds_dwordx4 v140, s[58:59]
	s_mov_b32 m0, s75
	s_nop 0
	global_load_lds_dwordx4 v134, s[48:49]
	s_mov_b32 m0, s76
	s_nop 0
	global_load_lds_dwordx4 v138, s[48:49]
	s_waitcnt vmcnt(8)
	s_waitcnt lgkmcnt(0)
	s_barrier
	s_waitcnt lgkmcnt(0)
	v_mfma_f32_16x16x32_bf16 v[126:129], v[130:133], v[202:205], v[126:129]
	v_mfma_f32_16x16x32_bf16 v[126:129], v[156:159], v[206:209], v[126:129]
	v_mfma_f32_16x16x32_bf16 v[122:125], v[172:175], v[206:209], v[122:125]
	v_mfma_f32_16x16x32_bf16 v[122:125], v[168:171], v[202:205], v[122:125]
	v_mfma_f32_16x16x32_bf16 v[118:121], v[180:183], v[202:205], v[118:121]
	v_mfma_f32_16x16x32_bf16 v[118:121], v[184:187], v[206:209], v[118:121]
	v_mfma_f32_16x16x32_bf16 v[114:117], v[198:201], v[206:209], v[114:117]
	v_mfma_f32_16x16x32_bf16 v[114:117], v[188:191], v[202:205], v[114:117]
	v_mfma_f32_16x16x32_bf16 v[74:77], v[188:191], v[210:213], v[74:77]
	v_mfma_f32_16x16x32_bf16 v[74:77], v[198:201], v[214:217], v[74:77]
	v_mfma_f32_16x16x32_bf16 v[78:81], v[184:187], v[214:217], v[78:81]
	v_mfma_f32_16x16x32_bf16 v[78:81], v[180:183], v[210:213], v[78:81]
	v_mfma_f32_16x16x32_bf16 v[98:101], v[168:171], v[210:213], v[98:101]
	v_mfma_f32_16x16x32_bf16 v[98:101], v[172:175], v[214:217], v[98:101]
	v_mfma_f32_16x16x32_bf16 v[102:105], v[156:159], v[214:217], v[102:105]
	v_mfma_f32_16x16x32_bf16 v[102:105], v[130:133], v[210:213], v[102:105]
	v_mfma_f32_16x16x32_bf16 v[62:65], v[130:133], v[218:221], v[62:65]
	v_mfma_f32_16x16x32_bf16 v[62:65], v[156:159], v[222:225], v[62:65]
	v_mfma_f32_16x16x32_bf16 v[58:61], v[172:175], v[222:225], v[58:61]
	v_mfma_f32_16x16x32_bf16 v[58:61], v[168:171], v[218:221], v[58:61]
	v_mfma_f32_16x16x32_bf16 v[46:49], v[180:183], v[218:221], v[46:49]
	v_mfma_f32_16x16x32_bf16 v[46:49], v[184:187], v[222:225], v[46:49]
	v_mfma_f32_16x16x32_bf16 v[42:45], v[198:201], v[222:225], v[42:45]
	v_mfma_f32_16x16x32_bf16 v[42:45], v[188:191], v[218:221], v[42:45]
	v_mfma_f32_16x16x32_bf16 v[2:5], v[188:191], v[226:229], v[2:5]
	v_mfma_f32_16x16x32_bf16 v[2:5], v[198:201], v[230:233], v[2:5]
	v_mfma_f32_16x16x32_bf16 v[6:9], v[184:187], v[230:233], v[6:9]
	v_mfma_f32_16x16x32_bf16 v[6:9], v[180:183], v[226:229], v[6:9]
	v_mfma_f32_16x16x32_bf16 v[18:21], v[168:171], v[226:229], v[18:21]
	v_mfma_f32_16x16x32_bf16 v[18:21], v[172:175], v[230:233], v[18:21]
	v_mfma_f32_16x16x32_bf16 v[22:25], v[156:159], v[230:233], v[22:25]
	v_mfma_f32_16x16x32_bf16 v[22:25], v[130:133], v[226:229], v[22:25]
	s_barrier
	s_add_i32 s56, s56, 2
	s_add_u32 s50, s50, 0x10000
	s_addc_u32 s51, s51, 0
	s_add_u32 s26, s26, 0x10000
	s_addc_u32 s33, s33, 0
	s_cmp_lt_u32 s56, 62
	s_cbranch_scc1 .LBB0_684
	s_andn2_b64 vcc, exec, s[12:13]
	s_cbranch_vccnz .LBB0_687
	s_barrier

; #define PG8_STAGE(bufoff, gbase, voff) do { _Pragma("unroll") for (int _i = 0; _i < 2; ++_i) \
;         __builtin_amdgcn_global_load_lds((const unsigned*)((const char*)(gbase) + (voff)[_i]), (PG8_LAS unsigned*)(lds + (bufoff) + ldsw + _i * 8192), 16, 0, 0); } while (0)
; #define PG8_LDA(dst, b, h) do { _Pragma("unroll") for (int m = 0; m < 4; ++m) _Pragma("unroll") for (int k = 0; k < 2; ++k) dst[m][k] = *(const PG8_LAS bf16x8*)(lds + PG8_SA(b, h) + aoff + m * 2048 + k * 1024); } while (0)
; #define PG8_LDB(dst, b, h) do { _Pragma("unroll") for (int n = 0; n < 2; ++n) _Pragma("unroll") for (int k = 0; k < 2; ++k) dst[n][k] = *(const PG8_LAS bf16x8*)(lds + PG8_SB(b, h) + boff + n * 2048 + k * 1024); } while (0)
; #define PG8_MMA(ai, bj, At, Bt) do { __builtin_amdgcn_s_setprio(1); _Pragma("unroll") for (int m = 0; m < 4; ++m) _Pragma("unroll") for (int n = 0; n < 2; ++n) _Pragma("unroll") for (int k = 0; k < 2; ++k) \
;         acc[ai][bj][m][n] = __builtin_amdgcn_mfma_f32_16x16x32_bf16(Bt[n][k], At[m][k], acc[ai][bj][m][n], 0, 0, 0); __builtin_amdgcn_s_setprio(0); } while (0)
; #define PG8_WAIT_V(n) asm volatile("s_waitcnt vmcnt(" #n ")" ::: "memory")
; #define PG8_WAIT_L(n) asm volatile("s_waitcnt lgkmcnt(" #n ")" ::: "memory")
; #define PG8_BAR __builtin_amdgcn_s_barrier()
; #define PG8_SCHED __builtin_amdgcn_sched_barrier(0)
; template <class Epi, class Sched, bool ALIGN_EPI = false, bool SP2 = false>
; __device__ __forceinline__ void gemm_phase(PG8_LAS unsigned char* lds, const Gemm g, const Sched& S, const Epi& E) {
;     ...
;             PG8_LDB(B0, 0, 0); PG8_LDB(B1, 0, 1); PG8_SCHED; PG8_LDA(At, 0, 0); PG8_STAGE(PG8_SA(1, 1), a1 + hstep, voffA);
;             PG8_WAIT_V(8); PG8_WAIT_L(0); PG8_BAR; PG8_MMA(0, 0, At, B0); PG8_MMA(0, 1, At, B1); PG8_BAR; PG8_SCHED;
;             PG8_LDA(At, 0, 1); PG8_STAGE(PG8_SB(0, 0), b2, voffB); PG8_STAGE(PG8_SB(0, 1), b2 + hstep, voffB); PG8_STAGE(PG8_SA(0, 0), a2, voffA);
;             PG8_WAIT_V(8); PG8_WAIT_L(0); PG8_BAR; PG8_MMA(1, 0, At, B0); PG8_MMA(1, 1, At, B1); PG8_BAR; PG8_SCHED;
.LBB0_757:
	ds_read_b128 v[154:157], v149
	ds_read_b128 v[158:161], v149 offset:1024
	ds_read_b128 v[162:165], v149 offset:2048
	ds_read_b128 v[166:169], v149 offset:3072
	ds_read_b128 v[170:173], v150
	ds_read_b128 v[174:177], v150 offset:1024
	ds_read_b128 v[180:183], v150 offset:2048
	ds_read_b128 v[184:187], v150 offset:3072
	s_add_u32 s46, s44, 0x4000
	s_addc_u32 s47, s45, 0
	s_cmp_eq_u32 s70, 60
	s_cselect_b32 s50, s39, s46
	s_cselect_b32 s51, s17, s47
	s_cselect_b32 s48, s41, s68
	s_cselect_b32 s49, s15, s69
	s_add_u32 s46, s50, 0x8000
	s_addc_u32 s47, s51, 0
	s_sub_u32 s46, s44, 0x4000
	s_subb_u32 s47, s45, 0
	s_mov_b32 m0, s57
	s_nop 0
	global_load_lds_dwordx4 v130, s[46:47]
	s_mov_b32 m0, s58
	s_nop 0
	global_load_lds_dwordx4 v134, s[46:47]
	s_add_i32 m0, s26, 0xc000
	ds_read_b128 v[188:191], v151
	ds_read_b128 v[198:201], v151 offset:1024
	ds_read_b128 v[202:205], v151 offset:2048
	ds_read_b128 v[206:209], v151 offset:3072
	ds_read_b128 v[210:213], v151 offset:4096
	ds_read_b128 v[214:217], v151 offset:5120
	ds_read_b128 v[218:221], v151 offset:6144
	ds_read_b128 v[222:225], v151 offset:7168
	global_load_lds_dwordx4 v138, s[44:45]
	s_add_i32 m0, s26, 0xe000
	s_nop 0
	global_load_lds_dwordx4 v140, s[44:45]
	s_waitcnt vmcnt(8)
	s_waitcnt lgkmcnt(0)
	s_barrier
	s_waitcnt lgkmcnt(0)
	v_mfma_f32_16x16x32_bf16 v[126:129], v[154:157], v[188:191], v[126:129]
	v_mfma_f32_16x16x32_bf16 v[126:129], v[158:161], v[198:201], v[126:129]
	v_mfma_f32_16x16x32_bf16 v[122:125], v[166:169], v[198:201], v[122:125]
	v_mfma_f32_16x16x32_bf16 v[122:125], v[162:165], v[188:191], v[122:125]
	v_mfma_f32_16x16x32_bf16 v[118:121], v[170:173], v[188:191], v[118:121]
	v_mfma_f32_16x16x32_bf16 v[118:121], v[174:177], v[198:201], v[118:121]
	v_mfma_f32_16x16x32_bf16 v[114:117], v[184:187], v[198:201], v[114:117]
	v_mfma_f32_16x16x32_bf16 v[114:117], v[180:183], v[188:191], v[114:117]
	v_mfma_f32_16x16x32_bf16 v[98:101], v[180:183], v[202:205], v[98:101]
	v_mfma_f32_16x16x32_bf16 v[98:101], v[184:187], v[206:209], v[98:101]
	v_mfma_f32_16x16x32_bf16 v[102:105], v[174:177], v[206:209], v[102:105]
	v_mfma_f32_16x16x32_bf16 v[102:105], v[170:173], v[202:205], v[102:105]
	v_mfma_f32_16x16x32_bf16 v[106:109], v[162:165], v[202:205], v[106:109]
	v_mfma_f32_16x16x32_bf16 v[106:109], v[166:169], v[206:209], v[106:109]
	v_mfma_f32_16x16x32_bf16 v[110:113], v[158:161], v[206:209], v[110:113]
	v_mfma_f32_16x16x32_bf16 v[110:113], v[154:157], v[202:205], v[110:113]
	v_mfma_f32_16x16x32_bf16 v[94:97], v[154:157], v[210:213], v[94:97]
	v_mfma_f32_16x16x32_bf16 v[94:97], v[158:161], v[214:217], v[94:97]
	v_mfma_f32_16x16x32_bf16 v[90:93], v[166:169], v[214:217], v[90:93]
	v_mfma_f32_16x16x32_bf16 v[90:93], v[162:165], v[210:213], v[90:93]
	v_mfma_f32_16x16x32_bf16 v[86:89], v[170:173], v[210:213], v[86:89]
	v_mfma_f32_16x16x32_bf16 v[86:89], v[174:177], v[214:217], v[86:89]
	v_mfma_f32_16x16x32_bf16 v[82:85], v[184:187], v[214:217], v[82:85]
	v_mfma_f32_16x16x32_bf16 v[82:85], v[180:183], v[210:213], v[82:85]
	v_mfma_f32_16x16x32_bf16 v[66:69], v[180:183], v[218:221], v[66:69]
	v_mfma_f32_16x16x32_bf16 v[66:69], v[184:187], v[222:225], v[66:69]
	v_mfma_f32_16x16x32_bf16 v[70:73], v[174:177], v[222:225], v[70:73]
	v_mfma_f32_16x16x32_bf16 v[70:73], v[170:173], v[218:221], v[70:73]
	v_mfma_f32_16x16x32_bf16 v[74:77], v[162:165], v[218:221], v[74:77]
	v_mfma_f32_16x16x32_bf16 v[74:77], v[166:169], v[222:225], v[74:77]
	v_mfma_f32_16x16x32_bf16 v[78:81], v[158:161], v[222:225], v[78:81]
	v_mfma_f32_16x16x32_bf16 v[78:81], v[154:157], v[218:221], v[78:81]
	s_barrier
	s_add_i32 s71, s59, s3
	s_mov_b32 m0, s71
	ds_read_b128 v[188:191], v151 offset:16384
	ds_read_b128 v[198:201], v151 offset:17408
	ds_read_b128 v[202:205], v151 offset:18432
	ds_read_b128 v[206:209], v151 offset:19456
	ds_read_b128 v[210:213], v151 offset:20480
	ds_read_b128 v[214:217], v151 offset:21504
	ds_read_b128 v[218:221], v151 offset:22528
	ds_read_b128 v[222:225], v151 offset:23552
	global_load_lds_dwordx4 v132, s[48:49]
	s_add_i32 m0, s71, 0x2000
	s_add_u32 s72, s48, 0x4000
	s_addc_u32 s73, s49, 0
	s_add_i32 s71, s61, s3
	global_load_lds_dwordx4 v136, s[48:49]
	s_mov_b32 m0, s71
	s_nop 0
	global_load_lds_dwordx4 v132, s[72:73]
	s_add_i32 m0, s71, 0x2000
	s_nop 0
	global_load_lds_dwordx4 v136, s[72:73]
	s_waitcnt vmcnt(6)
	s_waitcnt lgkmcnt(0)
	s_barrier
	s_waitcnt lgkmcnt(0)
	v_mfma_f32_16x16x32_bf16 v[62:65], v[154:157], v[188:191], v[62:65]
	v_mfma_f32_16x16x32_bf16 v[62:65], v[158:161], v[198:201], v[62:65]
	v_mfma_f32_16x16x32_bf16 v[58:61], v[166:169], v[198:201], v[58:61]
	v_mfma_f32_16x16x32_bf16 v[58:61], v[162:165], v[188:191], v[58:61]
	v_mfma_f32_16x16x32_bf16 v[54:57], v[170:173], v[188:191], v[54:57]
	v_mfma_f32_16x16x32_bf16 v[54:57], v[174:177], v[198:201], v[54:57]
	v_mfma_f32_16x16x32_bf16 v[50:53], v[184:187], v[198:201], v[50:53]
	v_mfma_f32_16x16x32_bf16 v[50:53], v[180:183], v[188:191], v[50:53]
	v_mfma_f32_16x16x32_bf16 v[34:37], v[180:183], v[202:205], v[34:37]
	v_mfma_f32_16x16x32_bf16 v[34:37], v[184:187], v[206:209], v[34:37]
	v_mfma_f32_16x16x32_bf16 v[38:41], v[174:177], v[206:209], v[38:41]
	v_mfma_f32_16x16x32_bf16 v[38:41], v[170:173], v[202:205], v[38:41]
	v_mfma_f32_16x16x32_bf16 v[42:45], v[162:165], v[202:205], v[42:45]
	v_mfma_f32_16x16x32_bf16 v[42:45], v[166:169], v[206:209], v[42:45]
	v_mfma_f32_16x16x32_bf16 v[46:49], v[158:161], v[206:209], v[46:49]
	v_mfma_f32_16x16x32_bf16 v[46:49], v[154:157], v[202:205], v[46:49]
	v_mfma_f32_16x16x32_bf16 v[30:33], v[154:157], v[210:213], v[30:33]
	v_mfma_f32_16x16x32_bf16 v[30:33], v[158:161], v[214:217], v[30:33]
	v_mfma_f32_16x16x32_bf16 v[26:29], v[166:169], v[214:217], v[26:29]
	v_mfma_f32_16x16x32_bf16 v[26:29], v[162:165], v[210:213], v[26:29]
	v_mfma_f32_16x16x32_bf16 v[22:25], v[170:173], v[210:213], v[22:25]
	v_mfma_f32_16x16x32_bf16 v[22:25], v[174:177], v[214:217], v[22:25]
	v_mfma_f32_16x16x32_bf16 v[18:21], v[184:187], v[214:217], v[18:21]
	v_mfma_f32_16x16x32_bf16 v[18:21], v[180:183], v[210:213], v[18:21]
	v_mfma_f32_16x16x32_bf16 v[2:5], v[180:183], v[218:221], v[2:5]
	v_mfma_f32_16x16x32_bf16 v[2:5], v[184:187], v[222:225], v[2:5]
	v_mfma_f32_16x16x32_bf16 v[6:9], v[174:177], v[222:225], v[6:9]
	v_mfma_f32_16x16x32_bf16 v[6:9], v[170:173], v[218:221], v[6:9]
	v_mfma_f32_16x16x32_bf16 v[10:13], v[162:165], v[218:221], v[10:13]
	v_mfma_f32_16x16x32_bf16 v[10:13], v[166:169], v[222:225], v[10:13]
	v_mfma_f32_16x16x32_bf16 v[14:17], v[158:161], v[222:225], v[14:17]
	v_mfma_f32_16x16x32_bf16 v[14:17], v[154:157], v[218:221], v[14:17]
	s_barrier
; #define PG8_STAGE(bufoff, gbase, voff) do { _Pragma("unroll") for (int _i = 0; _i < 2; ++_i) \
;         __builtin_amdgcn_global_load_lds((const unsigned*)((const char*)(gbase) + (voff)[_i]), (PG8_LAS unsigned*)(lds + (bufoff) + ldsw + _i * 8192), 16, 0, 0); } while (0)
; #define PG8_LDA(dst, b, h) do { _Pragma("unroll") for (int m = 0; m < 4; ++m) _Pragma("unroll") for (int k = 0; k < 2; ++k) dst[m][k] = *(const PG8_LAS bf16x8*)(lds + PG8_SA(b, h) + aoff + m * 2048 + k * 1024); } while (0)
; #define PG8_LDB(dst, b, h) do { _Pragma("unroll") for (int n = 0; n < 2; ++n) _Pragma("unroll") for (int k = 0; k < 2; ++k) dst[n][k] = *(const PG8_LAS bf16x8*)(lds + PG8_SB(b, h) + boff + n * 2048 + k * 1024); } while (0)
; #define PG8_MMA(ai, bj, At, Bt) do { __builtin_amdgcn_s_setprio(1); _Pragma("unroll") for (int m = 0; m < 4; ++m) _Pragma("unroll") for (int n = 0; n < 2; ++n) _Pragma("unroll") for (int k = 0; k < 2; ++k) \
;         acc[ai][bj][m][n] = __builtin_amdgcn_mfma_f32_16x16x32_bf16(Bt[n][k], At[m][k], acc[ai][bj][m][n], 0, 0, 0); __builtin_amdgcn_s_setprio(0); } while (0)
; #define PG8_WAIT_V(n) asm volatile("s_waitcnt vmcnt(" #n ")" ::: "memory")
; #define PG8_WAIT_L(n) asm volatile("s_waitcnt lgkmcnt(" #n ")" ::: "memory")
; #define PG8_BAR __builtin_amdgcn_s_barrier()
; #define PG8_SCHED __builtin_amdgcn_sched_barrier(0)
; template <class Epi, class Sched, bool ALIGN_EPI = false, bool SP2 = false>
; __device__ __forceinline__ void gemm_phase(PG8_LAS unsigned char* lds, const Gemm g, const Sched& S, const Epi& E) {
;     ...
;             PG8_LDB(B0, 1, 0); PG8_LDB(B1, 1, 1); PG8_SCHED; PG8_LDA(At, 1, 0); PG8_STAGE(PG8_SA(0, 1), a2 + hstep, voffA);
;             PG8_WAIT_V(8); PG8_WAIT_L(0); PG8_BAR; PG8_MMA(0, 0, At, B0); PG8_MMA(0, 1, At, B1); PG8_BAR; PG8_SCHED;
;             PG8_LDA(At, 1, 1); PG8_STAGE(PG8_SB(1, 0), b3, voffB); PG8_STAGE(PG8_SB(1, 1), b3 + hstep, voffB); PG8_STAGE(PG8_SA(1, 0), a3, voffA);
;             PG8_WAIT_V(8); PG8_WAIT_L(0); PG8_BAR; PG8_MMA(1, 0, At, B0); PG8_MMA(1, 1, At, B1); PG8_BAR; PG8_SCHED;
	s_add_i32 s71, 0, 0x18000
	v_add_u32_e32 v146, s71, v1
	s_add_i32 s72, 0, 0x1c000
	ds_read_b128 v[154:157], v146
	ds_read_b128 v[158:161], v146 offset:1024
	ds_read_b128 v[162:165], v146 offset:2048
	ds_read_b128 v[166:169], v146 offset:3072
	v_add_u32_e32 v146, s72, v1
	ds_read_b128 v[170:173], v146
	ds_read_b128 v[174:177], v146 offset:1024
	ds_read_b128 v[180:183], v146 offset:2048
	ds_read_b128 v[184:187], v146 offset:3072
	s_mov_b32 m0, s26
	s_nop 0
	global_load_lds_dwordx4 v130, s[50:51]
	s_mov_b32 m0, s27
	s_nop 0
	global_load_lds_dwordx4 v134, s[50:51]
	s_add_u32 s50, s50, 0x4000
	s_addc_u32 s51, s51, 0
	s_mov_b32 m0, s28
	ds_read_b128 v[188:191], v151 offset:32768
	ds_read_b128 v[198:201], v151 offset:33792
	ds_read_b128 v[202:205], v151 offset:34816
	ds_read_b128 v[206:209], v151 offset:35840
	ds_read_b128 v[210:213], v151 offset:36864
	ds_read_b128 v[214:217], v151 offset:37888
	ds_read_b128 v[218:221], v151 offset:38912
	ds_read_b128 v[222:225], v151 offset:39936
	global_load_lds_dwordx4 v130, s[50:51]
	s_mov_b32 m0, s29
	s_nop 0
	global_load_lds_dwordx4 v134, s[50:51]
	s_waitcnt vmcnt(8)
	s_waitcnt lgkmcnt(0)
	s_barrier
	s_waitcnt lgkmcnt(0)
	v_mfma_f32_16x16x32_bf16 v[126:129], v[154:157], v[188:191], v[126:129]
	v_mfma_f32_16x16x32_bf16 v[126:129], v[158:161], v[198:201], v[126:129]
	v_mfma_f32_16x16x32_bf16 v[122:125], v[166:169], v[198:201], v[122:125]
	v_mfma_f32_16x16x32_bf16 v[122:125], v[162:165], v[188:191], v[122:125]
	v_mfma_f32_16x16x32_bf16 v[118:121], v[170:173], v[188:191], v[118:121]
	v_mfma_f32_16x16x32_bf16 v[118:121], v[174:177], v[198:201], v[118:121]
	v_mfma_f32_16x16x32_bf16 v[114:117], v[184:187], v[198:201], v[114:117]
	v_mfma_f32_16x16x32_bf16 v[114:117], v[180:183], v[188:191], v[114:117]
	v_mfma_f32_16x16x32_bf16 v[98:101], v[180:183], v[202:205], v[98:101]
	v_mfma_f32_16x16x32_bf16 v[98:101], v[184:187], v[206:209], v[98:101]
	v_mfma_f32_16x16x32_bf16 v[102:105], v[174:177], v[206:209], v[102:105]
	v_mfma_f32_16x16x32_bf16 v[102:105], v[170:173], v[202:205], v[102:105]
	v_mfma_f32_16x16x32_bf16 v[106:109], v[162:165], v[202:205], v[106:109]
	v_mfma_f32_16x16x32_bf16 v[106:109], v[166:169], v[206:209], v[106:109]
	v_mfma_f32_16x16x32_bf16 v[110:113], v[158:161], v[206:209], v[110:113]
	v_mfma_f32_16x16x32_bf16 v[110:113], v[154:157], v[202:205], v[110:113]
	v_mfma_f32_16x16x32_bf16 v[94:97], v[154:157], v[210:213], v[94:97]
	v_mfma_f32_16x16x32_bf16 v[94:97], v[158:161], v[214:217], v[94:97]
	v_mfma_f32_16x16x32_bf16 v[90:93], v[166:169], v[214:217], v[90:93]
	v_mfma_f32_16x16x32_bf16 v[90:93], v[162:165], v[210:213], v[90:93]
	v_mfma_f32_16x16x32_bf16 v[86:89], v[170:173], v[210:213], v[86:89]
	v_mfma_f32_16x16x32_bf16 v[86:89], v[174:177], v[214:217], v[86:89]
	v_mfma_f32_16x16x32_bf16 v[82:85], v[184:187], v[214:217], v[82:85]
	v_mfma_f32_16x16x32_bf16 v[82:85], v[180:183], v[210:213], v[82:85]
	v_mfma_f32_16x16x32_bf16 v[66:69], v[180:183], v[218:221], v[66:69]
	v_mfma_f32_16x16x32_bf16 v[66:69], v[184:187], v[222:225], v[66:69]
	v_mfma_f32_16x16x32_bf16 v[70:73], v[174:177], v[222:225], v[70:73]
	v_mfma_f32_16x16x32_bf16 v[70:73], v[170:173], v[218:221], v[70:73]
	v_mfma_f32_16x16x32_bf16 v[74:77], v[162:165], v[218:221], v[74:77]
	v_mfma_f32_16x16x32_bf16 v[74:77], v[166:169], v[222:225], v[74:77]
	v_mfma_f32_16x16x32_bf16 v[78:81], v[158:161], v[222:225], v[78:81]
	v_mfma_f32_16x16x32_bf16 v[78:81], v[154:157], v[218:221], v[78:81]
	s_barrier
	s_add_u32 s50, s48, 0x8000
	s_addc_u32 s51, s49, 0
	s_add_i32 s71, s71, s3
	s_mov_b32 m0, s71
	ds_read_b128 v[188:191], v151 offset:49152
	ds_read_b128 v[198:201], v151 offset:50176
	ds_read_b128 v[202:205], v151 offset:51200
	ds_read_b128 v[206:209], v151 offset:52224
	ds_read_b128 v[210:213], v151 offset:53248
	ds_read_b128 v[214:217], v151 offset:54272
	ds_read_b128 v[218:221], v151 offset:55296
	ds_read_b128 v[222:225], v151 offset:56320
	global_load_lds_dwordx4 v132, s[50:51]
	s_add_i32 m0, s71, 0x2000
	s_add_u32 s48, s48, 0xc000
	v_lshl_add_u64 v[146:147], s[50:51], 0, v[136:137]
	s_addc_u32 s49, s49, 0
	s_add_i32 s50, s72, s3
	global_load_lds_dwordx4 v[146:147], off
	s_mov_b32 m0, s50
	s_nop 0
	global_load_lds_dwordx4 v132, s[48:49]
	s_add_i32 m0, s50, 0x2000
	s_nop 0
	global_load_lds_dwordx4 v136, s[48:49]
	s_waitcnt vmcnt(6)
	s_waitcnt lgkmcnt(0)
	s_barrier
	s_waitcnt lgkmcnt(0)
	v_mfma_f32_16x16x32_bf16 v[62:65], v[154:157], v[188:191], v[62:65]
	v_mfma_f32_16x16x32_bf16 v[62:65], v[158:161], v[198:201], v[62:65]
	v_mfma_f32_16x16x32_bf16 v[58:61], v[166:169], v[198:201], v[58:61]
	v_mfma_f32_16x16x32_bf16 v[58:61], v[162:165], v[188:191], v[58:61]
	v_mfma_f32_16x16x32_bf16 v[54:57], v[170:173], v[188:191], v[54:57]
	v_mfma_f32_16x16x32_bf16 v[54:57], v[174:177], v[198:201], v[54:57]
	v_mfma_f32_16x16x32_bf16 v[50:53], v[184:187], v[198:201], v[50:53]
	v_mfma_f32_16x16x32_bf16 v[50:53], v[180:183], v[188:191], v[50:53]
	v_mfma_f32_16x16x32_bf16 v[34:37], v[180:183], v[202:205], v[34:37]
	v_mfma_f32_16x16x32_bf16 v[34:37], v[184:187], v[206:209], v[34:37]
	v_mfma_f32_16x16x32_bf16 v[38:41], v[174:177], v[206:209], v[38:41]
	v_mfma_f32_16x16x32_bf16 v[38:41], v[170:173], v[202:205], v[38:41]
	v_mfma_f32_16x16x32_bf16 v[42:45], v[162:165], v[202:205], v[42:45]
	v_mfma_f32_16x16x32_bf16 v[42:45], v[166:169], v[206:209], v[42:45]
	v_mfma_f32_16x16x32_bf16 v[46:49], v[158:161], v[206:209], v[46:49]
	v_mfma_f32_16x16x32_bf16 v[46:49], v[154:157], v[202:205], v[46:49]
	v_mfma_f32_16x16x32_bf16 v[30:33], v[154:157], v[210:213], v[30:33]
	v_mfma_f32_16x16x32_bf16 v[30:33], v[158:161], v[214:217], v[30:33]
	v_mfma_f32_16x16x32_bf16 v[26:29], v[166:169], v[214:217], v[26:29]
	v_mfma_f32_16x16x32_bf16 v[26:29], v[162:165], v[210:213], v[26:29]
	v_mfma_f32_16x16x32_bf16 v[22:25], v[170:173], v[210:213], v[22:25]
	v_mfma_f32_16x16x32_bf16 v[22:25], v[174:177], v[214:217], v[22:25]
	v_mfma_f32_16x16x32_bf16 v[18:21], v[184:187], v[214:217], v[18:21]
	v_mfma_f32_16x16x32_bf16 v[18:21], v[180:183], v[210:213], v[18:21]
	v_mfma_f32_16x16x32_bf16 v[2:5], v[180:183], v[218:221], v[2:5]
	v_mfma_f32_16x16x32_bf16 v[2:5], v[184:187], v[222:225], v[2:5]
	v_mfma_f32_16x16x32_bf16 v[6:9], v[174:177], v[222:225], v[6:9]
	v_mfma_f32_16x16x32_bf16 v[6:9], v[170:173], v[218:221], v[6:9]
	v_mfma_f32_16x16x32_bf16 v[10:13], v[162:165], v[218:221], v[10:13]
	v_mfma_f32_16x16x32_bf16 v[10:13], v[166:169], v[222:225], v[10:13]
	v_mfma_f32_16x16x32_bf16 v[14:17], v[158:161], v[222:225], v[14:17]
	v_mfma_f32_16x16x32_bf16 v[14:17], v[154:157], v[218:221], v[14:17]
	s_barrier
	s_add_i32 s70, s70, 2
	s_add_u32 s44, s44, 0x10000
	s_addc_u32 s45, s45, 0
	s_add_u32 s68, s68, 0x10000
	s_addc_u32 s69, s69, 0
	s_cmp_gt_u32 s70, 61
	s_cbranch_scc0 .LBB0_757
	s_and_b64 vcc, exec, s[12:13]
	s_cbranch_vccz .LBB0_760
	s_barrier

; #define PG8_STAGE(bufoff, gbase, voff) do { _Pragma("unroll") for (int _i = 0; _i < 2; ++_i) \
;         __builtin_amdgcn_global_load_lds((const unsigned*)((const char*)(gbase) + (voff)[_i]), (PG8_LAS unsigned*)(lds + (bufoff) + ldsw + _i * 8192), 16, 0, 0); } while (0)
; #define PG8_LDA(dst, b, h) do { _Pragma("unroll") for (int m = 0; m < 4; ++m) _Pragma("unroll") for (int k = 0; k < 2; ++k) dst[m][k] = *(const PG8_LAS bf16x8*)(lds + PG8_SA(b, h) + aoff + m * 2048 + k * 1024); } while (0)
; #define PG8_LDB(dst, b, h) do { _Pragma("unroll") for (int n = 0; n < 2; ++n) _Pragma("unroll") for (int k = 0; k < 2; ++k) dst[n][k] = *(const PG8_LAS bf16x8*)(lds + PG8_SB(b, h) + boff + n * 2048 + k * 1024); } while (0)
; #define PG8_MMA(ai, bj, At, Bt) do { __builtin_amdgcn_s_setprio(1); _Pragma("unroll") for (int m = 0; m < 4; ++m) _Pragma("unroll") for (int n = 0; n < 2; ++n) _Pragma("unroll") for (int k = 0; k < 2; ++k) \
;         acc[ai][bj][m][n] = __builtin_amdgcn_mfma_f32_16x16x32_bf16(Bt[n][k], At[m][k], acc[ai][bj][m][n], 0, 0, 0); __builtin_amdgcn_s_setprio(0); } while (0)
; #define PG8_WAIT_V(n) asm volatile("s_waitcnt vmcnt(" #n ")" ::: "memory")
; #define PG8_WAIT_L(n) asm volatile("s_waitcnt lgkmcnt(" #n ")" ::: "memory")
; #define PG8_BAR __builtin_amdgcn_s_barrier()
; template <class Epi, class Sched, bool ALIGN_EPI = false, bool SP2 = false>
; __device__ __forceinline__ void gemm_phase(PG8_LAS unsigned char* lds, const Gemm g, const Sched& S, const Epi& E) {
;     ...
;             const char* a1 = cA + (size_t)(t + 1) * kstep;
;             const char* a2 = last ? nA : cA + (size_t)(t + 2) * kstep; const char* b2 = last ? nB : cB + (size_t)(t + 2) * kstep;
;             const char* a3 = a2 + kstep; const char* b3 = b2 + kstep;
;             if (last && has_next) S.a_ready(nxt);
;             if constexpr (SP2) {
;             PG8_LDB(B0, 0, 0); PG8_LDB(B1, 0, 1); PG8_SCHED; PG8_LDA(At, 0, 0); PG8_STAGE(PG8_SA(1, 1), a1 + hstep, voffA);
;             PG8_WAIT_V(8); PG8_WAIT_L(0); PG8_BAR; PG8_MMA(0, 0, At, B0); PG8_MMA(0, 1, At, B1); PG8_BAR; PG8_SCHED;
;             PG8_LDA(At, 0, 1); PG8_STAGE(PG8_SB(0, 0), b2, voffB); PG8_STAGE(PG8_SB(0, 1), b2 + hstep, voffB); PG8_STAGE(PG8_SA(0, 0), a2, voffA);
;             PG8_WAIT_V(8); PG8_WAIT_L(0); PG8_BAR; PG8_MMA(1, 0, At, B0); PG8_MMA(1, 1, At, B1); PG8_BAR; PG8_SCHED;
.LBB0_840:
	ds_read_b128 v[148:151], v153
	ds_read_b128 v[158:161], v153 offset:1024
	ds_read_b128 v[162:165], v153 offset:2048
	ds_read_b128 v[166:169], v153 offset:3072
	ds_read_b128 v[170:173], v154
	ds_read_b128 v[174:177], v154 offset:1024
	ds_read_b128 v[180:183], v154 offset:2048
	ds_read_b128 v[184:187], v154 offset:3072
	s_add_u32 s42, s40, 0x4000
	s_addc_u32 s43, s41, 0
	s_cmp_eq_u32 s69, 60
	s_cselect_b32 s46, s65, s42
	s_cselect_b32 s47, s23, s43
	s_cselect_b32 s44, s66, s67
	s_cselect_b32 s45, s17, s68
	s_add_u32 s42, s46, 0x8000
	s_addc_u32 s43, s47, 0
	s_sub_u32 s42, s40, 0x4000
	s_subb_u32 s43, s41, 0
	s_mov_b32 m0, s50
	s_nop 0
	global_load_lds_dwordx4 v130, s[42:43]
	s_mov_b32 m0, s51
	s_nop 0
	global_load_lds_dwordx4 v134, s[42:43]
	s_add_i32 m0, s28, 0xc000
	ds_read_b128 v[188:191], v155
	ds_read_b128 v[198:201], v155 offset:1024
	ds_read_b128 v[202:205], v155 offset:2048
	ds_read_b128 v[206:209], v155 offset:3072
	ds_read_b128 v[210:213], v155 offset:4096
	ds_read_b128 v[214:217], v155 offset:5120
	ds_read_b128 v[218:221], v155 offset:6144
	ds_read_b128 v[222:225], v155 offset:7168
	global_load_lds_dwordx4 v140, s[40:41]
	s_add_i32 m0, s28, 0xe000
	s_nop 0
	global_load_lds_dwordx4 v142, s[40:41]
	s_waitcnt vmcnt(8)
	s_waitcnt lgkmcnt(0)
	s_barrier
	s_waitcnt lgkmcnt(0)
	v_mfma_f32_16x16x32_bf16 v[126:129], v[148:151], v[188:191], v[126:129]
	v_mfma_f32_16x16x32_bf16 v[126:129], v[158:161], v[198:201], v[126:129]
	v_mfma_f32_16x16x32_bf16 v[122:125], v[166:169], v[198:201], v[122:125]
	v_mfma_f32_16x16x32_bf16 v[122:125], v[162:165], v[188:191], v[122:125]
	v_mfma_f32_16x16x32_bf16 v[118:121], v[170:173], v[188:191], v[118:121]
	v_mfma_f32_16x16x32_bf16 v[118:121], v[174:177], v[198:201], v[118:121]
	v_mfma_f32_16x16x32_bf16 v[114:117], v[184:187], v[198:201], v[114:117]
	v_mfma_f32_16x16x32_bf16 v[114:117], v[180:183], v[188:191], v[114:117]
	v_mfma_f32_16x16x32_bf16 v[98:101], v[180:183], v[202:205], v[98:101]
	v_mfma_f32_16x16x32_bf16 v[98:101], v[184:187], v[206:209], v[98:101]
	v_mfma_f32_16x16x32_bf16 v[102:105], v[174:177], v[206:209], v[102:105]
	v_mfma_f32_16x16x32_bf16 v[102:105], v[170:173], v[202:205], v[102:105]
	v_mfma_f32_16x16x32_bf16 v[106:109], v[162:165], v[202:205], v[106:109]
	v_mfma_f32_16x16x32_bf16 v[106:109], v[166:169], v[206:209], v[106:109]
	v_mfma_f32_16x16x32_bf16 v[110:113], v[158:161], v[206:209], v[110:113]
	v_mfma_f32_16x16x32_bf16 v[110:113], v[148:151], v[202:205], v[110:113]
	v_mfma_f32_16x16x32_bf16 v[94:97], v[148:151], v[210:213], v[94:97]
	v_mfma_f32_16x16x32_bf16 v[94:97], v[158:161], v[214:217], v[94:97]
	v_mfma_f32_16x16x32_bf16 v[90:93], v[166:169], v[214:217], v[90:93]
	v_mfma_f32_16x16x32_bf16 v[90:93], v[162:165], v[210:213], v[90:93]
	v_mfma_f32_16x16x32_bf16 v[86:89], v[170:173], v[210:213], v[86:89]
	v_mfma_f32_16x16x32_bf16 v[86:89], v[174:177], v[214:217], v[86:89]
	v_mfma_f32_16x16x32_bf16 v[82:85], v[184:187], v[214:217], v[82:85]
	v_mfma_f32_16x16x32_bf16 v[82:85], v[180:183], v[210:213], v[82:85]
	v_mfma_f32_16x16x32_bf16 v[66:69], v[180:183], v[218:221], v[66:69]
	v_mfma_f32_16x16x32_bf16 v[66:69], v[184:187], v[222:225], v[66:69]
	v_mfma_f32_16x16x32_bf16 v[70:73], v[174:177], v[222:225], v[70:73]
	v_mfma_f32_16x16x32_bf16 v[70:73], v[170:173], v[218:221], v[70:73]
	v_mfma_f32_16x16x32_bf16 v[74:77], v[162:165], v[218:221], v[74:77]
	v_mfma_f32_16x16x32_bf16 v[74:77], v[166:169], v[222:225], v[74:77]
	v_mfma_f32_16x16x32_bf16 v[78:81], v[158:161], v[222:225], v[78:81]
	v_mfma_f32_16x16x32_bf16 v[78:81], v[148:151], v[218:221], v[78:81]
	s_barrier
	s_add_i32 s70, s56, s3
	s_mov_b32 m0, s70
	ds_read_b128 v[188:191], v155 offset:16384
	ds_read_b128 v[198:201], v155 offset:17408
	ds_read_b128 v[202:205], v155 offset:18432
	ds_read_b128 v[206:209], v155 offset:19456
	ds_read_b128 v[210:213], v155 offset:20480
	ds_read_b128 v[214:217], v155 offset:21504
	ds_read_b128 v[218:221], v155 offset:22528
	ds_read_b128 v[222:225], v155 offset:23552
	global_load_lds_dwordx4 v132, s[44:45]
	s_add_i32 m0, s70, 0x2000
	s_add_u32 s70, s44, 0x4000
	s_addc_u32 s71, s45, 0
	s_add_i32 s72, s57, s3
	global_load_lds_dwordx4 v136, s[44:45]
	s_mov_b32 m0, s72
	s_nop 0
	global_load_lds_dwordx4 v132, s[70:71]
	s_add_i32 m0, s72, 0x2000
	s_nop 0
	global_load_lds_dwordx4 v136, s[70:71]
	s_waitcnt vmcnt(6)
	s_waitcnt lgkmcnt(0)
	s_barrier
	s_waitcnt lgkmcnt(0)
	v_mfma_f32_16x16x32_bf16 v[62:65], v[148:151], v[188:191], v[62:65]
	v_mfma_f32_16x16x32_bf16 v[62:65], v[158:161], v[198:201], v[62:65]
	v_mfma_f32_16x16x32_bf16 v[58:61], v[166:169], v[198:201], v[58:61]
	v_mfma_f32_16x16x32_bf16 v[58:61], v[162:165], v[188:191], v[58:61]
	v_mfma_f32_16x16x32_bf16 v[54:57], v[170:173], v[188:191], v[54:57]
	v_mfma_f32_16x16x32_bf16 v[54:57], v[174:177], v[198:201], v[54:57]
	v_mfma_f32_16x16x32_bf16 v[50:53], v[184:187], v[198:201], v[50:53]
	v_mfma_f32_16x16x32_bf16 v[50:53], v[180:183], v[188:191], v[50:53]
	v_mfma_f32_16x16x32_bf16 v[34:37], v[180:183], v[202:205], v[34:37]
	v_mfma_f32_16x16x32_bf16 v[34:37], v[184:187], v[206:209], v[34:37]
	v_mfma_f32_16x16x32_bf16 v[38:41], v[174:177], v[206:209], v[38:41]
	v_mfma_f32_16x16x32_bf16 v[38:41], v[170:173], v[202:205], v[38:41]
	v_mfma_f32_16x16x32_bf16 v[42:45], v[162:165], v[202:205], v[42:45]
	v_mfma_f32_16x16x32_bf16 v[42:45], v[166:169], v[206:209], v[42:45]
	v_mfma_f32_16x16x32_bf16 v[46:49], v[158:161], v[206:209], v[46:49]
	v_mfma_f32_16x16x32_bf16 v[46:49], v[148:151], v[202:205], v[46:49]
	v_mfma_f32_16x16x32_bf16 v[30:33], v[148:151], v[210:213], v[30:33]
	v_mfma_f32_16x16x32_bf16 v[30:33], v[158:161], v[214:217], v[30:33]
	v_mfma_f32_16x16x32_bf16 v[26:29], v[166:169], v[214:217], v[26:29]
	v_mfma_f32_16x16x32_bf16 v[26:29], v[162:165], v[210:213], v[26:29]
	v_mfma_f32_16x16x32_bf16 v[22:25], v[170:173], v[210:213], v[22:25]
	v_mfma_f32_16x16x32_bf16 v[22:25], v[174:177], v[214:217], v[22:25]
	v_mfma_f32_16x16x32_bf16 v[18:21], v[184:187], v[214:217], v[18:21]
	v_mfma_f32_16x16x32_bf16 v[18:21], v[180:183], v[210:213], v[18:21]
	v_mfma_f32_16x16x32_bf16 v[2:5], v[180:183], v[218:221], v[2:5]
	v_mfma_f32_16x16x32_bf16 v[2:5], v[184:187], v[222:225], v[2:5]
	v_mfma_f32_16x16x32_bf16 v[6:9], v[174:177], v[222:225], v[6:9]
	v_mfma_f32_16x16x32_bf16 v[6:9], v[170:173], v[218:221], v[6:9]
	v_mfma_f32_16x16x32_bf16 v[10:13], v[162:165], v[218:221], v[10:13]
	v_mfma_f32_16x16x32_bf16 v[10:13], v[166:169], v[222:225], v[10:13]
	v_mfma_f32_16x16x32_bf16 v[14:17], v[158:161], v[222:225], v[14:17]
	v_mfma_f32_16x16x32_bf16 v[14:17], v[148:151], v[218:221], v[14:17]
	s_barrier
; #define PG8_STAGE(bufoff, gbase, voff) do { _Pragma("unroll") for (int _i = 0; _i < 2; ++_i) \
;         __builtin_amdgcn_global_load_lds((const unsigned*)((const char*)(gbase) + (voff)[_i]), (PG8_LAS unsigned*)(lds + (bufoff) + ldsw + _i * 8192), 16, 0, 0); } while (0)
; #define PG8_LDA(dst, b, h) do { _Pragma("unroll") for (int m = 0; m < 4; ++m) _Pragma("unroll") for (int k = 0; k < 2; ++k) dst[m][k] = *(const PG8_LAS bf16x8*)(lds + PG8_SA(b, h) + aoff + m * 2048 + k * 1024); } while (0)
; #define PG8_LDB(dst, b, h) do { _Pragma("unroll") for (int n = 0; n < 2; ++n) _Pragma("unroll") for (int k = 0; k < 2; ++k) dst[n][k] = *(const PG8_LAS bf16x8*)(lds + PG8_SB(b, h) + boff + n * 2048 + k * 1024); } while (0)
; #define PG8_MMA(ai, bj, At, Bt) do { __builtin_amdgcn_s_setprio(1); _Pragma("unroll") for (int m = 0; m < 4; ++m) _Pragma("unroll") for (int n = 0; n < 2; ++n) _Pragma("unroll") for (int k = 0; k < 2; ++k) \
;         acc[ai][bj][m][n] = __builtin_amdgcn_mfma_f32_16x16x32_bf16(Bt[n][k], At[m][k], acc[ai][bj][m][n], 0, 0, 0); __builtin_amdgcn_s_setprio(0); } while (0)
; #define PG8_WAIT_V(n) asm volatile("s_waitcnt vmcnt(" #n ")" ::: "memory")
; #define PG8_WAIT_L(n) asm volatile("s_waitcnt lgkmcnt(" #n ")" ::: "memory")
; #define PG8_BAR __builtin_amdgcn_s_barrier()
; #define PG8_SCHED __builtin_amdgcn_sched_barrier(0)
; template <class Epi, class Sched, bool ALIGN_EPI = false, bool SP2 = false>
; __device__ __forceinline__ void gemm_phase(PG8_LAS unsigned char* lds, const Gemm g, const Sched& S, const Epi& E) {
;     ...
;             PG8_LDB(B0, 1, 0); PG8_LDB(B1, 1, 1); PG8_SCHED; PG8_LDA(At, 1, 0); PG8_STAGE(PG8_SA(0, 1), a2 + hstep, voffA);
;             PG8_WAIT_V(8); PG8_WAIT_L(0); PG8_BAR; PG8_MMA(0, 0, At, B0); PG8_MMA(0, 1, At, B1); PG8_BAR; PG8_SCHED;
;             PG8_LDA(At, 1, 1); PG8_STAGE(PG8_SB(1, 0), b3, voffB); PG8_STAGE(PG8_SB(1, 1), b3 + hstep, voffB); PG8_STAGE(PG8_SA(1, 0), a3, voffA);
;             PG8_WAIT_V(8); PG8_WAIT_L(0); PG8_BAR; PG8_MMA(1, 0, At, B0); PG8_MMA(1, 1, At, B1); PG8_BAR; PG8_SCHED;
	s_add_i32 s70, 0, 0x18000
	v_add_u32_e32 v138, s70, v1
	s_add_i32 s71, 0, 0x1c000
	ds_read_b128 v[148:151], v138
	ds_read_b128 v[158:161], v138 offset:1024
	ds_read_b128 v[162:165], v138 offset:2048
	ds_read_b128 v[166:169], v138 offset:3072
	v_add_u32_e32 v138, s71, v1
	ds_read_b128 v[170:173], v138
	ds_read_b128 v[174:177], v138 offset:1024
	ds_read_b128 v[180:183], v138 offset:2048
	ds_read_b128 v[184:187], v138 offset:3072
	s_mov_b32 m0, s28
	s_nop 0
	global_load_lds_dwordx4 v130, s[46:47]
	s_mov_b32 m0, s29
	s_nop 0
	global_load_lds_dwordx4 v134, s[46:47]
	s_add_u32 s46, s46, 0x4000
	s_addc_u32 s47, s47, 0
	s_mov_b32 m0, s30
	ds_read_b128 v[188:191], v155 offset:32768
	ds_read_b128 v[198:201], v155 offset:33792
	ds_read_b128 v[202:205], v155 offset:34816
	ds_read_b128 v[206:209], v155 offset:35840
	ds_read_b128 v[210:213], v155 offset:36864
	ds_read_b128 v[214:217], v155 offset:37888
	ds_read_b128 v[218:221], v155 offset:38912
	ds_read_b128 v[222:225], v155 offset:39936
	global_load_lds_dwordx4 v130, s[46:47]
	s_mov_b32 m0, s31
	s_nop 0
	global_load_lds_dwordx4 v134, s[46:47]
	s_waitcnt vmcnt(8)
	s_waitcnt lgkmcnt(0)
	s_barrier
	s_waitcnt lgkmcnt(0)
	v_mfma_f32_16x16x32_bf16 v[126:129], v[148:151], v[188:191], v[126:129]
	v_mfma_f32_16x16x32_bf16 v[126:129], v[158:161], v[198:201], v[126:129]
	v_mfma_f32_16x16x32_bf16 v[122:125], v[166:169], v[198:201], v[122:125]
	v_mfma_f32_16x16x32_bf16 v[122:125], v[162:165], v[188:191], v[122:125]
	v_mfma_f32_16x16x32_bf16 v[118:121], v[170:173], v[188:191], v[118:121]
	v_mfma_f32_16x16x32_bf16 v[118:121], v[174:177], v[198:201], v[118:121]
	v_mfma_f32_16x16x32_bf16 v[114:117], v[184:187], v[198:201], v[114:117]
	v_mfma_f32_16x16x32_bf16 v[114:117], v[180:183], v[188:191], v[114:117]
	v_mfma_f32_16x16x32_bf16 v[98:101], v[180:183], v[202:205], v[98:101]
	v_mfma_f32_16x16x32_bf16 v[98:101], v[184:187], v[206:209], v[98:101]
	v_mfma_f32_16x16x32_bf16 v[102:105], v[174:177], v[206:209], v[102:105]
	v_mfma_f32_16x16x32_bf16 v[102:105], v[170:173], v[202:205], v[102:105]
	v_mfma_f32_16x16x32_bf16 v[106:109], v[162:165], v[202:205], v[106:109]
	v_mfma_f32_16x16x32_bf16 v[106:109], v[166:169], v[206:209], v[106:109]
	v_mfma_f32_16x16x32_bf16 v[110:113], v[158:161], v[206:209], v[110:113]
	v_mfma_f32_16x16x32_bf16 v[110:113], v[148:151], v[202:205], v[110:113]
	v_mfma_f32_16x16x32_bf16 v[94:97], v[148:151], v[210:213], v[94:97]
	v_mfma_f32_16x16x32_bf16 v[94:97], v[158:161], v[214:217], v[94:97]
	v_mfma_f32_16x16x32_bf16 v[90:93], v[166:169], v[214:217], v[90:93]
	v_mfma_f32_16x16x32_bf16 v[90:93], v[162:165], v[210:213], v[90:93]
	v_mfma_f32_16x16x32_bf16 v[86:89], v[170:173], v[210:213], v[86:89]
	v_mfma_f32_16x16x32_bf16 v[86:89], v[174:177], v[214:217], v[86:89]
	v_mfma_f32_16x16x32_bf16 v[82:85], v[184:187], v[214:217], v[82:85]
	v_mfma_f32_16x16x32_bf16 v[82:85], v[180:183], v[210:213], v[82:85]
	v_mfma_f32_16x16x32_bf16 v[66:69], v[180:183], v[218:221], v[66:69]
	v_mfma_f32_16x16x32_bf16 v[66:69], v[184:187], v[222:225], v[66:69]
	v_mfma_f32_16x16x32_bf16 v[70:73], v[174:177], v[222:225], v[70:73]
	v_mfma_f32_16x16x32_bf16 v[70:73], v[170:173], v[218:221], v[70:73]
	v_mfma_f32_16x16x32_bf16 v[74:77], v[162:165], v[218:221], v[74:77]
	v_mfma_f32_16x16x32_bf16 v[74:77], v[166:169], v[222:225], v[74:77]
	v_mfma_f32_16x16x32_bf16 v[78:81], v[158:161], v[222:225], v[78:81]
	v_mfma_f32_16x16x32_bf16 v[78:81], v[148:151], v[218:221], v[78:81]
	s_barrier
	s_add_u32 s46, s44, 0x8000
	s_addc_u32 s47, s45, 0
	s_add_i32 s70, s70, s3
	s_mov_b32 m0, s70
	ds_read_b128 v[188:191], v155 offset:49152
	ds_read_b128 v[198:201], v155 offset:50176
	ds_read_b128 v[202:205], v155 offset:51200
	ds_read_b128 v[206:209], v155 offset:52224
	ds_read_b128 v[210:213], v155 offset:53248
	ds_read_b128 v[214:217], v155 offset:54272
	ds_read_b128 v[218:221], v155 offset:55296
	ds_read_b128 v[222:225], v155 offset:56320
	global_load_lds_dwordx4 v132, s[46:47]
	s_add_i32 m0, s70, 0x2000
	s_add_u32 s44, s44, 0xc000
	v_lshl_add_u64 v[226:227], s[46:47], 0, v[136:137]
	s_addc_u32 s45, s45, 0
	s_add_i32 s46, s71, s3
	global_load_lds_dwordx4 v[226:227], off
	s_mov_b32 m0, s46
	s_nop 0
	global_load_lds_dwordx4 v132, s[44:45]
	s_add_i32 m0, s46, 0x2000
	s_nop 0
	global_load_lds_dwordx4 v136, s[44:45]
	s_waitcnt vmcnt(6)
	s_waitcnt lgkmcnt(0)
	s_barrier
	s_waitcnt lgkmcnt(0)
	v_mfma_f32_16x16x32_bf16 v[62:65], v[148:151], v[188:191], v[62:65]
	v_mfma_f32_16x16x32_bf16 v[62:65], v[158:161], v[198:201], v[62:65]
	v_mfma_f32_16x16x32_bf16 v[58:61], v[166:169], v[198:201], v[58:61]
	v_mfma_f32_16x16x32_bf16 v[58:61], v[162:165], v[188:191], v[58:61]
	v_mfma_f32_16x16x32_bf16 v[54:57], v[170:173], v[188:191], v[54:57]
	v_mfma_f32_16x16x32_bf16 v[54:57], v[174:177], v[198:201], v[54:57]
	v_mfma_f32_16x16x32_bf16 v[50:53], v[184:187], v[198:201], v[50:53]
	v_mfma_f32_16x16x32_bf16 v[50:53], v[180:183], v[188:191], v[50:53]
	v_mfma_f32_16x16x32_bf16 v[34:37], v[180:183], v[202:205], v[34:37]
	v_mfma_f32_16x16x32_bf16 v[34:37], v[184:187], v[206:209], v[34:37]
	v_mfma_f32_16x16x32_bf16 v[38:41], v[174:177], v[206:209], v[38:41]
	v_mfma_f32_16x16x32_bf16 v[38:41], v[170:173], v[202:205], v[38:41]
	v_mfma_f32_16x16x32_bf16 v[42:45], v[162:165], v[202:205], v[42:45]
	v_mfma_f32_16x16x32_bf16 v[42:45], v[166:169], v[206:209], v[42:45]
	v_mfma_f32_16x16x32_bf16 v[46:49], v[158:161], v[206:209], v[46:49]
	v_mfma_f32_16x16x32_bf16 v[46:49], v[148:151], v[202:205], v[46:49]
	v_mfma_f32_16x16x32_bf16 v[30:33], v[148:151], v[210:213], v[30:33]
	v_mfma_f32_16x16x32_bf16 v[30:33], v[158:161], v[214:217], v[30:33]
	v_mfma_f32_16x16x32_bf16 v[26:29], v[166:169], v[214:217], v[26:29]
	v_mfma_f32_16x16x32_bf16 v[26:29], v[162:165], v[210:213], v[26:29]
	v_mfma_f32_16x16x32_bf16 v[22:25], v[170:173], v[210:213], v[22:25]
	v_mfma_f32_16x16x32_bf16 v[22:25], v[174:177], v[214:217], v[22:25]
	v_mfma_f32_16x16x32_bf16 v[18:21], v[184:187], v[214:217], v[18:21]
	v_mfma_f32_16x16x32_bf16 v[18:21], v[180:183], v[210:213], v[18:21]
	v_mfma_f32_16x16x32_bf16 v[2:5], v[180:183], v[218:221], v[2:5]
	v_mfma_f32_16x16x32_bf16 v[2:5], v[184:187], v[222:225], v[2:5]
	v_mfma_f32_16x16x32_bf16 v[6:9], v[174:177], v[222:225], v[6:9]
	v_mfma_f32_16x16x32_bf16 v[6:9], v[170:173], v[218:221], v[6:9]
	v_mfma_f32_16x16x32_bf16 v[10:13], v[162:165], v[218:221], v[10:13]
	v_mfma_f32_16x16x32_bf16 v[10:13], v[166:169], v[222:225], v[10:13]
	v_mfma_f32_16x16x32_bf16 v[14:17], v[158:161], v[222:225], v[14:17]
	v_mfma_f32_16x16x32_bf16 v[14:17], v[148:151], v[218:221], v[14:17]
	s_barrier
	s_add_i32 s69, s69, 2
	s_add_u32 s40, s40, 0x10000
	s_addc_u32 s41, s41, 0
	s_add_u32 s67, s67, 0x10000
	s_addc_u32 s68, s68, 0
	s_cmp_gt_u32 s69, 61
	s_cbranch_scc0 .LBB0_840
	s_and_b64 vcc, exec, s[14:15]
	s_cbranch_vccz .LBB0_843
	s_barrier

; #define PG8_STAGE(bufoff, gbase, voff) do { _Pragma("unroll") for (int _i = 0; _i < 2; ++_i) \
;         __builtin_amdgcn_global_load_lds((const unsigned*)((const char*)(gbase) + (voff)[_i]), (PG8_LAS unsigned*)(lds + (bufoff) + ldsw + _i * 8192), 16, 0, 0); } while (0)
; #define PG8_LDA(dst, b, h) do { _Pragma("unroll") for (int m = 0; m < 4; ++m) _Pragma("unroll") for (int k = 0; k < 2; ++k) dst[m][k] = *(const PG8_LAS bf16x8*)(lds + PG8_SA(b, h) + aoff + m * 2048 + k * 1024); } while (0)
; #define PG8_LDB(dst, b, h) do { _Pragma("unroll") for (int n = 0; n < 2; ++n) _Pragma("unroll") for (int k = 0; k < 2; ++k) dst[n][k] = *(const PG8_LAS bf16x8*)(lds + PG8_SB(b, h) + boff + n * 2048 + k * 1024); } while (0)
; #define PG8_MMA(ai, bj, At, Bt) do { __builtin_amdgcn_s_setprio(1); _Pragma("unroll") for (int m = 0; m < 4; ++m) _Pragma("unroll") for (int n = 0; n < 2; ++n) _Pragma("unroll") for (int k = 0; k < 2; ++k) \
;         acc[ai][bj][m][n] = __builtin_amdgcn_mfma_f32_16x16x32_bf16(Bt[n][k], At[m][k], acc[ai][bj][m][n], 0, 0, 0); __builtin_amdgcn_s_setprio(0); } while (0)
; #define PG8_WAIT_V(n) asm volatile("s_waitcnt vmcnt(" #n ")" ::: "memory")
; #define PG8_WAIT_L(n) asm volatile("s_waitcnt lgkmcnt(" #n ")" ::: "memory")
; template <class Epi, class Sched, bool ALIGN_EPI = false, bool SP2 = false>
; __device__ __forceinline__ void gemm_phase(PG8_LAS unsigned char* lds, const Gemm g, const Sched& S, const Epi& E) {
;     ...
;             const bool last = (t == nt - 2);
;             const char* a1 = cA + (size_t)(t + 1) * kstep;
;             const char* a2 = last ? nA : cA + (size_t)(t + 2) * kstep; const char* b2 = last ? nB : cB + (size_t)(t + 2) * kstep;
;             const char* a3 = a2 + kstep; const char* b3 = b2 + kstep;
;             if (last && has_next) S.a_ready(nxt);
;             if constexpr (SP2) {
;             PG8_LDB(B0, 0, 0); PG8_LDB(B1, 0, 1); PG8_SCHED; PG8_LDA(At, 0, 0); PG8_STAGE(PG8_SA(1, 1), a1 + hstep, voffA);
;             PG8_WAIT_V(8); PG8_WAIT_L(0); PG8_BAR; PG8_MMA(0, 0, At, B0); PG8_MMA(0, 1, At, B1); PG8_BAR; PG8_SCHED;
;             PG8_LDA(At, 0, 1); PG8_STAGE(PG8_SB(0, 0), b2, voffB); PG8_STAGE(PG8_SB(0, 1), b2 + hstep, voffB); PG8_STAGE(PG8_SA(0, 0), a2, voffA);
;             PG8_WAIT_V(8); PG8_WAIT_L(0); PG8_BAR; PG8_MMA(1, 0, At, B0); PG8_MMA(1, 1, At, B1); PG8_BAR; PG8_SCHED;
.LBB0_939:
	s_or_b32 s24, s59, 1
	s_lshl_b64 s[62:63], s[24:25], 15
	s_add_i32 s24, s59, 2
	ds_read_b128 v[156:159], v193
	ds_read_b128 v[160:163], v193 offset:1024
	ds_read_b128 v[196:199], v193 offset:2048
	ds_read_b128 v[200:203], v193 offset:3072
	ds_read_b128 v[204:207], v194
	ds_read_b128 v[208:211], v194 offset:1024
	ds_read_b128 v[212:215], v194 offset:2048
	ds_read_b128 v[216:219], v194 offset:3072
	s_lshl_b64 s[8:9], s[24:25], 15
	s_add_u32 s44, s6, s8
	s_addc_u32 s45, s7, s9
	s_cmpk_eq_i32 s59, 0xaa
	s_cselect_b32 s46, s58, s44
	s_cselect_b32 s47, s56, s45
	s_cselect_b32 s44, 0, s8
	s_cselect_b32 s45, 0, s9
	s_add_u32 s8, s46, 0x8000
	s_addc_u32 s9, s47, 0
	s_add_u32 s44, s14, s44
	s_addc_u32 s45, s15, s45
	s_add_u32 s62, s6, s62
	s_addc_u32 s63, s7, s63
	s_add_u32 s62, s62, 0x4000
	s_addc_u32 s63, s63, 0
	s_sub_u32 s8, s62, 0x4000
	s_subb_u32 s9, s63, 0
	s_mov_b32 m0, s51
	s_nop 0
	global_load_lds_dwordx4 v130, s[8:9]
	s_mov_b32 m0, s57
	s_nop 0
	global_load_lds_dwordx4 v134, s[8:9]
	s_add_i32 m0, s30, 0xc000
	ds_read_b128 v[220:223], v186
	ds_read_b128 v[224:227], v186 offset:1024
	ds_read_b128 v[228:231], v186 offset:2048
	ds_read_b128 v[232:235], v186 offset:3072
	ds_read_b128 v[236:239], v186 offset:4096
	ds_read_b128 v[240:243], v186 offset:5120
	ds_read_b128 v[244:247], v186 offset:6144
	ds_read_b128 v[248:251], v186 offset:7168
	global_load_lds_dwordx4 v130, s[62:63]
	s_add_i32 m0, s30, 0xe000
	s_nop 0
	global_load_lds_dwordx4 v134, s[62:63]
	s_waitcnt vmcnt(8)
	s_waitcnt lgkmcnt(0)
	s_barrier
	s_waitcnt lgkmcnt(0)
	v_mfma_f32_16x16x32_bf16 v[126:129], v[156:159], v[220:223], v[126:129]
	v_mfma_f32_16x16x32_bf16 v[126:129], v[160:163], v[224:227], v[126:129]
	v_mfma_f32_16x16x32_bf16 v[122:125], v[200:203], v[224:227], v[122:125]
	v_mfma_f32_16x16x32_bf16 v[122:125], v[196:199], v[220:223], v[122:125]
	v_mfma_f32_16x16x32_bf16 v[118:121], v[204:207], v[220:223], v[118:121]
	v_mfma_f32_16x16x32_bf16 v[118:121], v[208:211], v[224:227], v[118:121]
	v_mfma_f32_16x16x32_bf16 v[114:117], v[216:219], v[224:227], v[114:117]
	v_mfma_f32_16x16x32_bf16 v[114:117], v[212:215], v[220:223], v[114:117]
	v_mfma_f32_16x16x32_bf16 v[98:101], v[212:215], v[228:231], v[98:101]
	v_mfma_f32_16x16x32_bf16 v[98:101], v[216:219], v[232:235], v[98:101]
	v_mfma_f32_16x16x32_bf16 v[102:105], v[208:211], v[232:235], v[102:105]
	v_mfma_f32_16x16x32_bf16 v[102:105], v[204:207], v[228:231], v[102:105]
	v_mfma_f32_16x16x32_bf16 v[106:109], v[196:199], v[228:231], v[106:109]
	v_mfma_f32_16x16x32_bf16 v[106:109], v[200:203], v[232:235], v[106:109]
	v_mfma_f32_16x16x32_bf16 v[110:113], v[160:163], v[232:235], v[110:113]
	v_mfma_f32_16x16x32_bf16 v[110:113], v[156:159], v[228:231], v[110:113]
	v_mfma_f32_16x16x32_bf16 v[94:97], v[156:159], v[236:239], v[94:97]
	v_mfma_f32_16x16x32_bf16 v[94:97], v[160:163], v[240:243], v[94:97]
	v_mfma_f32_16x16x32_bf16 v[90:93], v[200:203], v[240:243], v[90:93]
	v_mfma_f32_16x16x32_bf16 v[90:93], v[196:199], v[236:239], v[90:93]
	v_mfma_f32_16x16x32_bf16 v[86:89], v[204:207], v[236:239], v[86:89]
	v_mfma_f32_16x16x32_bf16 v[86:89], v[208:211], v[240:243], v[86:89]
	v_mfma_f32_16x16x32_bf16 v[82:85], v[216:219], v[240:243], v[82:85]
	v_mfma_f32_16x16x32_bf16 v[82:85], v[212:215], v[236:239], v[82:85]
	v_mfma_f32_16x16x32_bf16 v[66:69], v[212:215], v[244:247], v[66:69]
	v_mfma_f32_16x16x32_bf16 v[66:69], v[216:219], v[248:251], v[66:69]
	v_mfma_f32_16x16x32_bf16 v[70:73], v[208:211], v[248:251], v[70:73]
	v_mfma_f32_16x16x32_bf16 v[70:73], v[204:207], v[244:247], v[70:73]
	v_mfma_f32_16x16x32_bf16 v[74:77], v[196:199], v[244:247], v[74:77]
	v_mfma_f32_16x16x32_bf16 v[74:77], v[200:203], v[248:251], v[74:77]
	v_mfma_f32_16x16x32_bf16 v[78:81], v[160:163], v[248:251], v[78:81]
	v_mfma_f32_16x16x32_bf16 v[78:81], v[156:159], v[244:247], v[78:81]
	s_barrier
	s_add_i32 s62, s67, s29
	s_mov_b32 m0, s62
	ds_read_b128 v[220:223], v186 offset:16384
	ds_read_b128 v[224:227], v186 offset:17408
	ds_read_b128 v[228:231], v186 offset:18432
	ds_read_b128 v[232:235], v186 offset:19456
	ds_read_b128 v[236:239], v186 offset:20480
	ds_read_b128 v[240:243], v186 offset:21504
	ds_read_b128 v[244:247], v186 offset:22528
	ds_read_b128 v[248:251], v186 offset:23552
	global_load_lds_dwordx4 v132, s[44:45]
	s_add_i32 m0, s62, 0x2000
	s_add_u32 s62, s44, 0x4000
	s_addc_u32 s63, s45, 0
	s_add_i32 s72, s68, s29
	global_load_lds_dwordx4 v136, s[44:45]
	s_mov_b32 m0, s72
	s_nop 0
	global_load_lds_dwordx4 v132, s[62:63]
	s_add_i32 m0, s72, 0x2000
	s_nop 0
	global_load_lds_dwordx4 v136, s[62:63]
	s_waitcnt vmcnt(6)
	s_waitcnt lgkmcnt(0)
	s_barrier
; #define PG8_STAGE(bufoff, gbase, voff) do { _Pragma("unroll") for (int _i = 0; _i < 2; ++_i) \
;         __builtin_amdgcn_global_load_lds((const unsigned*)((const char*)(gbase) + (voff)[_i]), (PG8_LAS unsigned*)(lds + (bufoff) + ldsw + _i * 8192), 16, 0, 0); } while (0)
; #define PG8_LDA(dst, b, h) do { _Pragma("unroll") for (int m = 0; m < 4; ++m) _Pragma("unroll") for (int k = 0; k < 2; ++k) dst[m][k] = *(const PG8_LAS bf16x8*)(lds + PG8_SA(b, h) + aoff + m * 2048 + k * 1024); } while (0)
; #define PG8_LDB(dst, b, h) do { _Pragma("unroll") for (int n = 0; n < 2; ++n) _Pragma("unroll") for (int k = 0; k < 2; ++k) dst[n][k] = *(const PG8_LAS bf16x8*)(lds + PG8_SB(b, h) + boff + n * 2048 + k * 1024); } while (0)
; #define PG8_MMA(ai, bj, At, Bt) do { __builtin_amdgcn_s_setprio(1); _Pragma("unroll") for (int m = 0; m < 4; ++m) _Pragma("unroll") for (int n = 0; n < 2; ++n) _Pragma("unroll") for (int k = 0; k < 2; ++k) \
;         acc[ai][bj][m][n] = __builtin_amdgcn_mfma_f32_16x16x32_bf16(Bt[n][k], At[m][k], acc[ai][bj][m][n], 0, 0, 0); __builtin_amdgcn_s_setprio(0); } while (0)
; #define PG8_WAIT_V(n) asm volatile("s_waitcnt vmcnt(" #n ")" ::: "memory")
; #define PG8_WAIT_L(n) asm volatile("s_waitcnt lgkmcnt(" #n ")" ::: "memory")
; #define PG8_BAR __builtin_amdgcn_s_barrier()
; #define PG8_SCHED __builtin_amdgcn_sched_barrier(0)
; template <class Epi, class Sched, bool ALIGN_EPI = false, bool SP2 = false>
; __device__ __forceinline__ void gemm_phase(PG8_LAS unsigned char* lds, const Gemm g, const Sched& S, const Epi& E) {
;     ...
;             PG8_WAIT_V(8); PG8_WAIT_L(0); PG8_BAR; PG8_MMA(1, 0, At, B0); PG8_MMA(1, 1, At, B1); PG8_BAR; PG8_SCHED;
;             PG8_LDB(B0, 1, 0); PG8_LDB(B1, 1, 1); PG8_SCHED; PG8_LDA(At, 1, 0); PG8_STAGE(PG8_SA(0, 1), a2 + hstep, voffA);
;             PG8_WAIT_V(8); PG8_WAIT_L(0); PG8_BAR; PG8_MMA(0, 0, At, B0); PG8_MMA(0, 1, At, B1); PG8_BAR; PG8_SCHED;
;             PG8_LDA(At, 1, 1); PG8_STAGE(PG8_SB(1, 0), b3, voffB); PG8_STAGE(PG8_SB(1, 1), b3 + hstep, voffB); PG8_STAGE(PG8_SA(1, 0), a3, voffA);
	s_waitcnt lgkmcnt(0)
	v_mfma_f32_16x16x32_bf16 v[62:65], v[156:159], v[220:223], v[62:65]
	v_mfma_f32_16x16x32_bf16 v[62:65], v[160:163], v[224:227], v[62:65]
	v_mfma_f32_16x16x32_bf16 v[58:61], v[200:203], v[224:227], v[58:61]
	v_mfma_f32_16x16x32_bf16 v[58:61], v[196:199], v[220:223], v[58:61]
	v_mfma_f32_16x16x32_bf16 v[54:57], v[204:207], v[220:223], v[54:57]
	v_mfma_f32_16x16x32_bf16 v[54:57], v[208:211], v[224:227], v[54:57]
	v_mfma_f32_16x16x32_bf16 v[50:53], v[216:219], v[224:227], v[50:53]
	v_mfma_f32_16x16x32_bf16 v[50:53], v[212:215], v[220:223], v[50:53]
	v_mfma_f32_16x16x32_bf16 v[34:37], v[212:215], v[228:231], v[34:37]
	v_mfma_f32_16x16x32_bf16 v[34:37], v[216:219], v[232:235], v[34:37]
	v_mfma_f32_16x16x32_bf16 v[38:41], v[208:211], v[232:235], v[38:41]
	v_mfma_f32_16x16x32_bf16 v[38:41], v[204:207], v[228:231], v[38:41]
	v_mfma_f32_16x16x32_bf16 v[42:45], v[196:199], v[228:231], v[42:45]
	v_mfma_f32_16x16x32_bf16 v[42:45], v[200:203], v[232:235], v[42:45]
	v_mfma_f32_16x16x32_bf16 v[46:49], v[160:163], v[232:235], v[46:49]
	v_mfma_f32_16x16x32_bf16 v[46:49], v[156:159], v[228:231], v[46:49]
	v_mfma_f32_16x16x32_bf16 v[30:33], v[156:159], v[236:239], v[30:33]
	v_mfma_f32_16x16x32_bf16 v[30:33], v[160:163], v[240:243], v[30:33]
	v_mfma_f32_16x16x32_bf16 v[26:29], v[200:203], v[240:243], v[26:29]
	v_mfma_f32_16x16x32_bf16 v[26:29], v[196:199], v[236:239], v[26:29]
	v_mfma_f32_16x16x32_bf16 v[22:25], v[204:207], v[236:239], v[22:25]
	v_mfma_f32_16x16x32_bf16 v[22:25], v[208:211], v[240:243], v[22:25]
	v_mfma_f32_16x16x32_bf16 v[18:21], v[216:219], v[240:243], v[18:21]
	v_mfma_f32_16x16x32_bf16 v[18:21], v[212:215], v[236:239], v[18:21]
	v_mfma_f32_16x16x32_bf16 v[2:5], v[212:215], v[244:247], v[2:5]
	v_mfma_f32_16x16x32_bf16 v[2:5], v[216:219], v[248:251], v[2:5]
	v_mfma_f32_16x16x32_bf16 v[6:9], v[208:211], v[248:251], v[6:9]
	v_mfma_f32_16x16x32_bf16 v[6:9], v[204:207], v[244:247], v[6:9]
	v_mfma_f32_16x16x32_bf16 v[10:13], v[196:199], v[244:247], v[10:13]
	v_mfma_f32_16x16x32_bf16 v[10:13], v[200:203], v[248:251], v[10:13]
	v_mfma_f32_16x16x32_bf16 v[14:17], v[160:163], v[248:251], v[14:17]
	v_mfma_f32_16x16x32_bf16 v[14:17], v[156:159], v[244:247], v[14:17]
	s_barrier
	s_add_i32 s62, 0, 0x18000
	v_add_u32_e32 v145, s62, v166
	s_add_i32 s63, 0, 0x1c000
	ds_read_b128 v[156:159], v145
	ds_read_b128 v[160:163], v145 offset:1024
	ds_read_b128 v[196:199], v145 offset:2048
	ds_read_b128 v[200:203], v145 offset:3072
	v_add_u32_e32 v145, s63, v166
	ds_read_b128 v[204:207], v145
	ds_read_b128 v[208:211], v145 offset:1024
	ds_read_b128 v[212:215], v145 offset:2048
	ds_read_b128 v[216:219], v145 offset:3072
	s_mov_b32 m0, s30
	s_nop 0
	global_load_lds_dwordx4 v130, s[46:47]
	s_mov_b32 m0, s31
	s_nop 0
	global_load_lds_dwordx4 v134, s[46:47]
	s_add_u32 s46, s46, 0x4000
	s_addc_u32 s47, s47, 0
	s_mov_b32 m0, s35
	ds_read_b128 v[220:223], v186 offset:32768
	ds_read_b128 v[224:227], v186 offset:33792
	ds_read_b128 v[228:231], v186 offset:34816
	ds_read_b128 v[232:235], v186 offset:35840
	ds_read_b128 v[236:239], v186 offset:36864
	ds_read_b128 v[240:243], v186 offset:37888
	ds_read_b128 v[244:247], v186 offset:38912
	ds_read_b128 v[248:251], v186 offset:39936
	global_load_lds_dwordx4 v130, s[46:47]
	s_mov_b32 m0, s48
	s_nop 0
	global_load_lds_dwordx4 v134, s[46:47]
	s_waitcnt vmcnt(8)
	s_waitcnt lgkmcnt(0)
	s_barrier
; #define PG8_STAGE(bufoff, gbase, voff) do { _Pragma("unroll") for (int _i = 0; _i < 2; ++_i) \
;         __builtin_amdgcn_global_load_lds((const unsigned*)((const char*)(gbase) + (voff)[_i]), (PG8_LAS unsigned*)(lds + (bufoff) + ldsw + _i * 8192), 16, 0, 0); } while (0)
; #define PG8_LDA(dst, b, h) do { _Pragma("unroll") for (int m = 0; m < 4; ++m) _Pragma("unroll") for (int k = 0; k < 2; ++k) dst[m][k] = *(const PG8_LAS bf16x8*)(lds + PG8_SA(b, h) + aoff + m * 2048 + k * 1024); } while (0)
; #define PG8_MMA(ai, bj, At, Bt) do { __builtin_amdgcn_s_setprio(1); _Pragma("unroll") for (int m = 0; m < 4; ++m) _Pragma("unroll") for (int n = 0; n < 2; ++n) _Pragma("unroll") for (int k = 0; k < 2; ++k) \
;         acc[ai][bj][m][n] = __builtin_amdgcn_mfma_f32_16x16x32_bf16(Bt[n][k], At[m][k], acc[ai][bj][m][n], 0, 0, 0); __builtin_amdgcn_s_setprio(0); } while (0)
; #define PG8_WAIT_V(n) asm volatile("s_waitcnt vmcnt(" #n ")" ::: "memory")
; #define PG8_WAIT_L(n) asm volatile("s_waitcnt lgkmcnt(" #n ")" ::: "memory")
; #define PG8_BAR __builtin_amdgcn_s_barrier()
; #define PG8_SCHED __builtin_amdgcn_sched_barrier(0)
; template <class Epi, class Sched, bool ALIGN_EPI = false, bool SP2 = false>
; __device__ __forceinline__ void gemm_phase(PG8_LAS unsigned char* lds, const Gemm g, const Sched& S, const Epi& E) {
;     ...
;             PG8_WAIT_V(8); PG8_WAIT_L(0); PG8_BAR; PG8_MMA(0, 0, At, B0); PG8_MMA(0, 1, At, B1); PG8_BAR; PG8_SCHED;
;             PG8_LDA(At, 1, 1); PG8_STAGE(PG8_SB(1, 0), b3, voffB); PG8_STAGE(PG8_SB(1, 1), b3 + hstep, voffB); PG8_STAGE(PG8_SA(1, 0), a3, voffA);
;             PG8_WAIT_V(8); PG8_WAIT_L(0); PG8_BAR; PG8_MMA(1, 0, At, B0); PG8_MMA(1, 1, At, B1); PG8_BAR; PG8_SCHED;
	s_waitcnt lgkmcnt(0)
	v_mfma_f32_16x16x32_bf16 v[126:129], v[156:159], v[220:223], v[126:129]
	v_mfma_f32_16x16x32_bf16 v[126:129], v[160:163], v[224:227], v[126:129]
	v_mfma_f32_16x16x32_bf16 v[122:125], v[200:203], v[224:227], v[122:125]
	v_mfma_f32_16x16x32_bf16 v[122:125], v[196:199], v[220:223], v[122:125]
	v_mfma_f32_16x16x32_bf16 v[118:121], v[204:207], v[220:223], v[118:121]
	v_mfma_f32_16x16x32_bf16 v[118:121], v[208:211], v[224:227], v[118:121]
	v_mfma_f32_16x16x32_bf16 v[114:117], v[216:219], v[224:227], v[114:117]
	v_mfma_f32_16x16x32_bf16 v[114:117], v[212:215], v[220:223], v[114:117]
	v_mfma_f32_16x16x32_bf16 v[98:101], v[212:215], v[228:231], v[98:101]
	v_mfma_f32_16x16x32_bf16 v[98:101], v[216:219], v[232:235], v[98:101]
	v_mfma_f32_16x16x32_bf16 v[102:105], v[208:211], v[232:235], v[102:105]
	v_mfma_f32_16x16x32_bf16 v[102:105], v[204:207], v[228:231], v[102:105]
	v_mfma_f32_16x16x32_bf16 v[106:109], v[196:199], v[228:231], v[106:109]
	v_mfma_f32_16x16x32_bf16 v[106:109], v[200:203], v[232:235], v[106:109]
	v_mfma_f32_16x16x32_bf16 v[110:113], v[160:163], v[232:235], v[110:113]
	v_mfma_f32_16x16x32_bf16 v[110:113], v[156:159], v[228:231], v[110:113]
	v_mfma_f32_16x16x32_bf16 v[94:97], v[156:159], v[236:239], v[94:97]
	v_mfma_f32_16x16x32_bf16 v[94:97], v[160:163], v[240:243], v[94:97]
	v_mfma_f32_16x16x32_bf16 v[90:93], v[200:203], v[240:243], v[90:93]
	v_mfma_f32_16x16x32_bf16 v[90:93], v[196:199], v[236:239], v[90:93]
	v_mfma_f32_16x16x32_bf16 v[86:89], v[204:207], v[236:239], v[86:89]
	v_mfma_f32_16x16x32_bf16 v[86:89], v[208:211], v[240:243], v[86:89]
	v_mfma_f32_16x16x32_bf16 v[82:85], v[216:219], v[240:243], v[82:85]
	v_mfma_f32_16x16x32_bf16 v[82:85], v[212:215], v[236:239], v[82:85]
	v_mfma_f32_16x16x32_bf16 v[66:69], v[212:215], v[244:247], v[66:69]
	v_mfma_f32_16x16x32_bf16 v[66:69], v[216:219], v[248:251], v[66:69]
	v_mfma_f32_16x16x32_bf16 v[70:73], v[208:211], v[248:251], v[70:73]
	v_mfma_f32_16x16x32_bf16 v[70:73], v[204:207], v[244:247], v[70:73]
	v_mfma_f32_16x16x32_bf16 v[74:77], v[196:199], v[244:247], v[74:77]
	v_mfma_f32_16x16x32_bf16 v[74:77], v[200:203], v[248:251], v[74:77]
	v_mfma_f32_16x16x32_bf16 v[78:81], v[160:163], v[248:251], v[78:81]
	v_mfma_f32_16x16x32_bf16 v[78:81], v[156:159], v[244:247], v[78:81]
	s_barrier
	s_add_u32 s46, s44, 0x8000
	s_addc_u32 s47, s45, 0
	s_add_i32 s62, s62, s29
	s_mov_b32 m0, s62
	ds_read_b128 v[220:223], v186 offset:49152
	ds_read_b128 v[224:227], v186 offset:50176
	ds_read_b128 v[228:231], v186 offset:51200
	ds_read_b128 v[232:235], v186 offset:52224
	ds_read_b128 v[236:239], v186 offset:53248
	ds_read_b128 v[240:243], v186 offset:54272
	ds_read_b128 v[244:247], v186 offset:55296
	ds_read_b128 v[248:251], v186 offset:56320
	global_load_lds_dwordx4 v132, s[46:47]
	s_add_i32 m0, s62, 0x2000
	s_add_u32 s44, s44, 0xc000
	v_lshl_add_u64 v[164:165], s[46:47], 0, v[136:137]
	s_addc_u32 s45, s45, 0
	s_add_i32 s46, s63, s29
	global_load_lds_dwordx4 v[164:165], off
	s_mov_b32 m0, s46
	s_nop 0
	global_load_lds_dwordx4 v132, s[44:45]
	s_add_i32 m0, s46, 0x2000
	s_nop 0
	global_load_lds_dwordx4 v136, s[44:45]
	s_waitcnt vmcnt(6)
	s_waitcnt lgkmcnt(0)
	s_barrier
	s_waitcnt lgkmcnt(0)
	v_mfma_f32_16x16x32_bf16 v[62:65], v[156:159], v[220:223], v[62:65]
	v_mfma_f32_16x16x32_bf16 v[62:65], v[160:163], v[224:227], v[62:65]
	v_mfma_f32_16x16x32_bf16 v[58:61], v[200:203], v[224:227], v[58:61]
	v_mfma_f32_16x16x32_bf16 v[58:61], v[196:199], v[220:223], v[58:61]
	v_mfma_f32_16x16x32_bf16 v[54:57], v[204:207], v[220:223], v[54:57]
	v_mfma_f32_16x16x32_bf16 v[54:57], v[208:211], v[224:227], v[54:57]
	v_mfma_f32_16x16x32_bf16 v[50:53], v[216:219], v[224:227], v[50:53]
	v_mfma_f32_16x16x32_bf16 v[50:53], v[212:215], v[220:223], v[50:53]
	v_mfma_f32_16x16x32_bf16 v[34:37], v[212:215], v[228:231], v[34:37]
	v_mfma_f32_16x16x32_bf16 v[34:37], v[216:219], v[232:235], v[34:37]
	v_mfma_f32_16x16x32_bf16 v[38:41], v[208:211], v[232:235], v[38:41]
	v_mfma_f32_16x16x32_bf16 v[38:41], v[204:207], v[228:231], v[38:41]
	v_mfma_f32_16x16x32_bf16 v[42:45], v[196:199], v[228:231], v[42:45]
	v_mfma_f32_16x16x32_bf16 v[42:45], v[200:203], v[232:235], v[42:45]
	v_mfma_f32_16x16x32_bf16 v[46:49], v[160:163], v[232:235], v[46:49]
	v_mfma_f32_16x16x32_bf16 v[46:49], v[156:159], v[228:231], v[46:49]
	v_mfma_f32_16x16x32_bf16 v[30:33], v[156:159], v[236:239], v[30:33]
	v_mfma_f32_16x16x32_bf16 v[30:33], v[160:163], v[240:243], v[30:33]
	v_mfma_f32_16x16x32_bf16 v[26:29], v[200:203], v[240:243], v[26:29]
	v_mfma_f32_16x16x32_bf16 v[26:29], v[196:199], v[236:239], v[26:29]
	v_mfma_f32_16x16x32_bf16 v[22:25], v[204:207], v[236:239], v[22:25]
	v_mfma_f32_16x16x32_bf16 v[22:25], v[208:211], v[240:243], v[22:25]
	v_mfma_f32_16x16x32_bf16 v[18:21], v[216:219], v[240:243], v[18:21]
	v_mfma_f32_16x16x32_bf16 v[18:21], v[212:215], v[236:239], v[18:21]
	v_mfma_f32_16x16x32_bf16 v[2:5], v[212:215], v[244:247], v[2:5]
	v_mfma_f32_16x16x32_bf16 v[2:5], v[216:219], v[248:251], v[2:5]
	v_mfma_f32_16x16x32_bf16 v[6:9], v[208:211], v[248:251], v[6:9]
	v_mfma_f32_16x16x32_bf16 v[6:9], v[204:207], v[244:247], v[6:9]
	v_mfma_f32_16x16x32_bf16 v[10:13], v[196:199], v[244:247], v[10:13]
	v_mfma_f32_16x16x32_bf16 v[10:13], v[200:203], v[248:251], v[10:13]
	v_mfma_f32_16x16x32_bf16 v[14:17], v[160:163], v[248:251], v[14:17]
	v_mfma_f32_16x16x32_bf16 v[14:17], v[156:159], v[244:247], v[14:17]
	s_barrier
	s_cmpk_gt_u32 s59, 0xa9
	s_mov_b32 s59, s24
	s_cbranch_scc0 .LBB0_939
	s_and_b64 vcc, exec, s[38:39]
	s_cbranch_vccz .LBB0_942
	s_barrier
